# revK_odd_units
# speedup vs baseline: 1.0180x; 1.0038x over previous
; template <class Epi, class Sched, bool ALIGN_EPI = false, bool SP2 = false>
; __device__ __forceinline__ void gemm_phase(PG8_LAS unsigned char* lds, const Gemm g, const Sched& S, const Epi& E) {
;     ...
;     const int tid = tid_, wid = __builtin_amdgcn_readfirstlane(tid >> 6), lane = tid & 63, wr = wid >> 2, wc = wid & 3, fr = lane & 15, fq = lane >> 4;
;     const int K = g.K, nt = K / BK;
;     unsigned voffA[2], voffB[2];
; #pragma unroll
;     for (int i = 0; i < 2; ++i) { int R, C; stage_rc(tid * 16 + i * 8192, R, C); const int Rb = Epi::PERM ? ((R & ~31) + perm32(R & 31)) : R;
;         voffA[i] = (unsigned)(R * K + C) * 2u; voffB[i] = (unsigned)(Rb * K + C) * 2u; }
;     const size_t kstep = (size_t)(BK * 2);
;     const size_t hstep = (size_t)HALF * K * 2;
;     const size_t tstep = 2 * hstep;
;     const unsigned ldsw = (unsigned)wid * 1024u;
;     const int aoff = lds_byte(wr * 64 + fr, fq * 8), boff = lds_byte(wc * 32 + fr, fq * 8);
;     ...
;     Unit cur, nxt; int ui = 0;
;     if (!S.next(0, cur)) return;
;     f32x4 acc[2][2][4][2];
; #pragma unroll
;     for (int a = 0; a < 2; ++a)
; #pragma unroll
;         for (int b = 0; b < 2; ++b)
; #pragma unroll
;             for (int m = 0; m < 4; ++m)
; #pragma unroll
;                 for (int n = 0; n < 2; ++n) acc[a][b][m][n] = (f32x4){0.f, 0.f, 0.f, 0.f};
;     bf16x8 At[4][2], B0[2][2], B1[2][2];
;     const char* cA = (const char*)g.A + (size_t)cur.pm * tstep; const char* cB = (const char*)g.Bt + (size_t)cur.pn * tstep;
;     S.a_ready(cur);
;     if constexpr (SP2) {
;         PG8_STAGE(PG8_SB(0, 0), cB, voffB); PG8_STAGE(PG8_SB(0, 1), cB + hstep, voffB); PG8_STAGE(PG8_SA(0, 0), cA, voffA); PG8_STAGE(PG8_SA(0, 1), cA + hstep, voffA);
;         if (wr == 1) PG8_BAR;
;         PG8_WAIT_V(2); PG8_BAR;
;         PG8_STAGE(PG8_SB(1, 0), cB + kstep, voffB); PG8_STAGE(PG8_SA(1, 0), cA + kstep, voffA); PG8_STAGE(PG8_SB(1, 1), cB + hstep + kstep, voffB);
;         PG8_WAIT_V(6); PG8_BAR;
;     } else {
;         PG8_STAGE(PG8_SB(0, 0), cB, voffB); PG8_STAGE(PG8_SA(0, 0), cA, voffA); PG8_STAGE(PG8_SB(0, 1), cB + hstep, voffB); PG8_STAGE(PG8_SA(0, 1), cA + hstep, voffA);
;         if (wr == 1) PG8_BAR;
;         PG8_WAIT_V(4); PG8_BAR;
;         PG8_STAGE(PG8_SB(1, 0), cB + kstep, voffB); PG8_STAGE(PG8_SA(1, 0), cA + kstep, voffA); PG8_STAGE(PG8_SB(1, 1), cB + hstep + kstep, voffB);
;         PG8_WAIT_V(6); PG8_BAR;
.LBB0_769:
	s_cmp_lt_i32 s70, 6
	s_cselect_b64 s[4:5], -1, 0
	s_and_b64 s[4:5], s[4:5], s[0:1]
	s_andn2_b64 vcc, exec, s[4:5]
	s_cbranch_vccnz .LBB0_786
	v_writelane_b32 v253, s4, 0
	v_writelane_b32 v253, s5, 1
	v_writelane_b32 v253, s6, 2
	v_writelane_b32 v253, s7, 3
	v_writelane_b32 v253, s8, 4
	v_writelane_b32 v253, s9, 5
	v_writelane_b32 v253, s10, 6
	v_writelane_b32 v253, s11, 7
	v_writelane_b32 v253, s12, 8
	v_writelane_b32 v253, s13, 9
	v_writelane_b32 v253, s14, 10
	v_writelane_b32 v253, s15, 11
	v_writelane_b32 v253, s16, 12
	v_writelane_b32 v253, s17, 13
	v_writelane_b32 v253, s18, 14
	v_writelane_b32 v253, s19, 15
	v_writelane_b32 v253, s20, 16
	v_writelane_b32 v253, s21, 17
	v_writelane_b32 v253, s22, 18
	v_writelane_b32 v253, s23, 19
	v_writelane_b32 v253, s24, 20
	v_writelane_b32 v253, s25, 21
	v_writelane_b32 v253, s26, 22
	v_writelane_b32 v253, s27, 23
	v_writelane_b32 v253, s28, 24
	v_writelane_b32 v253, s29, 25
	v_writelane_b32 v253, s30, 26
	v_writelane_b32 v253, s31, 27
	v_writelane_b32 v253, s32, 28
	v_writelane_b32 v253, s33, 29
	v_writelane_b32 v253, s34, 30
	v_writelane_b32 v253, s35, 31
	v_writelane_b32 v253, s36, 32
	v_writelane_b32 v253, s37, 33
	v_writelane_b32 v253, s38, 34
	v_writelane_b32 v253, s39, 35
	v_writelane_b32 v253, s40, 36
	v_writelane_b32 v253, s41, 37
	v_writelane_b32 v253, s42, 38
	v_writelane_b32 v253, s43, 39
	v_writelane_b32 v253, s44, 40
	v_writelane_b32 v253, s45, 41
	v_writelane_b32 v253, s46, 42
	v_writelane_b32 v253, s47, 43
	v_writelane_b32 v253, s48, 44
	v_writelane_b32 v253, s49, 45
	v_writelane_b32 v253, s50, 46
	v_writelane_b32 v253, s51, 47
	v_writelane_b32 v253, s52, 48
	v_writelane_b32 v253, s53, 49
	v_writelane_b32 v253, s54, 50
	v_writelane_b32 v253, s55, 51
	v_writelane_b32 v253, s56, 52
	v_writelane_b32 v253, s57, 53
	v_writelane_b32 v253, s58, 54
	v_writelane_b32 v253, s59, 55
	s_mov_b32 s40, vcc_lo
	s_mov_b32 s41, vcc_hi
	v_writelane_b32 v253, s40, 60
	v_writelane_b32 v253, s41, 61
	v_lshrrev_b32_e32 v254, 6, v185
	v_readlane_b32 s14, v244, 4
	v_readfirstlane_b32 s36, v254
	s_nop 3
	s_lshr_b32 s37, s36, 2
	s_and_b32 s38, s36, 3
	s_lshl_b32 s35, s36, 10
	s_add_u32 s10, s76, 0x6800000
	s_addc_u32 s11, s77, 0
	s_add_u32 s12, s76, 0x2500000
	s_addc_u32 s13, s77, 0
	s_mov_b32 s16, 0
	s_mul_i32 s40, s16, s14
	s_add_u32 s40, s40, s2
	s_cmp_lt_u32 s40, 2816
	s_cselect_b32 s44, 1, 0
	s_min_u32 s40, s40, 2815
	s_and_b32 s41, s40, 7
	s_lshr_b32 s42, s40, 3
	s_mul_i32 s41, s41, 352
	s_add_u32 s41, s41, s42
	s_mul_hi_u32 s42, s41, 0xba2e8c
	s_mul_i32 s43, s42, 352
	s_sub_u32 s43, s41, s43
	s_and_b32 s40, s43, 7
	s_lshl_b32 s42, s42, 3
	s_add_u32 s17, s42, s40
	s_lshr_b32 s18, s43, 3
	s_cmp_eq_u32 s44, 0
	s_cbranch_scc1 .Lp5_exit
	v_and_b32_e32 v254, 63, v185
	v_and_b32_e32 v255, 15, v254
	v_lshrrev_b32_e32 v226, 1, v255
	v_lshrrev_b32_e32 v227, 4, v254
	v_xor_b32_e32 v226, v226, v227
	v_lshlrev_b32_e32 v255, 7, v255
	v_lshl_or_b32 v255, v226, 4, v255
	s_lshl_b32 s40, s37, 13
	s_lshl_b32 s41, s38, 12
	s_add_u32 s41, s41, 0x10000
	v_add_u32_e32 v245, s40, v255
	v_add_u32_e32 v247, s41, v255
	v_xor_b32_e32 v246, 64, v245
	v_xor_b32_e32 v248, 64, v247
	v_lshrrev_b32_e32 v255, 3, v254
	v_and_b32_e32 v226, 7, v254
	s_and_b32 s40, s36, 1
	s_lshl_b32 s40, s40, 2
	v_lshrrev_b32_e32 v227, 1, v255
	v_add_u32_e32 v227, s40, v227
	v_xor_b32_e32 v226, v226, v227
	v_lshlrev_b32_e32 v226, 4, v226
	s_lshl_b32 s40, s36, 3
	v_add_u32_e32 v227, s40, v255
	v_mul_u32_u24_e32 v227, 0x1000, v227
	v_add_u32_e32 v249, v227, v226
	v_add_u32_e32 v250, 0x40000, v249
	s_and_b32 s40, s36, 3
	s_lshl_b32 s40, s40, 3
	v_add_u32_e32 v227, s40, v255
	v_lshrrev_b32_e32 v254, 4, v227
	v_lshlrev_b32_e32 v254, 2, v254
	v_and_b32_e32 v255, 3, v227
	v_add_u32_e32 v254, v254, v255
	v_and_b32_e32 v227, 12, v227
	v_lshl_add_u32 v254, v227, 1, v254
	s_lshr_b32 s40, s36, 2
	s_lshl_b32 s40, s40, 5
	v_add_u32_e32 v254, s40, v254
	v_mul_u32_u24_e32 v254, 0x1000, v254
	v_add_u32_e32 v251, v254, v226
	v_add_u32_e32 v252, 0x40000, v251
	s_mul_i32 s40, s17, 0x100000
	s_add_u32 s22, s10, s40
	s_addc_u32 s23, s11, 0
	s_mul_i32 s40, s18, 0x100000
	s_add_u32 s24, s12, s40
	s_addc_u32 s25, s13, 0
	s_and_b32 s40, s16, 1
	s_lshl_b32 s4, s40, 8
	s_sub_u32 s4, 128, s4
	s_sub_u32 s5, 0, s40
	s_mul_i32 s8, s40, 3968
	s_add_u32 s30, s22, s8
	s_addc_u32 s31, s23, 0
	s_add_u32 s32, s24, s8
	s_addc_u32 s33, s25, 0
	s_add_u32 s56, s30, 0x80000
	s_addc_u32 s57, s31, 0
	s_add_u32 s58, s32, 0x80000
	s_addc_u32 s59, s33, 0
	s_add_i32 m0, s35, 0x0
	s_nop 0
	global_load_lds_dwordx4 v249, s[30:31]
	s_add_i32 m0, s35, 0x2000
	s_nop 0
	global_load_lds_dwordx4 v250, s[30:31]
	s_add_i32 m0, s35, 0x10000
	s_nop 0
	global_load_lds_dwordx4 v251, s[32:33]
	s_add_i32 m0, s35, 0x12000
	s_nop 0
	global_load_lds_dwordx4 v252, s[32:33]
	s_add_i32 m0, s35, 0x4000
	s_nop 0
	global_load_lds_dwordx4 v249, s[56:57]
	s_add_i32 m0, s35, 0x6000
	s_nop 0
	global_load_lds_dwordx4 v250, s[56:57]
	s_add_i32 m0, s35, 0x14000
	s_nop 0
	global_load_lds_dwordx4 v251, s[58:59]
	s_add_i32 m0, s35, 0x16000
	s_nop 0
	global_load_lds_dwordx4 v252, s[58:59]
	s_add_u32 s30, s30, s4
	s_addc_u32 s31, s31, s5
	s_add_u32 s56, s56, s4
	s_addc_u32 s57, s57, s5
	s_add_u32 s32, s32, s4
	s_addc_u32 s33, s33, s5
	s_add_u32 s58, s58, s4
	s_addc_u32 s59, s59, s5
	s_add_i32 m0, s35, 0x8000
	s_nop 0
	global_load_lds_dwordx4 v249, s[30:31]
	s_add_i32 m0, s35, 0xa000
	s_nop 0
	global_load_lds_dwordx4 v250, s[30:31]
	s_add_i32 m0, s35, 0x1c000
	s_nop 0
	global_load_lds_dwordx4 v251, s[58:59]
	s_add_i32 m0, s35, 0x1e000
	s_nop 0
	global_load_lds_dwordx4 v252, s[58:59]
	s_add_i32 m0, s35, 0xc000
	s_nop 0
	global_load_lds_dwordx4 v249, s[56:57]
	s_add_i32 m0, s35, 0xe000
	s_nop 0
	global_load_lds_dwordx4 v250, s[56:57]
	s_add_i32 m0, s35, 0x18000
	s_nop 0
	global_load_lds_dwordx4 v251, s[32:33]
	s_add_i32 m0, s35, 0x1a000
	s_nop 0
	global_load_lds_dwordx4 v252, s[32:33]
	s_add_u32 s30, s30, s4
	s_addc_u32 s31, s31, s5
	s_add_u32 s56, s56, s4
	s_addc_u32 s57, s57, s5
	s_add_u32 s32, s32, s4
	s_addc_u32 s33, s33, s5
	s_add_u32 s58, s58, s4
	s_addc_u32 s59, s59, s5
	s_waitcnt vmcnt(12)
	s_barrier
; #define PG8_STAGE(bufoff, gbase, voff) do { _Pragma("unroll") for (int _i = 0; _i < 2; ++_i) \
;         __builtin_amdgcn_global_load_lds((const unsigned*)((const char*)(gbase) + (voff)[_i]), (PG8_LAS unsigned*)(lds + (bufoff) + ldsw + _i * 8192), 16, 0, 0); } while (0)
; #define PG8_LDA(dst, b, h) do { _Pragma("unroll") for (int m = 0; m < 4; ++m) _Pragma("unroll") for (int k = 0; k < 2; ++k) dst[m][k] = *(const PG8_LAS bf16x8*)(lds + PG8_SA(b, h) + aoff + m * 2048 + k * 1024); } while (0)
; #define PG8_LDB(dst, b, h) do { _Pragma("unroll") for (int n = 0; n < 2; ++n) _Pragma("unroll") for (int k = 0; k < 2; ++k) dst[n][k] = *(const PG8_LAS bf16x8*)(lds + PG8_SB(b, h) + boff + n * 2048 + k * 1024); } while (0)
; #define PG8_SCHED __builtin_amdgcn_sched_barrier(0)
; template <class Epi, class Sched, bool ALIGN_EPI = false, bool SP2 = false>
; __device__ __forceinline__ void gemm_phase(PG8_LAS unsigned char* lds, const Gemm g, const Sched& S, const Epi& E) {
;     ...
;         const bool has_next = S.next(ui + 1, nxt);
;         const char* nA = has_next ? (const char*)g.A + (size_t)nxt.pm * tstep : cA; const char* nB = has_next ? (const char*)g.Bt + (size_t)nxt.pn * tstep : cB;
;         for (int t = 0; t < nt; t += 2) {
;             const bool last = (t == nt - 2);
;             const char* a1 = cA + (size_t)(t + 1) * kstep;
;             const char* a2 = last ? nA : cA + (size_t)(t + 2) * kstep; const char* b2 = last ? nB : cB + (size_t)(t + 2) * kstep;
;             const char* a3 = a2 + kstep; const char* b3 = b2 + kstep;
;             if (last && has_next) S.a_ready(nxt);
;             if constexpr (SP2) {
;             PG8_LDB(B0, 0, 0); PG8_LDB(B1, 0, 1); PG8_SCHED; PG8_LDA(At, 0, 0); PG8_STAGE(PG8_SA(1, 1), a1 + hstep, voffA);
;     ...
; #pragma unroll
;         for (int a = 0; a < 2; ++a)
; #pragma unroll
;             for (int b = 0; b < 2; ++b)
; #pragma unroll
;                 for (int m = 0; m < 4; ++m)
; #pragma unroll
;                     for (int n = 0; n < 2; ++n) acc[a][b][m][n] = (f32x4){0.f, 0.f, 0.f, 0.f};
;         cur = nxt; cA = nA; cB = nB; ++ui;
.Lp5_unit:
	s_add_u32 s45, s16, 1
	s_mul_i32 s40, s45, s14
	s_add_u32 s40, s40, s2
	s_cmp_lt_u32 s40, 2816
	s_cselect_b32 s19, 1, 0
	s_min_u32 s40, s40, 2815
	s_and_b32 s41, s40, 7
	s_lshr_b32 s42, s40, 3
	s_mul_i32 s41, s41, 352
	s_add_u32 s41, s41, s42
	s_mul_hi_u32 s42, s41, 0xba2e8c
	s_mul_i32 s43, s42, 352
	s_sub_u32 s43, s41, s43
	s_and_b32 s40, s43, 7
	s_lshl_b32 s42, s42, 3
	s_add_u32 s20, s42, s40
	s_lshr_b32 s21, s43, 3
	s_mul_i32 s40, s20, 0x100000
	s_add_u32 s26, s10, s40
	s_addc_u32 s27, s11, 0
	s_mul_i32 s40, s21, 0x100000
	s_add_u32 s28, s12, s40
	s_addc_u32 s29, s13, 0
	s_cmp_eq_u32 s19, 0
	s_cselect_b32 s26, s22, s26
	s_cselect_b32 s27, s23, s27
	s_cselect_b32 s28, s24, s28
	s_cselect_b32 s29, s25, s29
	s_add_u32 s30, s22, s8
	s_addc_u32 s31, s23, 0
	s_add_u32 s32, s24, s8
	s_addc_u32 s33, s25, 0
	s_add_u32 s30, s30, s4
	s_addc_u32 s31, s31, s5
	s_add_u32 s32, s32, s4
	s_addc_u32 s33, s33, s5
	s_add_u32 s30, s30, s4
	s_addc_u32 s31, s31, s5
	s_add_u32 s32, s32, s4
	s_addc_u32 s33, s33, s5
	s_add_u32 s56, s30, 0x80000
	s_addc_u32 s57, s31, 0
	s_add_u32 s58, s32, 0x80000
	s_addc_u32 s59, s33, 0
	s_movk_i32 s34, 16
	v_mov_b32_e32 v0, 0
	v_mov_b32_e32 v1, 0
	v_mov_b32_e32 v2, 0
	v_mov_b32_e32 v3, 0
	v_mov_b32_e32 v4, 0
	v_mov_b32_e32 v5, 0
	v_mov_b32_e32 v6, 0
	v_mov_b32_e32 v7, 0
	v_mov_b32_e32 v8, 0
	v_mov_b32_e32 v9, 0
	v_mov_b32_e32 v10, 0
	v_mov_b32_e32 v11, 0
	v_mov_b32_e32 v12, 0
	v_mov_b32_e32 v13, 0
	v_mov_b32_e32 v14, 0
	v_mov_b32_e32 v15, 0
	v_mov_b32_e32 v16, 0
	v_mov_b32_e32 v17, 0
	v_mov_b32_e32 v18, 0
	v_mov_b32_e32 v19, 0
	v_mov_b32_e32 v20, 0
	v_mov_b32_e32 v21, 0
	v_mov_b32_e32 v22, 0
	v_mov_b32_e32 v23, 0
	v_mov_b32_e32 v24, 0
	v_mov_b32_e32 v25, 0
	v_mov_b32_e32 v26, 0
	v_mov_b32_e32 v27, 0
	v_mov_b32_e32 v28, 0
	v_mov_b32_e32 v29, 0
	v_mov_b32_e32 v30, 0
	v_mov_b32_e32 v31, 0
	v_mov_b32_e32 v32, 0
	v_mov_b32_e32 v33, 0
	v_mov_b32_e32 v34, 0
	v_mov_b32_e32 v35, 0
	v_mov_b32_e32 v36, 0
	v_mov_b32_e32 v37, 0
	v_mov_b32_e32 v38, 0
	v_mov_b32_e32 v39, 0
	v_mov_b32_e32 v40, 0
	v_mov_b32_e32 v41, 0
	v_mov_b32_e32 v42, 0
	v_mov_b32_e32 v43, 0
	v_mov_b32_e32 v44, 0
	v_mov_b32_e32 v45, 0
	v_mov_b32_e32 v46, 0
	v_mov_b32_e32 v47, 0
	v_mov_b32_e32 v48, 0
	v_mov_b32_e32 v49, 0
	v_mov_b32_e32 v50, 0
	v_mov_b32_e32 v51, 0
	v_mov_b32_e32 v52, 0
	v_mov_b32_e32 v53, 0
	v_mov_b32_e32 v54, 0
	v_mov_b32_e32 v55, 0
	v_mov_b32_e32 v56, 0
	v_mov_b32_e32 v57, 0
	v_mov_b32_e32 v58, 0
	v_mov_b32_e32 v59, 0
	v_mov_b32_e32 v60, 0
	v_mov_b32_e32 v61, 0
	v_mov_b32_e32 v62, 0
	v_mov_b32_e32 v63, 0
	v_mov_b32_e32 v64, 0
	v_mov_b32_e32 v65, 0
	v_mov_b32_e32 v66, 0
	v_mov_b32_e32 v67, 0
	v_mov_b32_e32 v68, 0
	v_mov_b32_e32 v69, 0
	v_mov_b32_e32 v70, 0
	v_mov_b32_e32 v71, 0
	v_mov_b32_e32 v72, 0
	v_mov_b32_e32 v73, 0
	v_mov_b32_e32 v74, 0
	v_mov_b32_e32 v75, 0
	v_mov_b32_e32 v76, 0
	v_mov_b32_e32 v77, 0
	v_mov_b32_e32 v78, 0
	v_mov_b32_e32 v79, 0
	v_mov_b32_e32 v80, 0
	v_mov_b32_e32 v81, 0
	v_mov_b32_e32 v82, 0
	v_mov_b32_e32 v83, 0
	v_mov_b32_e32 v84, 0
	v_mov_b32_e32 v85, 0
	v_mov_b32_e32 v86, 0
	v_mov_b32_e32 v87, 0
	v_mov_b32_e32 v88, 0
	v_mov_b32_e32 v89, 0
	v_mov_b32_e32 v90, 0
	v_mov_b32_e32 v91, 0
	v_mov_b32_e32 v92, 0
	v_mov_b32_e32 v93, 0
	v_mov_b32_e32 v94, 0
	v_mov_b32_e32 v95, 0
	v_mov_b32_e32 v96, 0
	v_mov_b32_e32 v97, 0
	v_mov_b32_e32 v98, 0
	v_mov_b32_e32 v99, 0
	v_mov_b32_e32 v100, 0
	v_mov_b32_e32 v101, 0
	v_mov_b32_e32 v102, 0
	v_mov_b32_e32 v103, 0
	v_mov_b32_e32 v104, 0
	v_mov_b32_e32 v105, 0
	v_mov_b32_e32 v106, 0
	v_mov_b32_e32 v107, 0
	v_mov_b32_e32 v108, 0
	v_mov_b32_e32 v109, 0
	v_mov_b32_e32 v110, 0
	v_mov_b32_e32 v111, 0
	v_mov_b32_e32 v112, 0
	v_mov_b32_e32 v113, 0
	v_mov_b32_e32 v114, 0
	v_mov_b32_e32 v115, 0
	v_mov_b32_e32 v116, 0
	v_mov_b32_e32 v117, 0
	v_mov_b32_e32 v118, 0
	v_mov_b32_e32 v119, 0
	v_mov_b32_e32 v120, 0
	v_mov_b32_e32 v121, 0
	v_mov_b32_e32 v122, 0
	v_mov_b32_e32 v123, 0
	v_mov_b32_e32 v124, 0
	v_mov_b32_e32 v125, 0
	v_mov_b32_e32 v126, 0
	v_mov_b32_e32 v127, 0
	ds_read_b128 v[194:197], v247 offset:0
	ds_read_b128 v[198:201], v248 offset:0
	ds_read_b128 v[202:205], v247 offset:2048
	ds_read_b128 v[206:209], v248 offset:2048
	ds_read_b128 v[128:131], v245 offset:0
	ds_read_b128 v[132:135], v246 offset:0
	ds_read_b128 v[136:139], v245 offset:2048
	ds_read_b128 v[140:143], v246 offset:2048
	ds_read_b128 v[144:147], v245 offset:4096
	ds_read_b128 v[148:151], v246 offset:4096
	ds_read_b128 v[152:155], v245 offset:6144
	ds_read_b128 v[156:159], v246 offset:6144
	s_cmp_ge_u32 s36, 4
	s_cbranch_scc1 .Lp5_kloop1
; #define PG8_STAGE(bufoff, gbase, voff) do { _Pragma("unroll") for (int _i = 0; _i < 2; ++_i) \
;         __builtin_amdgcn_global_load_lds((const unsigned*)((const char*)(gbase) + (voff)[_i]), (PG8_LAS unsigned*)(lds + (bufoff) + ldsw + _i * 8192), 16, 0, 0); } while (0)
; #define PG8_LDA(dst, b, h) do { _Pragma("unroll") for (int m = 0; m < 4; ++m) _Pragma("unroll") for (int k = 0; k < 2; ++k) dst[m][k] = *(const PG8_LAS bf16x8*)(lds + PG8_SA(b, h) + aoff + m * 2048 + k * 1024); } while (0)
; #define PG8_LDB(dst, b, h) do { _Pragma("unroll") for (int n = 0; n < 2; ++n) _Pragma("unroll") for (int k = 0; k < 2; ++k) dst[n][k] = *(const PG8_LAS bf16x8*)(lds + PG8_SB(b, h) + boff + n * 2048 + k * 1024); } while (0)
; template <class Epi, class Sched, bool ALIGN_EPI = false, bool SP2 = false>
; __device__ __forceinline__ void gemm_phase(PG8_LAS unsigned char* lds, const Gemm g, const Sched& S, const Epi& E) {
;     ...
;         for (int t = 0; t < nt; t += 2) {
;             const bool last = (t == nt - 2);
;             const char* a1 = cA + (size_t)(t + 1) * kstep;
;             const char* a2 = last ? nA : cA + (size_t)(t + 2) * kstep; const char* b2 = last ? nB : cB + (size_t)(t + 2) * kstep;
;             const char* a3 = a2 + kstep; const char* b3 = b2 + kstep;
;             if (last && has_next) S.a_ready(nxt);
;             if constexpr (SP2) {
;             PG8_LDB(B0, 0, 0); PG8_LDB(B1, 0, 1); PG8_SCHED; PG8_LDA(At, 0, 0); PG8_STAGE(PG8_SA(1, 1), a1 + hstep, voffA);
;             PG8_WAIT_V(8); PG8_WAIT_L(0); PG8_BAR; PG8_MMA(0, 0, At, B0); PG8_MMA(0, 1, At, B1); PG8_BAR; PG8_SCHED;
;             PG8_LDA(At, 0, 1); PG8_STAGE(PG8_SB(0, 0), b2, voffB); PG8_STAGE(PG8_SB(0, 1), b2 + hstep, voffB); PG8_STAGE(PG8_SA(0, 0), a2, voffA);
;             PG8_WAIT_V(8); PG8_WAIT_L(0); PG8_BAR; PG8_MMA(1, 0, At, B0); PG8_MMA(1, 1, At, B1); PG8_BAR; PG8_SCHED;
;             PG8_LDB(B0, 1, 0); PG8_LDB(B1, 1, 1); PG8_SCHED; PG8_LDA(At, 1, 0); PG8_STAGE(PG8_SA(0, 1), a2 + hstep, voffA);
;             PG8_WAIT_V(8); PG8_WAIT_L(0); PG8_BAR; PG8_MMA(0, 0, At, B0); PG8_MMA(0, 1, At, B1); PG8_BAR; PG8_SCHED;
;             PG8_LDA(At, 1, 1); PG8_STAGE(PG8_SB(1, 0), b3, voffB); PG8_STAGE(PG8_SB(1, 1), b3 + hstep, voffB); PG8_STAGE(PG8_SA(1, 0), a3, voffA);
;             PG8_WAIT_V(8); PG8_WAIT_L(0); PG8_BAR; PG8_MMA(1, 0, At, B0); PG8_MMA(1, 1, At, B1); PG8_BAR; PG8_SCHED;
.Lp5_kloop0:
	s_waitcnt vmcnt(8)
	s_waitcnt lgkmcnt(0)
	s_barrier
	v_mfma_f32_16x16x32_bf16 v[0:3], v[194:197], v[128:131], v[0:3]
	ds_read_b128 v[210:213], v247 offset:16384
	v_mfma_f32_16x16x32_bf16 v[4:7], v[202:205], v[128:131], v[4:7]
	ds_read_b128 v[214:217], v248 offset:16384
	v_mfma_f32_16x16x32_bf16 v[8:11], v[194:197], v[136:139], v[8:11]
	ds_read_b128 v[218:221], v247 offset:18432
	v_mfma_f32_16x16x32_bf16 v[12:15], v[202:205], v[136:139], v[12:15]
	ds_read_b128 v[222:225], v248 offset:18432
	v_mfma_f32_16x16x32_bf16 v[16:19], v[194:197], v[144:147], v[16:19]
	s_add_i32 m0, s35, 0x0
	v_mfma_f32_16x16x32_bf16 v[20:23], v[202:205], v[144:147], v[20:23]
	global_load_lds_dwordx4 v249, s[30:31]
	v_mfma_f32_16x16x32_bf16 v[24:27], v[194:197], v[152:155], v[24:27]
	s_add_i32 m0, s35, 0x2000
	v_mfma_f32_16x16x32_bf16 v[28:31], v[202:205], v[152:155], v[28:31]
	global_load_lds_dwordx4 v250, s[30:31]
	v_mfma_f32_16x16x32_bf16 v[0:3], v[198:201], v[132:135], v[0:3]
	s_add_i32 m0, s35, 0x10000
	v_mfma_f32_16x16x32_bf16 v[4:7], v[206:209], v[132:135], v[4:7]
	global_load_lds_dwordx4 v251, s[32:33]
	v_mfma_f32_16x16x32_bf16 v[8:11], v[198:201], v[140:143], v[8:11]
	s_add_i32 m0, s35, 0x12000
	v_mfma_f32_16x16x32_bf16 v[12:15], v[206:209], v[140:143], v[12:15]
	global_load_lds_dwordx4 v252, s[32:33]
	v_mfma_f32_16x16x32_bf16 v[16:19], v[198:201], v[148:151], v[16:19]
	ds_read_b128 v[160:163], v245 offset:16384
	v_mfma_f32_16x16x32_bf16 v[20:23], v[206:209], v[148:151], v[20:23]
	ds_read_b128 v[164:167], v246 offset:16384
	v_mfma_f32_16x16x32_bf16 v[24:27], v[198:201], v[156:159], v[24:27]
	ds_read_b128 v[168:171], v245 offset:18432
	v_mfma_f32_16x16x32_bf16 v[28:31], v[206:209], v[156:159], v[28:31]
	ds_read_b128 v[172:175], v246 offset:18432
	s_waitcnt lgkmcnt(4)
	v_mfma_f32_16x16x32_bf16 v[32:35], v[210:213], v[128:131], v[32:35]
	ds_read_b128 v[176:179], v245 offset:20480
	v_mfma_f32_16x16x32_bf16 v[36:39], v[218:221], v[128:131], v[36:39]
	ds_read_b128 v[180:183], v246 offset:20480
	v_mfma_f32_16x16x32_bf16 v[40:43], v[210:213], v[136:139], v[40:43]
	ds_read_b128 v[186:189], v245 offset:22528
	v_mfma_f32_16x16x32_bf16 v[44:47], v[218:221], v[136:139], v[44:47]
	ds_read_b128 v[190:193], v246 offset:22528
	v_mfma_f32_16x16x32_bf16 v[48:51], v[210:213], v[144:147], v[48:51]
	v_mfma_f32_16x16x32_bf16 v[52:55], v[218:221], v[144:147], v[52:55]
	v_mfma_f32_16x16x32_bf16 v[56:59], v[210:213], v[152:155], v[56:59]
	v_mfma_f32_16x16x32_bf16 v[60:63], v[218:221], v[152:155], v[60:63]
	v_mfma_f32_16x16x32_bf16 v[32:35], v[214:217], v[132:135], v[32:35]
	v_mfma_f32_16x16x32_bf16 v[36:39], v[222:225], v[132:135], v[36:39]
	v_mfma_f32_16x16x32_bf16 v[40:43], v[214:217], v[140:143], v[40:43]
	v_mfma_f32_16x16x32_bf16 v[44:47], v[222:225], v[140:143], v[44:47]
	v_mfma_f32_16x16x32_bf16 v[48:51], v[214:217], v[148:151], v[48:51]
	v_mfma_f32_16x16x32_bf16 v[52:55], v[222:225], v[148:151], v[52:55]
	v_mfma_f32_16x16x32_bf16 v[56:59], v[214:217], v[156:159], v[56:59]
	v_mfma_f32_16x16x32_bf16 v[60:63], v[222:225], v[156:159], v[60:63]
	s_waitcnt vmcnt(8)
	s_waitcnt lgkmcnt(0)
	s_barrier
	v_mfma_f32_16x16x32_bf16 v[96:99], v[210:213], v[160:163], v[96:99]
	s_add_i32 m0, s35, 0x4000
	v_mfma_f32_16x16x32_bf16 v[100:103], v[218:221], v[160:163], v[100:103]
	global_load_lds_dwordx4 v249, s[56:57]
	v_mfma_f32_16x16x32_bf16 v[104:107], v[210:213], v[168:171], v[104:107]
	s_add_i32 m0, s35, 0x6000
	v_mfma_f32_16x16x32_bf16 v[108:111], v[218:221], v[168:171], v[108:111]
	global_load_lds_dwordx4 v250, s[56:57]
	v_mfma_f32_16x16x32_bf16 v[112:115], v[210:213], v[176:179], v[112:115]
	s_add_i32 m0, s35, 0x14000
	v_mfma_f32_16x16x32_bf16 v[116:119], v[218:221], v[176:179], v[116:119]
	global_load_lds_dwordx4 v251, s[58:59]
	v_mfma_f32_16x16x32_bf16 v[120:123], v[210:213], v[186:189], v[120:123]
	s_add_i32 m0, s35, 0x16000
	v_mfma_f32_16x16x32_bf16 v[124:127], v[218:221], v[186:189], v[124:127]
	global_load_lds_dwordx4 v252, s[58:59]
	v_mfma_f32_16x16x32_bf16 v[96:99], v[214:217], v[164:167], v[96:99]
	ds_read_b128 v[128:131], v245 offset:32768
	v_mfma_f32_16x16x32_bf16 v[100:103], v[222:225], v[164:167], v[100:103]
	ds_read_b128 v[132:135], v246 offset:32768
	v_mfma_f32_16x16x32_bf16 v[104:107], v[214:217], v[172:175], v[104:107]
	ds_read_b128 v[136:139], v245 offset:34816
	v_mfma_f32_16x16x32_bf16 v[108:111], v[222:225], v[172:175], v[108:111]
	ds_read_b128 v[140:143], v246 offset:34816
	v_mfma_f32_16x16x32_bf16 v[112:115], v[214:217], v[180:183], v[112:115]
	ds_read_b128 v[144:147], v245 offset:36864
	v_mfma_f32_16x16x32_bf16 v[116:119], v[222:225], v[180:183], v[116:119]
	ds_read_b128 v[148:151], v246 offset:36864
	v_mfma_f32_16x16x32_bf16 v[120:123], v[214:217], v[190:193], v[120:123]
	ds_read_b128 v[152:155], v245 offset:38912
	v_mfma_f32_16x16x32_bf16 v[124:127], v[222:225], v[190:193], v[124:127]
	ds_read_b128 v[156:159], v246 offset:38912
	v_mfma_f32_16x16x32_bf16 v[64:67], v[194:197], v[160:163], v[64:67]
	ds_read_b128 v[210:213], v247 offset:49152
	v_mfma_f32_16x16x32_bf16 v[68:71], v[202:205], v[160:163], v[68:71]
	ds_read_b128 v[214:217], v248 offset:49152
	v_mfma_f32_16x16x32_bf16 v[72:75], v[194:197], v[168:171], v[72:75]
	ds_read_b128 v[218:221], v247 offset:51200
	v_mfma_f32_16x16x32_bf16 v[76:79], v[202:205], v[168:171], v[76:79]
	ds_read_b128 v[222:225], v248 offset:51200
	v_mfma_f32_16x16x32_bf16 v[80:83], v[194:197], v[176:179], v[80:83]
	s_add_u32 s30, s30, s4
	s_addc_u32 s31, s31, s5
	v_mfma_f32_16x16x32_bf16 v[84:87], v[202:205], v[176:179], v[84:87]
	s_add_u32 s56, s56, s4
	s_addc_u32 s57, s57, s5
	v_mfma_f32_16x16x32_bf16 v[88:91], v[194:197], v[186:189], v[88:91]
	s_add_u32 s32, s32, s4
	s_addc_u32 s33, s33, s5
	v_mfma_f32_16x16x32_bf16 v[92:95], v[202:205], v[186:189], v[92:95]
	s_add_u32 s58, s58, s4
	s_addc_u32 s59, s59, s5
	v_mfma_f32_16x16x32_bf16 v[64:67], v[198:201], v[164:167], v[64:67]
	v_mfma_f32_16x16x32_bf16 v[68:71], v[206:209], v[164:167], v[68:71]
	v_mfma_f32_16x16x32_bf16 v[72:75], v[198:201], v[172:175], v[72:75]
	v_mfma_f32_16x16x32_bf16 v[76:79], v[206:209], v[172:175], v[76:79]
	v_mfma_f32_16x16x32_bf16 v[80:83], v[198:201], v[180:183], v[80:83]
	v_mfma_f32_16x16x32_bf16 v[84:87], v[206:209], v[180:183], v[84:87]
	v_mfma_f32_16x16x32_bf16 v[88:91], v[198:201], v[190:193], v[88:91]
	v_mfma_f32_16x16x32_bf16 v[92:95], v[206:209], v[190:193], v[92:95]
	s_waitcnt vmcnt(8)
	s_waitcnt lgkmcnt(0)
	s_barrier
; #define PG8_STAGE(bufoff, gbase, voff) do { _Pragma("unroll") for (int _i = 0; _i < 2; ++_i) \
;         __builtin_amdgcn_global_load_lds((const unsigned*)((const char*)(gbase) + (voff)[_i]), (PG8_LAS unsigned*)(lds + (bufoff) + ldsw + _i * 8192), 16, 0, 0); } while (0)
; #define PG8_LDA(dst, b, h) do { _Pragma("unroll") for (int m = 0; m < 4; ++m) _Pragma("unroll") for (int k = 0; k < 2; ++k) dst[m][k] = *(const PG8_LAS bf16x8*)(lds + PG8_SA(b, h) + aoff + m * 2048 + k * 1024); } while (0)
; #define PG8_LDB(dst, b, h) do { _Pragma("unroll") for (int n = 0; n < 2; ++n) _Pragma("unroll") for (int k = 0; k < 2; ++k) dst[n][k] = *(const PG8_LAS bf16x8*)(lds + PG8_SB(b, h) + boff + n * 2048 + k * 1024); } while (0)
; template <class Epi, class Sched, bool ALIGN_EPI = false, bool SP2 = false>
; __device__ __forceinline__ void gemm_phase(PG8_LAS unsigned char* lds, const Gemm g, const Sched& S, const Epi& E) {
;     ...
;         for (int t = 0; t < nt; t += 2) {
;             const bool last = (t == nt - 2);
;             const char* a1 = cA + (size_t)(t + 1) * kstep;
;             const char* a2 = last ? nA : cA + (size_t)(t + 2) * kstep; const char* b2 = last ? nB : cB + (size_t)(t + 2) * kstep;
;             const char* a3 = a2 + kstep; const char* b3 = b2 + kstep;
;             if (last && has_next) S.a_ready(nxt);
;             if constexpr (SP2) {
;             PG8_LDB(B0, 0, 0); PG8_LDB(B1, 0, 1); PG8_SCHED; PG8_LDA(At, 0, 0); PG8_STAGE(PG8_SA(1, 1), a1 + hstep, voffA);
;             PG8_WAIT_V(8); PG8_WAIT_L(0); PG8_BAR; PG8_MMA(0, 0, At, B0); PG8_MMA(0, 1, At, B1); PG8_BAR; PG8_SCHED;
;             PG8_LDA(At, 0, 1); PG8_STAGE(PG8_SB(0, 0), b2, voffB); PG8_STAGE(PG8_SB(0, 1), b2 + hstep, voffB); PG8_STAGE(PG8_SA(0, 0), a2, voffA);
;             PG8_WAIT_V(8); PG8_WAIT_L(0); PG8_BAR; PG8_MMA(1, 0, At, B0); PG8_MMA(1, 1, At, B1); PG8_BAR; PG8_SCHED;
;             PG8_LDB(B0, 1, 0); PG8_LDB(B1, 1, 1); PG8_SCHED; PG8_LDA(At, 1, 0); PG8_STAGE(PG8_SA(0, 1), a2 + hstep, voffA);
;             PG8_WAIT_V(8); PG8_WAIT_L(0); PG8_BAR; PG8_MMA(0, 0, At, B0); PG8_MMA(0, 1, At, B1); PG8_BAR; PG8_SCHED;
;             PG8_LDA(At, 1, 1); PG8_STAGE(PG8_SB(1, 0), b3, voffB); PG8_STAGE(PG8_SB(1, 1), b3 + hstep, voffB); PG8_STAGE(PG8_SA(1, 0), a3, voffA);
;             PG8_WAIT_V(8); PG8_WAIT_L(0); PG8_BAR; PG8_MMA(1, 0, At, B0); PG8_MMA(1, 1, At, B1); PG8_BAR; PG8_SCHED;
	v_mfma_f32_16x16x32_bf16 v[32:35], v[210:213], v[128:131], v[32:35]
	ds_read_b128 v[194:197], v247 offset:32768
	v_mfma_f32_16x16x32_bf16 v[36:39], v[218:221], v[128:131], v[36:39]
	ds_read_b128 v[198:201], v248 offset:32768
	v_mfma_f32_16x16x32_bf16 v[40:43], v[210:213], v[136:139], v[40:43]
	ds_read_b128 v[202:205], v247 offset:34816
	v_mfma_f32_16x16x32_bf16 v[44:47], v[218:221], v[136:139], v[44:47]
	ds_read_b128 v[206:209], v248 offset:34816
	v_mfma_f32_16x16x32_bf16 v[48:51], v[210:213], v[144:147], v[48:51]
	s_add_i32 m0, s35, 0x8000
	v_mfma_f32_16x16x32_bf16 v[52:55], v[218:221], v[144:147], v[52:55]
	global_load_lds_dwordx4 v249, s[30:31]
	v_mfma_f32_16x16x32_bf16 v[56:59], v[210:213], v[152:155], v[56:59]
	s_add_i32 m0, s35, 0xa000
	v_mfma_f32_16x16x32_bf16 v[60:63], v[218:221], v[152:155], v[60:63]
	global_load_lds_dwordx4 v250, s[30:31]
	v_mfma_f32_16x16x32_bf16 v[32:35], v[214:217], v[132:135], v[32:35]
	s_add_i32 m0, s35, 0x1c000
	v_mfma_f32_16x16x32_bf16 v[36:39], v[222:225], v[132:135], v[36:39]
	global_load_lds_dwordx4 v251, s[58:59]
	v_mfma_f32_16x16x32_bf16 v[40:43], v[214:217], v[140:143], v[40:43]
	s_add_i32 m0, s35, 0x1e000
	v_mfma_f32_16x16x32_bf16 v[44:47], v[222:225], v[140:143], v[44:47]
	global_load_lds_dwordx4 v252, s[58:59]
	v_mfma_f32_16x16x32_bf16 v[48:51], v[214:217], v[148:151], v[48:51]
	ds_read_b128 v[160:163], v245 offset:49152
	v_mfma_f32_16x16x32_bf16 v[52:55], v[222:225], v[148:151], v[52:55]
	ds_read_b128 v[164:167], v246 offset:49152
	v_mfma_f32_16x16x32_bf16 v[56:59], v[214:217], v[156:159], v[56:59]
	ds_read_b128 v[168:171], v245 offset:51200
	v_mfma_f32_16x16x32_bf16 v[60:63], v[222:225], v[156:159], v[60:63]
	ds_read_b128 v[172:175], v246 offset:51200
	s_waitcnt lgkmcnt(4)
	v_mfma_f32_16x16x32_bf16 v[0:3], v[194:197], v[128:131], v[0:3]
	ds_read_b128 v[176:179], v245 offset:53248
	v_mfma_f32_16x16x32_bf16 v[4:7], v[202:205], v[128:131], v[4:7]
	ds_read_b128 v[180:183], v246 offset:53248
	v_mfma_f32_16x16x32_bf16 v[8:11], v[194:197], v[136:139], v[8:11]
	ds_read_b128 v[186:189], v245 offset:55296
	v_mfma_f32_16x16x32_bf16 v[12:15], v[202:205], v[136:139], v[12:15]
	ds_read_b128 v[190:193], v246 offset:55296
	v_mfma_f32_16x16x32_bf16 v[16:19], v[194:197], v[144:147], v[16:19]
	v_mfma_f32_16x16x32_bf16 v[20:23], v[202:205], v[144:147], v[20:23]
	v_mfma_f32_16x16x32_bf16 v[24:27], v[194:197], v[152:155], v[24:27]
	v_mfma_f32_16x16x32_bf16 v[28:31], v[202:205], v[152:155], v[28:31]
	v_mfma_f32_16x16x32_bf16 v[0:3], v[198:201], v[132:135], v[0:3]
	v_mfma_f32_16x16x32_bf16 v[4:7], v[206:209], v[132:135], v[4:7]
	v_mfma_f32_16x16x32_bf16 v[8:11], v[198:201], v[140:143], v[8:11]
	v_mfma_f32_16x16x32_bf16 v[12:15], v[206:209], v[140:143], v[12:15]
	v_mfma_f32_16x16x32_bf16 v[16:19], v[198:201], v[148:151], v[16:19]
	v_mfma_f32_16x16x32_bf16 v[20:23], v[206:209], v[148:151], v[20:23]
	v_mfma_f32_16x16x32_bf16 v[24:27], v[198:201], v[156:159], v[24:27]
	v_mfma_f32_16x16x32_bf16 v[28:31], v[206:209], v[156:159], v[28:31]
	s_waitcnt vmcnt(8)
	s_waitcnt lgkmcnt(0)
	s_barrier
	v_mfma_f32_16x16x32_bf16 v[64:67], v[194:197], v[160:163], v[64:67]
	s_add_i32 m0, s35, 0xc000
	v_mfma_f32_16x16x32_bf16 v[68:71], v[202:205], v[160:163], v[68:71]
	global_load_lds_dwordx4 v249, s[56:57]
	v_mfma_f32_16x16x32_bf16 v[72:75], v[194:197], v[168:171], v[72:75]
	s_add_i32 m0, s35, 0xe000
	v_mfma_f32_16x16x32_bf16 v[76:79], v[202:205], v[168:171], v[76:79]
	global_load_lds_dwordx4 v250, s[56:57]
	v_mfma_f32_16x16x32_bf16 v[80:83], v[194:197], v[176:179], v[80:83]
	s_add_i32 m0, s35, 0x18000
	v_mfma_f32_16x16x32_bf16 v[84:87], v[202:205], v[176:179], v[84:87]
	global_load_lds_dwordx4 v251, s[32:33]
	v_mfma_f32_16x16x32_bf16 v[88:91], v[194:197], v[186:189], v[88:91]
	s_add_i32 m0, s35, 0x1a000
	v_mfma_f32_16x16x32_bf16 v[92:95], v[202:205], v[186:189], v[92:95]
	global_load_lds_dwordx4 v252, s[32:33]
	v_mfma_f32_16x16x32_bf16 v[64:67], v[198:201], v[164:167], v[64:67]
	ds_read_b128 v[128:131], v245 offset:0
	v_mfma_f32_16x16x32_bf16 v[68:71], v[206:209], v[164:167], v[68:71]
	ds_read_b128 v[132:135], v246 offset:0
	v_mfma_f32_16x16x32_bf16 v[72:75], v[198:201], v[172:175], v[72:75]
	ds_read_b128 v[136:139], v245 offset:2048
	v_mfma_f32_16x16x32_bf16 v[76:79], v[206:209], v[172:175], v[76:79]
	ds_read_b128 v[140:143], v246 offset:2048
	v_mfma_f32_16x16x32_bf16 v[80:83], v[198:201], v[180:183], v[80:83]
	ds_read_b128 v[144:147], v245 offset:4096
	v_mfma_f32_16x16x32_bf16 v[84:87], v[206:209], v[180:183], v[84:87]
	ds_read_b128 v[148:151], v246 offset:4096
	v_mfma_f32_16x16x32_bf16 v[88:91], v[198:201], v[190:193], v[88:91]
	ds_read_b128 v[152:155], v245 offset:6144
	v_mfma_f32_16x16x32_bf16 v[92:95], v[206:209], v[190:193], v[92:95]
	ds_read_b128 v[156:159], v246 offset:6144
	v_mfma_f32_16x16x32_bf16 v[96:99], v[210:213], v[160:163], v[96:99]
	ds_read_b128 v[194:197], v247 offset:0
	v_mfma_f32_16x16x32_bf16 v[100:103], v[218:221], v[160:163], v[100:103]
	ds_read_b128 v[198:201], v248 offset:0
	v_mfma_f32_16x16x32_bf16 v[104:107], v[210:213], v[168:171], v[104:107]
	ds_read_b128 v[202:205], v247 offset:2048
	v_mfma_f32_16x16x32_bf16 v[108:111], v[218:221], v[168:171], v[108:111]
	ds_read_b128 v[206:209], v248 offset:2048
	v_mfma_f32_16x16x32_bf16 v[112:115], v[210:213], v[176:179], v[112:115]
	s_add_u32 s30, s30, s4
	s_addc_u32 s31, s31, s5
	v_mfma_f32_16x16x32_bf16 v[116:119], v[218:221], v[176:179], v[116:119]
	s_add_u32 s56, s56, s4
	s_addc_u32 s57, s57, s5
	v_mfma_f32_16x16x32_bf16 v[120:123], v[210:213], v[186:189], v[120:123]
	s_add_u32 s32, s32, s4
	s_addc_u32 s33, s33, s5
	v_mfma_f32_16x16x32_bf16 v[124:127], v[218:221], v[186:189], v[124:127]
	s_add_u32 s58, s58, s4
	s_addc_u32 s59, s59, s5
	v_mfma_f32_16x16x32_bf16 v[96:99], v[214:217], v[164:167], v[96:99]
	v_mfma_f32_16x16x32_bf16 v[100:103], v[222:225], v[164:167], v[100:103]
	v_mfma_f32_16x16x32_bf16 v[104:107], v[214:217], v[172:175], v[104:107]
	v_mfma_f32_16x16x32_bf16 v[108:111], v[222:225], v[172:175], v[108:111]
	v_mfma_f32_16x16x32_bf16 v[112:115], v[214:217], v[180:183], v[112:115]
	v_mfma_f32_16x16x32_bf16 v[116:119], v[222:225], v[180:183], v[116:119]
	v_mfma_f32_16x16x32_bf16 v[120:123], v[214:217], v[190:193], v[120:123]
	v_mfma_f32_16x16x32_bf16 v[124:127], v[222:225], v[190:193], v[124:127]
	s_add_i32 s34, s34, -1
	s_cmp_lg_u32 s34, 1
	s_cbranch_scc1 .Lp5_nosw0
	s_add_u32 s45, s16, 1
	s_and_b32 s40, s45, 1
	s_lshl_b32 s4, s40, 8
	s_sub_u32 s4, 128, s4
	s_sub_u32 s5, 0, s40
	s_mul_i32 s8, s40, 3968
	s_add_u32 s30, s26, s8
	s_addc_u32 s31, s27, 0
	s_add_u32 s32, s28, s8
	s_addc_u32 s33, s29, 0
	s_add_u32 s56, s30, 0x80000
	s_addc_u32 s57, s31, 0
	s_add_u32 s58, s32, 0x80000
	s_addc_u32 s59, s33, 0

; #define PG8_STAGE(bufoff, gbase, voff) do { _Pragma("unroll") for (int _i = 0; _i < 2; ++_i) \
;         __builtin_amdgcn_global_load_lds((const unsigned*)((const char*)(gbase) + (voff)[_i]), (PG8_LAS unsigned*)(lds + (bufoff) + ldsw + _i * 8192), 16, 0, 0); } while (0)
; #define PG8_LDA(dst, b, h) do { _Pragma("unroll") for (int m = 0; m < 4; ++m) _Pragma("unroll") for (int k = 0; k < 2; ++k) dst[m][k] = *(const PG8_LAS bf16x8*)(lds + PG8_SA(b, h) + aoff + m * 2048 + k * 1024); } while (0)
; #define PG8_LDB(dst, b, h) do { _Pragma("unroll") for (int n = 0; n < 2; ++n) _Pragma("unroll") for (int k = 0; k < 2; ++k) dst[n][k] = *(const PG8_LAS bf16x8*)(lds + PG8_SB(b, h) + boff + n * 2048 + k * 1024); } while (0)
; template <class Epi, class Sched, bool ALIGN_EPI = false, bool SP2 = false>
; __device__ __forceinline__ void gemm_phase(PG8_LAS unsigned char* lds, const Gemm g, const Sched& S, const Epi& E) {
;     ...
;         for (int t = 0; t < nt; t += 2) {
;             const bool last = (t == nt - 2);
;             const char* a1 = cA + (size_t)(t + 1) * kstep;
;             const char* a2 = last ? nA : cA + (size_t)(t + 2) * kstep; const char* b2 = last ? nB : cB + (size_t)(t + 2) * kstep;
;             const char* a3 = a2 + kstep; const char* b3 = b2 + kstep;
;             if (last && has_next) S.a_ready(nxt);
;             if constexpr (SP2) {
;             PG8_LDB(B0, 0, 0); PG8_LDB(B1, 0, 1); PG8_SCHED; PG8_LDA(At, 0, 0); PG8_STAGE(PG8_SA(1, 1), a1 + hstep, voffA);
;             PG8_WAIT_V(8); PG8_WAIT_L(0); PG8_BAR; PG8_MMA(0, 0, At, B0); PG8_MMA(0, 1, At, B1); PG8_BAR; PG8_SCHED;
;             PG8_LDA(At, 0, 1); PG8_STAGE(PG8_SB(0, 0), b2, voffB); PG8_STAGE(PG8_SB(0, 1), b2 + hstep, voffB); PG8_STAGE(PG8_SA(0, 0), a2, voffA);
;             PG8_WAIT_V(8); PG8_WAIT_L(0); PG8_BAR; PG8_MMA(1, 0, At, B0); PG8_MMA(1, 1, At, B1); PG8_BAR; PG8_SCHED;
;             PG8_LDB(B0, 1, 0); PG8_LDB(B1, 1, 1); PG8_SCHED; PG8_LDA(At, 1, 0); PG8_STAGE(PG8_SA(0, 1), a2 + hstep, voffA);
;             PG8_WAIT_V(8); PG8_WAIT_L(0); PG8_BAR; PG8_MMA(0, 0, At, B0); PG8_MMA(0, 1, At, B1); PG8_BAR; PG8_SCHED;
;             PG8_LDA(At, 1, 1); PG8_STAGE(PG8_SB(1, 0), b3, voffB); PG8_STAGE(PG8_SB(1, 1), b3 + hstep, voffB); PG8_STAGE(PG8_SA(1, 0), a3, voffA);
;             PG8_WAIT_V(8); PG8_WAIT_L(0); PG8_BAR; PG8_MMA(1, 0, At, B0); PG8_MMA(1, 1, At, B1); PG8_BAR; PG8_SCHED;
.Lp5_kloop1:
	s_waitcnt vmcnt(8)
	s_waitcnt lgkmcnt(0)
	s_barrier
	v_mfma_f32_16x16x32_bf16 v[0:3], v[194:197], v[128:131], v[0:3]
	ds_read_b128 v[210:213], v247 offset:16384
	v_mfma_f32_16x16x32_bf16 v[4:7], v[202:205], v[128:131], v[4:7]
	ds_read_b128 v[214:217], v248 offset:16384
	v_mfma_f32_16x16x32_bf16 v[8:11], v[194:197], v[136:139], v[8:11]
	ds_read_b128 v[218:221], v247 offset:18432
	v_mfma_f32_16x16x32_bf16 v[12:15], v[202:205], v[136:139], v[12:15]
	ds_read_b128 v[222:225], v248 offset:18432
	v_mfma_f32_16x16x32_bf16 v[16:19], v[194:197], v[144:147], v[16:19]
	ds_read_b128 v[160:163], v245 offset:16384
	v_mfma_f32_16x16x32_bf16 v[20:23], v[202:205], v[144:147], v[20:23]
	ds_read_b128 v[164:167], v246 offset:16384
	v_mfma_f32_16x16x32_bf16 v[24:27], v[194:197], v[152:155], v[24:27]
	ds_read_b128 v[168:171], v245 offset:18432
	v_mfma_f32_16x16x32_bf16 v[28:31], v[202:205], v[152:155], v[28:31]
	ds_read_b128 v[172:175], v246 offset:18432
	v_mfma_f32_16x16x32_bf16 v[0:3], v[198:201], v[132:135], v[0:3]
	ds_read_b128 v[176:179], v245 offset:20480
	v_mfma_f32_16x16x32_bf16 v[4:7], v[206:209], v[132:135], v[4:7]
	ds_read_b128 v[180:183], v246 offset:20480
	v_mfma_f32_16x16x32_bf16 v[8:11], v[198:201], v[140:143], v[8:11]
	ds_read_b128 v[186:189], v245 offset:22528
	v_mfma_f32_16x16x32_bf16 v[12:15], v[206:209], v[140:143], v[12:15]
	ds_read_b128 v[190:193], v246 offset:22528
	v_mfma_f32_16x16x32_bf16 v[16:19], v[198:201], v[148:151], v[16:19]
	v_mfma_f32_16x16x32_bf16 v[20:23], v[206:209], v[148:151], v[20:23]
	v_mfma_f32_16x16x32_bf16 v[24:27], v[198:201], v[156:159], v[24:27]
	v_mfma_f32_16x16x32_bf16 v[28:31], v[206:209], v[156:159], v[28:31]
	s_waitcnt lgkmcnt(8)
	v_mfma_f32_16x16x32_bf16 v[32:35], v[210:213], v[128:131], v[32:35]
	v_mfma_f32_16x16x32_bf16 v[36:39], v[218:221], v[128:131], v[36:39]
	s_add_i32 m0, s35, 0x0
	v_mfma_f32_16x16x32_bf16 v[40:43], v[210:213], v[136:139], v[40:43]
	global_load_lds_dwordx4 v249, s[30:31]
	v_mfma_f32_16x16x32_bf16 v[44:47], v[218:221], v[136:139], v[44:47]
	v_mfma_f32_16x16x32_bf16 v[48:51], v[210:213], v[144:147], v[48:51]
	s_add_i32 m0, s35, 0x2000
	v_mfma_f32_16x16x32_bf16 v[52:55], v[218:221], v[144:147], v[52:55]
	global_load_lds_dwordx4 v250, s[30:31]
	v_mfma_f32_16x16x32_bf16 v[56:59], v[210:213], v[152:155], v[56:59]
	v_mfma_f32_16x16x32_bf16 v[60:63], v[218:221], v[152:155], v[60:63]
	s_add_i32 m0, s35, 0x10000
	v_mfma_f32_16x16x32_bf16 v[32:35], v[214:217], v[132:135], v[32:35]
	global_load_lds_dwordx4 v251, s[32:33]
	v_mfma_f32_16x16x32_bf16 v[36:39], v[222:225], v[132:135], v[36:39]
	v_mfma_f32_16x16x32_bf16 v[40:43], v[214:217], v[140:143], v[40:43]
	s_add_i32 m0, s35, 0x12000
	v_mfma_f32_16x16x32_bf16 v[44:47], v[222:225], v[140:143], v[44:47]
	global_load_lds_dwordx4 v252, s[32:33]
	v_mfma_f32_16x16x32_bf16 v[48:51], v[214:217], v[148:151], v[48:51]
	v_mfma_f32_16x16x32_bf16 v[52:55], v[222:225], v[148:151], v[52:55]
	v_mfma_f32_16x16x32_bf16 v[56:59], v[214:217], v[156:159], v[56:59]
	v_mfma_f32_16x16x32_bf16 v[60:63], v[222:225], v[156:159], v[60:63]
	s_waitcnt vmcnt(8)
	s_waitcnt lgkmcnt(0)
	s_barrier
	v_mfma_f32_16x16x32_bf16 v[96:99], v[210:213], v[160:163], v[96:99]
	ds_read_b128 v[128:131], v245 offset:32768
	v_mfma_f32_16x16x32_bf16 v[100:103], v[218:221], v[160:163], v[100:103]
	ds_read_b128 v[132:135], v246 offset:32768
	v_mfma_f32_16x16x32_bf16 v[104:107], v[210:213], v[168:171], v[104:107]
	ds_read_b128 v[136:139], v245 offset:34816
	v_mfma_f32_16x16x32_bf16 v[108:111], v[218:221], v[168:171], v[108:111]
	ds_read_b128 v[140:143], v246 offset:34816
	v_mfma_f32_16x16x32_bf16 v[112:115], v[210:213], v[176:179], v[112:115]
	ds_read_b128 v[144:147], v245 offset:36864
	v_mfma_f32_16x16x32_bf16 v[116:119], v[218:221], v[176:179], v[116:119]
	ds_read_b128 v[148:151], v246 offset:36864
	v_mfma_f32_16x16x32_bf16 v[120:123], v[210:213], v[186:189], v[120:123]
	ds_read_b128 v[152:155], v245 offset:38912
	v_mfma_f32_16x16x32_bf16 v[124:127], v[218:221], v[186:189], v[124:127]
	ds_read_b128 v[156:159], v246 offset:38912
	v_mfma_f32_16x16x32_bf16 v[96:99], v[214:217], v[164:167], v[96:99]
	v_mfma_f32_16x16x32_bf16 v[100:103], v[222:225], v[164:167], v[100:103]
	v_mfma_f32_16x16x32_bf16 v[104:107], v[214:217], v[172:175], v[104:107]
	v_mfma_f32_16x16x32_bf16 v[108:111], v[222:225], v[172:175], v[108:111]
	v_mfma_f32_16x16x32_bf16 v[112:115], v[214:217], v[180:183], v[112:115]
	v_mfma_f32_16x16x32_bf16 v[116:119], v[222:225], v[180:183], v[116:119]
	v_mfma_f32_16x16x32_bf16 v[120:123], v[214:217], v[190:193], v[120:123]
	v_mfma_f32_16x16x32_bf16 v[124:127], v[222:225], v[190:193], v[124:127]
	v_mfma_f32_16x16x32_bf16 v[64:67], v[194:197], v[160:163], v[64:67]
	ds_read_b128 v[210:213], v247 offset:49152
	v_mfma_f32_16x16x32_bf16 v[68:71], v[202:205], v[160:163], v[68:71]
	ds_read_b128 v[214:217], v248 offset:49152
	v_mfma_f32_16x16x32_bf16 v[72:75], v[194:197], v[168:171], v[72:75]
	ds_read_b128 v[218:221], v247 offset:51200
	v_mfma_f32_16x16x32_bf16 v[76:79], v[202:205], v[168:171], v[76:79]
	ds_read_b128 v[222:225], v248 offset:51200
	v_mfma_f32_16x16x32_bf16 v[80:83], v[194:197], v[176:179], v[80:83]
	s_add_i32 m0, s35, 0x4000
	v_mfma_f32_16x16x32_bf16 v[84:87], v[202:205], v[176:179], v[84:87]
	global_load_lds_dwordx4 v249, s[56:57]
	v_mfma_f32_16x16x32_bf16 v[88:91], v[194:197], v[186:189], v[88:91]
	s_add_i32 m0, s35, 0x6000
	v_mfma_f32_16x16x32_bf16 v[92:95], v[202:205], v[186:189], v[92:95]
	global_load_lds_dwordx4 v250, s[56:57]
	v_mfma_f32_16x16x32_bf16 v[64:67], v[198:201], v[164:167], v[64:67]
	s_add_i32 m0, s35, 0x14000
	v_mfma_f32_16x16x32_bf16 v[68:71], v[206:209], v[164:167], v[68:71]
	global_load_lds_dwordx4 v251, s[58:59]
	v_mfma_f32_16x16x32_bf16 v[72:75], v[198:201], v[172:175], v[72:75]
	s_add_i32 m0, s35, 0x16000
	v_mfma_f32_16x16x32_bf16 v[76:79], v[206:209], v[172:175], v[76:79]
	global_load_lds_dwordx4 v252, s[58:59]
	v_mfma_f32_16x16x32_bf16 v[80:83], v[198:201], v[180:183], v[80:83]
	s_add_u32 s30, s30, s4
	s_addc_u32 s31, s31, s5
	v_mfma_f32_16x16x32_bf16 v[84:87], v[206:209], v[180:183], v[84:87]
	s_add_u32 s56, s56, s4
	s_addc_u32 s57, s57, s5
	v_mfma_f32_16x16x32_bf16 v[88:91], v[198:201], v[190:193], v[88:91]
	s_add_u32 s32, s32, s4
	s_addc_u32 s33, s33, s5
	v_mfma_f32_16x16x32_bf16 v[92:95], v[206:209], v[190:193], v[92:95]
	s_add_u32 s58, s58, s4
	s_addc_u32 s59, s59, s5
	s_waitcnt vmcnt(8)
	s_waitcnt lgkmcnt(0)
	s_barrier
; #define PG8_STAGE(bufoff, gbase, voff) do { _Pragma("unroll") for (int _i = 0; _i < 2; ++_i) \
;         __builtin_amdgcn_global_load_lds((const unsigned*)((const char*)(gbase) + (voff)[_i]), (PG8_LAS unsigned*)(lds + (bufoff) + ldsw + _i * 8192), 16, 0, 0); } while (0)
; #define PG8_LDA(dst, b, h) do { _Pragma("unroll") for (int m = 0; m < 4; ++m) _Pragma("unroll") for (int k = 0; k < 2; ++k) dst[m][k] = *(const PG8_LAS bf16x8*)(lds + PG8_SA(b, h) + aoff + m * 2048 + k * 1024); } while (0)
; #define PG8_LDB(dst, b, h) do { _Pragma("unroll") for (int n = 0; n < 2; ++n) _Pragma("unroll") for (int k = 0; k < 2; ++k) dst[n][k] = *(const PG8_LAS bf16x8*)(lds + PG8_SB(b, h) + boff + n * 2048 + k * 1024); } while (0)
; template <class Epi, class Sched, bool ALIGN_EPI = false, bool SP2 = false>
; __device__ __forceinline__ void gemm_phase(PG8_LAS unsigned char* lds, const Gemm g, const Sched& S, const Epi& E) {
;     ...
;         for (int t = 0; t < nt; t += 2) {
;             const bool last = (t == nt - 2);
;             const char* a1 = cA + (size_t)(t + 1) * kstep;
;             const char* a2 = last ? nA : cA + (size_t)(t + 2) * kstep; const char* b2 = last ? nB : cB + (size_t)(t + 2) * kstep;
;             const char* a3 = a2 + kstep; const char* b3 = b2 + kstep;
;             if (last && has_next) S.a_ready(nxt);
;             if constexpr (SP2) {
;             PG8_LDB(B0, 0, 0); PG8_LDB(B1, 0, 1); PG8_SCHED; PG8_LDA(At, 0, 0); PG8_STAGE(PG8_SA(1, 1), a1 + hstep, voffA);
;             PG8_WAIT_V(8); PG8_WAIT_L(0); PG8_BAR; PG8_MMA(0, 0, At, B0); PG8_MMA(0, 1, At, B1); PG8_BAR; PG8_SCHED;
;             PG8_LDA(At, 0, 1); PG8_STAGE(PG8_SB(0, 0), b2, voffB); PG8_STAGE(PG8_SB(0, 1), b2 + hstep, voffB); PG8_STAGE(PG8_SA(0, 0), a2, voffA);
;             PG8_WAIT_V(8); PG8_WAIT_L(0); PG8_BAR; PG8_MMA(1, 0, At, B0); PG8_MMA(1, 1, At, B1); PG8_BAR; PG8_SCHED;
;             PG8_LDB(B0, 1, 0); PG8_LDB(B1, 1, 1); PG8_SCHED; PG8_LDA(At, 1, 0); PG8_STAGE(PG8_SA(0, 1), a2 + hstep, voffA);
;             PG8_WAIT_V(8); PG8_WAIT_L(0); PG8_BAR; PG8_MMA(0, 0, At, B0); PG8_MMA(0, 1, At, B1); PG8_BAR; PG8_SCHED;
;             PG8_LDA(At, 1, 1); PG8_STAGE(PG8_SB(1, 0), b3, voffB); PG8_STAGE(PG8_SB(1, 1), b3 + hstep, voffB); PG8_STAGE(PG8_SA(1, 0), a3, voffA);
;             PG8_WAIT_V(8); PG8_WAIT_L(0); PG8_BAR; PG8_MMA(1, 0, At, B0); PG8_MMA(1, 1, At, B1); PG8_BAR; PG8_SCHED;
	v_mfma_f32_16x16x32_bf16 v[32:35], v[210:213], v[128:131], v[32:35]
	ds_read_b128 v[194:197], v247 offset:32768
	v_mfma_f32_16x16x32_bf16 v[36:39], v[218:221], v[128:131], v[36:39]
	ds_read_b128 v[198:201], v248 offset:32768
	v_mfma_f32_16x16x32_bf16 v[40:43], v[210:213], v[136:139], v[40:43]
	ds_read_b128 v[202:205], v247 offset:34816
	v_mfma_f32_16x16x32_bf16 v[44:47], v[218:221], v[136:139], v[44:47]
	ds_read_b128 v[206:209], v248 offset:34816
	v_mfma_f32_16x16x32_bf16 v[48:51], v[210:213], v[144:147], v[48:51]
	ds_read_b128 v[160:163], v245 offset:49152
	v_mfma_f32_16x16x32_bf16 v[52:55], v[218:221], v[144:147], v[52:55]
	ds_read_b128 v[164:167], v246 offset:49152
	v_mfma_f32_16x16x32_bf16 v[56:59], v[210:213], v[152:155], v[56:59]
	ds_read_b128 v[168:171], v245 offset:51200
	v_mfma_f32_16x16x32_bf16 v[60:63], v[218:221], v[152:155], v[60:63]
	ds_read_b128 v[172:175], v246 offset:51200
	v_mfma_f32_16x16x32_bf16 v[32:35], v[214:217], v[132:135], v[32:35]
	ds_read_b128 v[176:179], v245 offset:53248
	v_mfma_f32_16x16x32_bf16 v[36:39], v[222:225], v[132:135], v[36:39]
	ds_read_b128 v[180:183], v246 offset:53248
	v_mfma_f32_16x16x32_bf16 v[40:43], v[214:217], v[140:143], v[40:43]
	ds_read_b128 v[186:189], v245 offset:55296
	v_mfma_f32_16x16x32_bf16 v[44:47], v[222:225], v[140:143], v[44:47]
	ds_read_b128 v[190:193], v246 offset:55296
	v_mfma_f32_16x16x32_bf16 v[48:51], v[214:217], v[148:151], v[48:51]
	v_mfma_f32_16x16x32_bf16 v[52:55], v[222:225], v[148:151], v[52:55]
	v_mfma_f32_16x16x32_bf16 v[56:59], v[214:217], v[156:159], v[56:59]
	v_mfma_f32_16x16x32_bf16 v[60:63], v[222:225], v[156:159], v[60:63]
	s_waitcnt lgkmcnt(8)
	v_mfma_f32_16x16x32_bf16 v[0:3], v[194:197], v[128:131], v[0:3]
	v_mfma_f32_16x16x32_bf16 v[4:7], v[202:205], v[128:131], v[4:7]
	s_add_i32 m0, s35, 0x8000
	v_mfma_f32_16x16x32_bf16 v[8:11], v[194:197], v[136:139], v[8:11]
	global_load_lds_dwordx4 v249, s[30:31]
	v_mfma_f32_16x16x32_bf16 v[12:15], v[202:205], v[136:139], v[12:15]
	v_mfma_f32_16x16x32_bf16 v[16:19], v[194:197], v[144:147], v[16:19]
	s_add_i32 m0, s35, 0xa000
	v_mfma_f32_16x16x32_bf16 v[20:23], v[202:205], v[144:147], v[20:23]
	global_load_lds_dwordx4 v250, s[30:31]
	v_mfma_f32_16x16x32_bf16 v[24:27], v[194:197], v[152:155], v[24:27]
	v_mfma_f32_16x16x32_bf16 v[28:31], v[202:205], v[152:155], v[28:31]
	s_add_i32 m0, s35, 0x1c000
	v_mfma_f32_16x16x32_bf16 v[0:3], v[198:201], v[132:135], v[0:3]
	global_load_lds_dwordx4 v251, s[58:59]
	v_mfma_f32_16x16x32_bf16 v[4:7], v[206:209], v[132:135], v[4:7]
	v_mfma_f32_16x16x32_bf16 v[8:11], v[198:201], v[140:143], v[8:11]
	s_add_i32 m0, s35, 0x1e000
	v_mfma_f32_16x16x32_bf16 v[12:15], v[206:209], v[140:143], v[12:15]
	global_load_lds_dwordx4 v252, s[58:59]
	v_mfma_f32_16x16x32_bf16 v[16:19], v[198:201], v[148:151], v[16:19]
	v_mfma_f32_16x16x32_bf16 v[20:23], v[206:209], v[148:151], v[20:23]
	v_mfma_f32_16x16x32_bf16 v[24:27], v[198:201], v[156:159], v[24:27]
	v_mfma_f32_16x16x32_bf16 v[28:31], v[206:209], v[156:159], v[28:31]
	s_waitcnt vmcnt(8)
	s_waitcnt lgkmcnt(0)
	s_barrier
	v_mfma_f32_16x16x32_bf16 v[64:67], v[194:197], v[160:163], v[64:67]
	ds_read_b128 v[128:131], v245 offset:0
	v_mfma_f32_16x16x32_bf16 v[68:71], v[202:205], v[160:163], v[68:71]
	ds_read_b128 v[132:135], v246 offset:0
	v_mfma_f32_16x16x32_bf16 v[72:75], v[194:197], v[168:171], v[72:75]
	ds_read_b128 v[136:139], v245 offset:2048
	v_mfma_f32_16x16x32_bf16 v[76:79], v[202:205], v[168:171], v[76:79]
	ds_read_b128 v[140:143], v246 offset:2048
	v_mfma_f32_16x16x32_bf16 v[80:83], v[194:197], v[176:179], v[80:83]
	ds_read_b128 v[144:147], v245 offset:4096
	v_mfma_f32_16x16x32_bf16 v[84:87], v[202:205], v[176:179], v[84:87]
	ds_read_b128 v[148:151], v246 offset:4096
	v_mfma_f32_16x16x32_bf16 v[88:91], v[194:197], v[186:189], v[88:91]
	ds_read_b128 v[152:155], v245 offset:6144
	v_mfma_f32_16x16x32_bf16 v[92:95], v[202:205], v[186:189], v[92:95]
	ds_read_b128 v[156:159], v246 offset:6144
	v_mfma_f32_16x16x32_bf16 v[64:67], v[198:201], v[164:167], v[64:67]
	v_mfma_f32_16x16x32_bf16 v[68:71], v[206:209], v[164:167], v[68:71]
	v_mfma_f32_16x16x32_bf16 v[72:75], v[198:201], v[172:175], v[72:75]
	v_mfma_f32_16x16x32_bf16 v[76:79], v[206:209], v[172:175], v[76:79]
	v_mfma_f32_16x16x32_bf16 v[80:83], v[198:201], v[180:183], v[80:83]
	v_mfma_f32_16x16x32_bf16 v[84:87], v[206:209], v[180:183], v[84:87]
	v_mfma_f32_16x16x32_bf16 v[88:91], v[198:201], v[190:193], v[88:91]
	v_mfma_f32_16x16x32_bf16 v[92:95], v[206:209], v[190:193], v[92:95]
	v_mfma_f32_16x16x32_bf16 v[96:99], v[210:213], v[160:163], v[96:99]
	ds_read_b128 v[194:197], v247 offset:0
	v_mfma_f32_16x16x32_bf16 v[100:103], v[218:221], v[160:163], v[100:103]
	ds_read_b128 v[198:201], v248 offset:0
	v_mfma_f32_16x16x32_bf16 v[104:107], v[210:213], v[168:171], v[104:107]
	ds_read_b128 v[202:205], v247 offset:2048
	v_mfma_f32_16x16x32_bf16 v[108:111], v[218:221], v[168:171], v[108:111]
	ds_read_b128 v[206:209], v248 offset:2048
	v_mfma_f32_16x16x32_bf16 v[112:115], v[210:213], v[176:179], v[112:115]
	s_add_i32 m0, s35, 0xc000
	v_mfma_f32_16x16x32_bf16 v[116:119], v[218:221], v[176:179], v[116:119]
	global_load_lds_dwordx4 v249, s[56:57]
	v_mfma_f32_16x16x32_bf16 v[120:123], v[210:213], v[186:189], v[120:123]
	s_add_i32 m0, s35, 0xe000
	v_mfma_f32_16x16x32_bf16 v[124:127], v[218:221], v[186:189], v[124:127]
	global_load_lds_dwordx4 v250, s[56:57]
	v_mfma_f32_16x16x32_bf16 v[96:99], v[214:217], v[164:167], v[96:99]
	s_add_i32 m0, s35, 0x18000
	v_mfma_f32_16x16x32_bf16 v[100:103], v[222:225], v[164:167], v[100:103]
	global_load_lds_dwordx4 v251, s[32:33]
	v_mfma_f32_16x16x32_bf16 v[104:107], v[214:217], v[172:175], v[104:107]
	s_add_i32 m0, s35, 0x1a000
	v_mfma_f32_16x16x32_bf16 v[108:111], v[222:225], v[172:175], v[108:111]
	global_load_lds_dwordx4 v252, s[32:33]
	v_mfma_f32_16x16x32_bf16 v[112:115], v[214:217], v[180:183], v[112:115]
	s_add_u32 s30, s30, s4
	s_addc_u32 s31, s31, s5
	v_mfma_f32_16x16x32_bf16 v[116:119], v[222:225], v[180:183], v[116:119]
	s_add_u32 s56, s56, s4
	s_addc_u32 s57, s57, s5
	v_mfma_f32_16x16x32_bf16 v[120:123], v[214:217], v[190:193], v[120:123]
	s_add_u32 s32, s32, s4
	s_addc_u32 s33, s33, s5
	v_mfma_f32_16x16x32_bf16 v[124:127], v[222:225], v[190:193], v[124:127]
	s_add_u32 s58, s58, s4
	s_addc_u32 s59, s59, s5
	s_add_i32 s34, s34, -1
	s_cmp_lg_u32 s34, 1
	s_cbranch_scc1 .Lp5_nosw1
	s_add_u32 s45, s16, 1
	s_and_b32 s40, s45, 1
	s_lshl_b32 s4, s40, 8
	s_sub_u32 s4, 128, s4
	s_sub_u32 s5, 0, s40
	s_mul_i32 s8, s40, 3968
	s_add_u32 s30, s26, s8
	s_addc_u32 s31, s27, 0
	s_add_u32 s32, s28, s8
	s_addc_u32 s33, s29, 0
	s_add_u32 s56, s30, 0x80000
	s_addc_u32 s57, s31, 0
	s_add_u32 s58, s32, 0x80000
	s_addc_u32 s59, s33, 0

; template <class Epi, class Sched, bool ALIGN_EPI = false, bool SP2 = false>
; __device__ __forceinline__ void gemm_phase(PG8_LAS unsigned char* lds, const Gemm g, const Sched& S, const Epi& E) {
;     ...
;     const int tid = tid_, wid = __builtin_amdgcn_readfirstlane(tid >> 6), lane = tid & 63, wr = wid >> 2, wc = wid & 3, fr = lane & 15, fq = lane >> 4;
;     const int K = g.K, nt = K / BK;
;     unsigned voffA[2], voffB[2];
; #pragma unroll
;     for (int i = 0; i < 2; ++i) { int R, C; stage_rc(tid * 16 + i * 8192, R, C); const int Rb = Epi::PERM ? ((R & ~31) + perm32(R & 31)) : R;
;         voffA[i] = (unsigned)(R * K + C) * 2u; voffB[i] = (unsigned)(Rb * K + C) * 2u; }
;     const size_t kstep = (size_t)(BK * 2);
;     const size_t hstep = (size_t)HALF * K * 2;
;     const size_t tstep = 2 * hstep;
;     const unsigned ldsw = (unsigned)wid * 1024u;
;     const int aoff = lds_byte(wr * 64 + fr, fq * 8), boff = lds_byte(wc * 32 + fr, fq * 8);
;     ...
;     Unit cur, nxt; int ui = 0;
;     if (!S.next(0, cur)) return;
;     f32x4 acc[2][2][4][2];
; #pragma unroll
;     for (int a = 0; a < 2; ++a)
; #pragma unroll
;         for (int b = 0; b < 2; ++b)
; #pragma unroll
;             for (int m = 0; m < 4; ++m)
; #pragma unroll
;                 for (int n = 0; n < 2; ++n) acc[a][b][m][n] = (f32x4){0.f, 0.f, 0.f, 0.f};
;     bf16x8 At[4][2], B0[2][2], B1[2][2];
;     const char* cA = (const char*)g.A + (size_t)cur.pm * tstep; const char* cB = (const char*)g.Bt + (size_t)cur.pn * tstep;
;     S.a_ready(cur);
;     if constexpr (SP2) {
;         PG8_STAGE(PG8_SB(0, 0), cB, voffB); PG8_STAGE(PG8_SB(0, 1), cB + hstep, voffB); PG8_STAGE(PG8_SA(0, 0), cA, voffA); PG8_STAGE(PG8_SA(0, 1), cA + hstep, voffA);
;         if (wr == 1) PG8_BAR;
;         PG8_WAIT_V(2); PG8_BAR;
;         PG8_STAGE(PG8_SB(1, 0), cB + kstep, voffB); PG8_STAGE(PG8_SA(1, 0), cA + kstep, voffA); PG8_STAGE(PG8_SB(1, 1), cB + hstep + kstep, voffB);
;         PG8_WAIT_V(6); PG8_BAR;
;     } else {
;         PG8_STAGE(PG8_SB(0, 0), cB, voffB); PG8_STAGE(PG8_SA(0, 0), cA, voffA); PG8_STAGE(PG8_SB(0, 1), cB + hstep, voffB); PG8_STAGE(PG8_SA(0, 1), cA + hstep, voffA);
;         if (wr == 1) PG8_BAR;
;         PG8_WAIT_V(4); PG8_BAR;
;         PG8_STAGE(PG8_SB(1, 0), cB + kstep, voffB); PG8_STAGE(PG8_SA(1, 0), cA + kstep, voffA); PG8_STAGE(PG8_SB(1, 1), cB + hstep + kstep, voffB);
;         PG8_WAIT_V(6); PG8_BAR;
.LBB0_840:
	s_cmp_lt_i32 s70, 7
	s_cselect_b64 s[4:5], -1, 0
	s_and_b64 s[8:9], s[4:5], s[0:1]
	s_andn2_b64 vcc, exec, s[8:9]
	s_cbranch_vccnz .LBB0_887
	v_readlane_b32 s100, v244, 4
	s_nop 3
	s_cmp_lg_u32 s100, 0x100
	s_cbranch_scc1 .Lp6_base
	v_writelane_b32 v253, s4, 0
	v_writelane_b32 v253, s5, 1
	v_writelane_b32 v253, s6, 2
	v_writelane_b32 v253, s7, 3
	v_writelane_b32 v253, s8, 4
	v_writelane_b32 v253, s9, 5
	v_writelane_b32 v253, s10, 6
	v_writelane_b32 v253, s11, 7
	v_writelane_b32 v253, s12, 8
	v_writelane_b32 v253, s13, 9
	v_writelane_b32 v253, s14, 10
	v_writelane_b32 v253, s15, 11
	v_writelane_b32 v253, s16, 12
	v_writelane_b32 v253, s17, 13
	v_writelane_b32 v253, s18, 14
	v_writelane_b32 v253, s19, 15
	v_writelane_b32 v253, s20, 16
	v_writelane_b32 v253, s21, 17
	v_writelane_b32 v253, s22, 18
	v_writelane_b32 v253, s23, 19
	v_writelane_b32 v253, s24, 20
	v_writelane_b32 v253, s25, 21
	v_writelane_b32 v253, s26, 22
	v_writelane_b32 v253, s27, 23
	v_writelane_b32 v253, s28, 24
	v_writelane_b32 v253, s29, 25
	v_writelane_b32 v253, s30, 26
	v_writelane_b32 v253, s31, 27
	v_writelane_b32 v253, s32, 28
	v_writelane_b32 v253, s33, 29
	v_writelane_b32 v253, s34, 30
	v_writelane_b32 v253, s35, 31
	v_writelane_b32 v253, s36, 32
	v_writelane_b32 v253, s37, 33
	v_writelane_b32 v253, s38, 34
	v_writelane_b32 v253, s39, 35
	v_writelane_b32 v253, s40, 36
	v_writelane_b32 v253, s41, 37
	v_writelane_b32 v253, s42, 38
	v_writelane_b32 v253, s43, 39
	v_writelane_b32 v253, s44, 40
	v_writelane_b32 v253, s45, 41
	v_writelane_b32 v253, s46, 42
	v_writelane_b32 v253, s47, 43
	v_writelane_b32 v253, s48, 44
	v_writelane_b32 v253, s49, 45
	v_writelane_b32 v253, s50, 46
	v_writelane_b32 v253, s51, 47
	v_writelane_b32 v253, s52, 48
	v_writelane_b32 v253, s53, 49
	v_writelane_b32 v253, s54, 50
	v_writelane_b32 v253, s55, 51
	v_writelane_b32 v253, s56, 52
	v_writelane_b32 v253, s57, 53
	v_writelane_b32 v253, s58, 54
	v_writelane_b32 v253, s59, 55
	s_mov_b32 s40, vcc_lo
	s_mov_b32 s41, vcc_hi
	v_writelane_b32 v253, s40, 60
	v_writelane_b32 v253, s41, 61
	v_lshrrev_b32_e32 v254, 6, v185
	v_readlane_b32 s14, v244, 4
	v_readfirstlane_b32 s36, v254
	s_nop 3
	s_lshr_b32 s37, s36, 2
	s_and_b32 s38, s36, 3
	s_lshl_b32 s35, s36, 10
	s_add_u32 s10, s76, 0xa800000
	s_addc_u32 s11, s77, 0
	s_add_u32 s12, s76, 0x5100000
	s_addc_u32 s13, s77, 0
	s_mov_b32 s16, 0
	s_mul_i32 s40, s16, s14
	s_add_u32 s40, s40, s2
	s_cmp_lt_u32 s40, 512
	s_cselect_b32 s44, 1, 0
	s_min_u32 s40, s40, 511
	s_and_b32 s41, s40, 7
	s_lshr_b32 s42, s40, 3
	s_mul_i32 s41, s41, 64
	s_add_u32 s41, s41, s42
	s_lshr_b32 s42, s41, 5
	s_and_b32 s43, s41, 31
	s_and_b32 s40, s43, 3
	s_lshl_b32 s42, s42, 2
	s_add_u32 s17, s42, s40
	s_lshr_b32 s18, s43, 2
	s_cmp_eq_u32 s44, 0
	s_cbranch_scc1 .Lp6_exit
	v_and_b32_e32 v254, 63, v185
	v_and_b32_e32 v255, 15, v254
	v_lshrrev_b32_e32 v226, 1, v255
	v_lshrrev_b32_e32 v227, 4, v254
	v_xor_b32_e32 v226, v226, v227
	v_lshlrev_b32_e32 v255, 7, v255
	v_lshl_or_b32 v255, v226, 4, v255
	s_lshl_b32 s40, s37, 13
	s_lshl_b32 s41, s38, 12
	s_add_u32 s41, s41, 0x10000
	v_add_u32_e32 v245, s40, v255
	v_add_u32_e32 v247, s41, v255
	v_xor_b32_e32 v246, 64, v245
	v_xor_b32_e32 v248, 64, v247
	v_lshrrev_b32_e32 v255, 3, v254
	v_and_b32_e32 v226, 7, v254
	s_and_b32 s40, s36, 1
	s_lshl_b32 s40, s40, 2
	v_lshrrev_b32_e32 v227, 1, v255
	v_add_u32_e32 v227, s40, v227
	v_xor_b32_e32 v226, v226, v227
	v_lshlrev_b32_e32 v226, 4, v226
	s_lshl_b32 s40, s36, 3
	v_add_u32_e32 v227, s40, v255
	v_mul_u32_u24_e32 v227, 0x2c00, v227
	v_add_u32_e32 v249, v227, v226
	v_add_u32_e32 v250, 0xb0000, v249
	s_and_b32 s40, s36, 3
	s_lshl_b32 s40, s40, 3
	v_add_u32_e32 v227, s40, v255
	v_lshrrev_b32_e32 v254, 4, v227
	v_lshlrev_b32_e32 v254, 2, v254
	v_and_b32_e32 v255, 3, v227
	v_add_u32_e32 v254, v254, v255
	v_and_b32_e32 v227, 12, v227
	v_lshl_add_u32 v254, v227, 1, v254
	s_lshr_b32 s40, s36, 2
	s_lshl_b32 s40, s40, 5
	v_add_u32_e32 v254, s40, v254
	v_mul_u32_u24_e32 v254, 0x2c00, v254
	v_add_u32_e32 v251, v254, v226
	v_add_u32_e32 v252, 0xb0000, v251
	s_mul_i32 s40, s17, 0x2c0000
	s_add_u32 s22, s10, s40
	s_addc_u32 s23, s11, 0
	s_mul_i32 s40, s18, 0x2c0000
	s_add_u32 s24, s12, s40
	s_addc_u32 s25, s13, 0
	s_and_b32 s40, s16, 1
	s_lshl_b32 s4, s40, 8
	s_sub_u32 s4, 128, s4
	s_sub_u32 s5, 0, s40
	s_mul_i32 s8, s40, 11136
	s_add_u32 s30, s22, s8
	s_addc_u32 s31, s23, 0
	s_add_u32 s32, s24, s8
	s_addc_u32 s33, s25, 0
	s_add_u32 s56, s30, 0x160000
	s_addc_u32 s57, s31, 0
	s_add_u32 s58, s32, 0x160000
	s_addc_u32 s59, s33, 0
	s_add_i32 m0, s35, 0x0
	s_nop 0
	global_load_lds_dwordx4 v249, s[30:31]
	s_add_i32 m0, s35, 0x2000
	s_nop 0
	global_load_lds_dwordx4 v250, s[30:31]
	s_add_i32 m0, s35, 0x10000
	s_nop 0
	global_load_lds_dwordx4 v251, s[32:33]
	s_add_i32 m0, s35, 0x12000
	s_nop 0
	global_load_lds_dwordx4 v252, s[32:33]
	s_add_i32 m0, s35, 0x4000
	s_nop 0
	global_load_lds_dwordx4 v249, s[56:57]
	s_add_i32 m0, s35, 0x6000
	s_nop 0
	global_load_lds_dwordx4 v250, s[56:57]
	s_add_i32 m0, s35, 0x14000
	s_nop 0
	global_load_lds_dwordx4 v251, s[58:59]
	s_add_i32 m0, s35, 0x16000
	s_nop 0
	global_load_lds_dwordx4 v252, s[58:59]
	s_add_u32 s30, s30, s4
	s_addc_u32 s31, s31, s5
	s_add_u32 s56, s56, s4
	s_addc_u32 s57, s57, s5
	s_add_u32 s32, s32, s4
	s_addc_u32 s33, s33, s5
	s_add_u32 s58, s58, s4
	s_addc_u32 s59, s59, s5
	s_add_i32 m0, s35, 0x8000
	s_nop 0
	global_load_lds_dwordx4 v249, s[30:31]
	s_add_i32 m0, s35, 0xa000
	s_nop 0
	global_load_lds_dwordx4 v250, s[30:31]
	s_add_i32 m0, s35, 0x1c000
	s_nop 0
	global_load_lds_dwordx4 v251, s[58:59]
	s_add_i32 m0, s35, 0x1e000
	s_nop 0
	global_load_lds_dwordx4 v252, s[58:59]
	s_add_i32 m0, s35, 0xc000
	s_nop 0
	global_load_lds_dwordx4 v249, s[56:57]
	s_add_i32 m0, s35, 0xe000
	s_nop 0
	global_load_lds_dwordx4 v250, s[56:57]
	s_add_i32 m0, s35, 0x18000
	s_nop 0
	global_load_lds_dwordx4 v251, s[32:33]
	s_add_i32 m0, s35, 0x1a000
	s_nop 0
	global_load_lds_dwordx4 v252, s[32:33]
	s_add_u32 s30, s30, s4
	s_addc_u32 s31, s31, s5
	s_add_u32 s56, s56, s4
	s_addc_u32 s57, s57, s5
	s_add_u32 s32, s32, s4
	s_addc_u32 s33, s33, s5
	s_add_u32 s58, s58, s4
	s_addc_u32 s59, s59, s5
	s_waitcnt vmcnt(12)
	s_barrier
; #define PG8_STAGE(bufoff, gbase, voff) do { _Pragma("unroll") for (int _i = 0; _i < 2; ++_i) \
;         __builtin_amdgcn_global_load_lds((const unsigned*)((const char*)(gbase) + (voff)[_i]), (PG8_LAS unsigned*)(lds + (bufoff) + ldsw + _i * 8192), 16, 0, 0); } while (0)
; #define PG8_LDA(dst, b, h) do { _Pragma("unroll") for (int m = 0; m < 4; ++m) _Pragma("unroll") for (int k = 0; k < 2; ++k) dst[m][k] = *(const PG8_LAS bf16x8*)(lds + PG8_SA(b, h) + aoff + m * 2048 + k * 1024); } while (0)
; #define PG8_LDB(dst, b, h) do { _Pragma("unroll") for (int n = 0; n < 2; ++n) _Pragma("unroll") for (int k = 0; k < 2; ++k) dst[n][k] = *(const PG8_LAS bf16x8*)(lds + PG8_SB(b, h) + boff + n * 2048 + k * 1024); } while (0)
; #define PG8_SCHED __builtin_amdgcn_sched_barrier(0)
; template <class Epi, class Sched, bool ALIGN_EPI = false, bool SP2 = false>
; __device__ __forceinline__ void gemm_phase(PG8_LAS unsigned char* lds, const Gemm g, const Sched& S, const Epi& E) {
;     ...
;         const bool has_next = S.next(ui + 1, nxt);
;         const char* nA = has_next ? (const char*)g.A + (size_t)nxt.pm * tstep : cA; const char* nB = has_next ? (const char*)g.Bt + (size_t)nxt.pn * tstep : cB;
;         for (int t = 0; t < nt; t += 2) {
;             const bool last = (t == nt - 2);
;             const char* a1 = cA + (size_t)(t + 1) * kstep;
;             const char* a2 = last ? nA : cA + (size_t)(t + 2) * kstep; const char* b2 = last ? nB : cB + (size_t)(t + 2) * kstep;
;             const char* a3 = a2 + kstep; const char* b3 = b2 + kstep;
;             if (last && has_next) S.a_ready(nxt);
;             if constexpr (SP2) {
;             PG8_LDB(B0, 0, 0); PG8_LDB(B1, 0, 1); PG8_SCHED; PG8_LDA(At, 0, 0); PG8_STAGE(PG8_SA(1, 1), a1 + hstep, voffA);
;     ...
; #pragma unroll
;         for (int a = 0; a < 2; ++a)
; #pragma unroll
;             for (int b = 0; b < 2; ++b)
; #pragma unroll
;                 for (int m = 0; m < 4; ++m)
; #pragma unroll
;                     for (int n = 0; n < 2; ++n) acc[a][b][m][n] = (f32x4){0.f, 0.f, 0.f, 0.f};
;         cur = nxt; cA = nA; cB = nB; ++ui;
.Lp6_unit:
	s_add_u32 s45, s16, 1
	s_mul_i32 s40, s45, s14
	s_add_u32 s40, s40, s2
	s_cmp_lt_u32 s40, 512
	s_cselect_b32 s19, 1, 0
	s_min_u32 s40, s40, 511
	s_and_b32 s41, s40, 7
	s_lshr_b32 s42, s40, 3
	s_mul_i32 s41, s41, 64
	s_add_u32 s41, s41, s42
	s_lshr_b32 s42, s41, 5
	s_and_b32 s43, s41, 31
	s_and_b32 s40, s43, 3
	s_lshl_b32 s42, s42, 2
	s_add_u32 s20, s42, s40
	s_lshr_b32 s21, s43, 2
	s_mul_i32 s40, s20, 0x2c0000
	s_add_u32 s26, s10, s40
	s_addc_u32 s27, s11, 0
	s_mul_i32 s40, s21, 0x2c0000
	s_add_u32 s28, s12, s40
	s_addc_u32 s29, s13, 0
	s_cmp_eq_u32 s19, 0
	s_cselect_b32 s26, s22, s26
	s_cselect_b32 s27, s23, s27
	s_cselect_b32 s28, s24, s28
	s_cselect_b32 s29, s25, s29
	s_add_u32 s30, s22, s8
	s_addc_u32 s31, s23, 0
	s_add_u32 s32, s24, s8
	s_addc_u32 s33, s25, 0
	s_add_u32 s30, s30, s4
	s_addc_u32 s31, s31, s5
	s_add_u32 s32, s32, s4
	s_addc_u32 s33, s33, s5
	s_add_u32 s30, s30, s4
	s_addc_u32 s31, s31, s5
	s_add_u32 s32, s32, s4
	s_addc_u32 s33, s33, s5
	s_add_u32 s56, s30, 0x160000
	s_addc_u32 s57, s31, 0
	s_add_u32 s58, s32, 0x160000
	s_addc_u32 s59, s33, 0
	s_movk_i32 s34, 44
	v_mov_b32_e32 v0, 0
	v_mov_b32_e32 v1, 0
	v_mov_b32_e32 v2, 0
	v_mov_b32_e32 v3, 0
	v_mov_b32_e32 v4, 0
	v_mov_b32_e32 v5, 0
	v_mov_b32_e32 v6, 0
	v_mov_b32_e32 v7, 0
	v_mov_b32_e32 v8, 0
	v_mov_b32_e32 v9, 0
	v_mov_b32_e32 v10, 0
	v_mov_b32_e32 v11, 0
	v_mov_b32_e32 v12, 0
	v_mov_b32_e32 v13, 0
	v_mov_b32_e32 v14, 0
	v_mov_b32_e32 v15, 0
	v_mov_b32_e32 v16, 0
	v_mov_b32_e32 v17, 0
	v_mov_b32_e32 v18, 0
	v_mov_b32_e32 v19, 0
	v_mov_b32_e32 v20, 0
	v_mov_b32_e32 v21, 0
	v_mov_b32_e32 v22, 0
	v_mov_b32_e32 v23, 0
	v_mov_b32_e32 v24, 0
	v_mov_b32_e32 v25, 0
	v_mov_b32_e32 v26, 0
	v_mov_b32_e32 v27, 0
	v_mov_b32_e32 v28, 0
	v_mov_b32_e32 v29, 0
	v_mov_b32_e32 v30, 0
	v_mov_b32_e32 v31, 0
	v_mov_b32_e32 v32, 0
	v_mov_b32_e32 v33, 0
	v_mov_b32_e32 v34, 0
	v_mov_b32_e32 v35, 0
	v_mov_b32_e32 v36, 0
	v_mov_b32_e32 v37, 0
	v_mov_b32_e32 v38, 0
	v_mov_b32_e32 v39, 0
	v_mov_b32_e32 v40, 0
	v_mov_b32_e32 v41, 0
	v_mov_b32_e32 v42, 0
	v_mov_b32_e32 v43, 0
	v_mov_b32_e32 v44, 0
	v_mov_b32_e32 v45, 0
	v_mov_b32_e32 v46, 0
	v_mov_b32_e32 v47, 0
	v_mov_b32_e32 v48, 0
	v_mov_b32_e32 v49, 0
	v_mov_b32_e32 v50, 0
	v_mov_b32_e32 v51, 0
	v_mov_b32_e32 v52, 0
	v_mov_b32_e32 v53, 0
	v_mov_b32_e32 v54, 0
	v_mov_b32_e32 v55, 0
	v_mov_b32_e32 v56, 0
	v_mov_b32_e32 v57, 0
	v_mov_b32_e32 v58, 0
	v_mov_b32_e32 v59, 0
	v_mov_b32_e32 v60, 0
	v_mov_b32_e32 v61, 0
	v_mov_b32_e32 v62, 0
	v_mov_b32_e32 v63, 0
	v_mov_b32_e32 v64, 0
	v_mov_b32_e32 v65, 0
	v_mov_b32_e32 v66, 0
	v_mov_b32_e32 v67, 0
	v_mov_b32_e32 v68, 0
	v_mov_b32_e32 v69, 0
	v_mov_b32_e32 v70, 0
	v_mov_b32_e32 v71, 0
	v_mov_b32_e32 v72, 0
	v_mov_b32_e32 v73, 0
	v_mov_b32_e32 v74, 0
	v_mov_b32_e32 v75, 0
	v_mov_b32_e32 v76, 0
	v_mov_b32_e32 v77, 0
	v_mov_b32_e32 v78, 0
	v_mov_b32_e32 v79, 0
	v_mov_b32_e32 v80, 0
	v_mov_b32_e32 v81, 0
	v_mov_b32_e32 v82, 0
	v_mov_b32_e32 v83, 0
	v_mov_b32_e32 v84, 0
	v_mov_b32_e32 v85, 0
	v_mov_b32_e32 v86, 0
	v_mov_b32_e32 v87, 0
	v_mov_b32_e32 v88, 0
	v_mov_b32_e32 v89, 0
	v_mov_b32_e32 v90, 0
	v_mov_b32_e32 v91, 0
	v_mov_b32_e32 v92, 0
	v_mov_b32_e32 v93, 0
	v_mov_b32_e32 v94, 0
	v_mov_b32_e32 v95, 0
	v_mov_b32_e32 v96, 0
	v_mov_b32_e32 v97, 0
	v_mov_b32_e32 v98, 0
	v_mov_b32_e32 v99, 0
	v_mov_b32_e32 v100, 0
	v_mov_b32_e32 v101, 0
	v_mov_b32_e32 v102, 0
	v_mov_b32_e32 v103, 0
	v_mov_b32_e32 v104, 0
	v_mov_b32_e32 v105, 0
	v_mov_b32_e32 v106, 0
	v_mov_b32_e32 v107, 0
	v_mov_b32_e32 v108, 0
	v_mov_b32_e32 v109, 0
	v_mov_b32_e32 v110, 0
	v_mov_b32_e32 v111, 0
	v_mov_b32_e32 v112, 0
	v_mov_b32_e32 v113, 0
	v_mov_b32_e32 v114, 0
	v_mov_b32_e32 v115, 0
	v_mov_b32_e32 v116, 0
	v_mov_b32_e32 v117, 0
	v_mov_b32_e32 v118, 0
	v_mov_b32_e32 v119, 0
	v_mov_b32_e32 v120, 0
	v_mov_b32_e32 v121, 0
	v_mov_b32_e32 v122, 0
	v_mov_b32_e32 v123, 0
	v_mov_b32_e32 v124, 0
	v_mov_b32_e32 v125, 0
	v_mov_b32_e32 v126, 0
	v_mov_b32_e32 v127, 0
	ds_read_b128 v[194:197], v247 offset:0
	ds_read_b128 v[198:201], v248 offset:0
	ds_read_b128 v[202:205], v247 offset:2048
	ds_read_b128 v[206:209], v248 offset:2048
	ds_read_b128 v[128:131], v245 offset:0
	ds_read_b128 v[132:135], v246 offset:0
	ds_read_b128 v[136:139], v245 offset:2048
	ds_read_b128 v[140:143], v246 offset:2048
	ds_read_b128 v[144:147], v245 offset:4096
	ds_read_b128 v[148:151], v246 offset:4096
	ds_read_b128 v[152:155], v245 offset:6144
	ds_read_b128 v[156:159], v246 offset:6144
	s_cmp_ge_u32 s36, 4
	s_cbranch_scc1 .Lp6_kloop1
; #define PG8_STAGE(bufoff, gbase, voff) do { _Pragma("unroll") for (int _i = 0; _i < 2; ++_i) \
;         __builtin_amdgcn_global_load_lds((const unsigned*)((const char*)(gbase) + (voff)[_i]), (PG8_LAS unsigned*)(lds + (bufoff) + ldsw + _i * 8192), 16, 0, 0); } while (0)
; #define PG8_LDA(dst, b, h) do { _Pragma("unroll") for (int m = 0; m < 4; ++m) _Pragma("unroll") for (int k = 0; k < 2; ++k) dst[m][k] = *(const PG8_LAS bf16x8*)(lds + PG8_SA(b, h) + aoff + m * 2048 + k * 1024); } while (0)
; #define PG8_LDB(dst, b, h) do { _Pragma("unroll") for (int n = 0; n < 2; ++n) _Pragma("unroll") for (int k = 0; k < 2; ++k) dst[n][k] = *(const PG8_LAS bf16x8*)(lds + PG8_SB(b, h) + boff + n * 2048 + k * 1024); } while (0)
; template <class Epi, class Sched, bool ALIGN_EPI = false, bool SP2 = false>
; __device__ __forceinline__ void gemm_phase(PG8_LAS unsigned char* lds, const Gemm g, const Sched& S, const Epi& E) {
;     ...
;         for (int t = 0; t < nt; t += 2) {
;             const bool last = (t == nt - 2);
;             const char* a1 = cA + (size_t)(t + 1) * kstep;
;             const char* a2 = last ? nA : cA + (size_t)(t + 2) * kstep; const char* b2 = last ? nB : cB + (size_t)(t + 2) * kstep;
;             const char* a3 = a2 + kstep; const char* b3 = b2 + kstep;
;             if (last && has_next) S.a_ready(nxt);
;             if constexpr (SP2) {
;             PG8_LDB(B0, 0, 0); PG8_LDB(B1, 0, 1); PG8_SCHED; PG8_LDA(At, 0, 0); PG8_STAGE(PG8_SA(1, 1), a1 + hstep, voffA);
;             PG8_WAIT_V(8); PG8_WAIT_L(0); PG8_BAR; PG8_MMA(0, 0, At, B0); PG8_MMA(0, 1, At, B1); PG8_BAR; PG8_SCHED;
;             PG8_LDA(At, 0, 1); PG8_STAGE(PG8_SB(0, 0), b2, voffB); PG8_STAGE(PG8_SB(0, 1), b2 + hstep, voffB); PG8_STAGE(PG8_SA(0, 0), a2, voffA);
;             PG8_WAIT_V(8); PG8_WAIT_L(0); PG8_BAR; PG8_MMA(1, 0, At, B0); PG8_MMA(1, 1, At, B1); PG8_BAR; PG8_SCHED;
;             PG8_LDB(B0, 1, 0); PG8_LDB(B1, 1, 1); PG8_SCHED; PG8_LDA(At, 1, 0); PG8_STAGE(PG8_SA(0, 1), a2 + hstep, voffA);
;             PG8_WAIT_V(8); PG8_WAIT_L(0); PG8_BAR; PG8_MMA(0, 0, At, B0); PG8_MMA(0, 1, At, B1); PG8_BAR; PG8_SCHED;
;             PG8_LDA(At, 1, 1); PG8_STAGE(PG8_SB(1, 0), b3, voffB); PG8_STAGE(PG8_SB(1, 1), b3 + hstep, voffB); PG8_STAGE(PG8_SA(1, 0), a3, voffA);
;             PG8_WAIT_V(8); PG8_WAIT_L(0); PG8_BAR; PG8_MMA(1, 0, At, B0); PG8_MMA(1, 1, At, B1); PG8_BAR; PG8_SCHED;
.Lp6_kloop0:
	s_waitcnt vmcnt(8)
	s_waitcnt lgkmcnt(0)
	s_barrier
	v_mfma_f32_16x16x32_bf16 v[0:3], v[194:197], v[128:131], v[0:3]
	ds_read_b128 v[210:213], v247 offset:16384
	v_mfma_f32_16x16x32_bf16 v[4:7], v[202:205], v[128:131], v[4:7]
	ds_read_b128 v[214:217], v248 offset:16384
	v_mfma_f32_16x16x32_bf16 v[8:11], v[194:197], v[136:139], v[8:11]
	ds_read_b128 v[218:221], v247 offset:18432
	v_mfma_f32_16x16x32_bf16 v[12:15], v[202:205], v[136:139], v[12:15]
	ds_read_b128 v[222:225], v248 offset:18432
	v_mfma_f32_16x16x32_bf16 v[16:19], v[194:197], v[144:147], v[16:19]
	s_add_i32 m0, s35, 0x0
	v_mfma_f32_16x16x32_bf16 v[20:23], v[202:205], v[144:147], v[20:23]
	global_load_lds_dwordx4 v249, s[30:31]
	v_mfma_f32_16x16x32_bf16 v[24:27], v[194:197], v[152:155], v[24:27]
	s_add_i32 m0, s35, 0x2000
	v_mfma_f32_16x16x32_bf16 v[28:31], v[202:205], v[152:155], v[28:31]
	global_load_lds_dwordx4 v250, s[30:31]
	v_mfma_f32_16x16x32_bf16 v[0:3], v[198:201], v[132:135], v[0:3]
	s_add_i32 m0, s35, 0x10000
	v_mfma_f32_16x16x32_bf16 v[4:7], v[206:209], v[132:135], v[4:7]
	global_load_lds_dwordx4 v251, s[32:33]
	v_mfma_f32_16x16x32_bf16 v[8:11], v[198:201], v[140:143], v[8:11]
	s_add_i32 m0, s35, 0x12000
	v_mfma_f32_16x16x32_bf16 v[12:15], v[206:209], v[140:143], v[12:15]
	global_load_lds_dwordx4 v252, s[32:33]
	v_mfma_f32_16x16x32_bf16 v[16:19], v[198:201], v[148:151], v[16:19]
	ds_read_b128 v[160:163], v245 offset:16384
	v_mfma_f32_16x16x32_bf16 v[20:23], v[206:209], v[148:151], v[20:23]
	ds_read_b128 v[164:167], v246 offset:16384
	v_mfma_f32_16x16x32_bf16 v[24:27], v[198:201], v[156:159], v[24:27]
	ds_read_b128 v[168:171], v245 offset:18432
	v_mfma_f32_16x16x32_bf16 v[28:31], v[206:209], v[156:159], v[28:31]
	ds_read_b128 v[172:175], v246 offset:18432
	s_waitcnt lgkmcnt(4)
	v_mfma_f32_16x16x32_bf16 v[32:35], v[210:213], v[128:131], v[32:35]
	ds_read_b128 v[176:179], v245 offset:20480
	v_mfma_f32_16x16x32_bf16 v[36:39], v[218:221], v[128:131], v[36:39]
	ds_read_b128 v[180:183], v246 offset:20480
	v_mfma_f32_16x16x32_bf16 v[40:43], v[210:213], v[136:139], v[40:43]
	ds_read_b128 v[186:189], v245 offset:22528
	v_mfma_f32_16x16x32_bf16 v[44:47], v[218:221], v[136:139], v[44:47]
	ds_read_b128 v[190:193], v246 offset:22528
	v_mfma_f32_16x16x32_bf16 v[48:51], v[210:213], v[144:147], v[48:51]
	v_mfma_f32_16x16x32_bf16 v[52:55], v[218:221], v[144:147], v[52:55]
	v_mfma_f32_16x16x32_bf16 v[56:59], v[210:213], v[152:155], v[56:59]
	v_mfma_f32_16x16x32_bf16 v[60:63], v[218:221], v[152:155], v[60:63]
	v_mfma_f32_16x16x32_bf16 v[32:35], v[214:217], v[132:135], v[32:35]
	v_mfma_f32_16x16x32_bf16 v[36:39], v[222:225], v[132:135], v[36:39]
	v_mfma_f32_16x16x32_bf16 v[40:43], v[214:217], v[140:143], v[40:43]
	v_mfma_f32_16x16x32_bf16 v[44:47], v[222:225], v[140:143], v[44:47]
	v_mfma_f32_16x16x32_bf16 v[48:51], v[214:217], v[148:151], v[48:51]
	v_mfma_f32_16x16x32_bf16 v[52:55], v[222:225], v[148:151], v[52:55]
	v_mfma_f32_16x16x32_bf16 v[56:59], v[214:217], v[156:159], v[56:59]
	v_mfma_f32_16x16x32_bf16 v[60:63], v[222:225], v[156:159], v[60:63]
	s_waitcnt vmcnt(8)
	s_waitcnt lgkmcnt(0)
	s_barrier
	v_mfma_f32_16x16x32_bf16 v[96:99], v[210:213], v[160:163], v[96:99]
	s_add_i32 m0, s35, 0x4000
	v_mfma_f32_16x16x32_bf16 v[100:103], v[218:221], v[160:163], v[100:103]
	global_load_lds_dwordx4 v249, s[56:57]
	v_mfma_f32_16x16x32_bf16 v[104:107], v[210:213], v[168:171], v[104:107]
	s_add_i32 m0, s35, 0x6000
	v_mfma_f32_16x16x32_bf16 v[108:111], v[218:221], v[168:171], v[108:111]
	global_load_lds_dwordx4 v250, s[56:57]
	v_mfma_f32_16x16x32_bf16 v[112:115], v[210:213], v[176:179], v[112:115]
	s_add_i32 m0, s35, 0x14000
	v_mfma_f32_16x16x32_bf16 v[116:119], v[218:221], v[176:179], v[116:119]
	global_load_lds_dwordx4 v251, s[58:59]
	v_mfma_f32_16x16x32_bf16 v[120:123], v[210:213], v[186:189], v[120:123]
	s_add_i32 m0, s35, 0x16000
	v_mfma_f32_16x16x32_bf16 v[124:127], v[218:221], v[186:189], v[124:127]
	global_load_lds_dwordx4 v252, s[58:59]
	v_mfma_f32_16x16x32_bf16 v[96:99], v[214:217], v[164:167], v[96:99]
	ds_read_b128 v[128:131], v245 offset:32768
	v_mfma_f32_16x16x32_bf16 v[100:103], v[222:225], v[164:167], v[100:103]
	ds_read_b128 v[132:135], v246 offset:32768
	v_mfma_f32_16x16x32_bf16 v[104:107], v[214:217], v[172:175], v[104:107]
	ds_read_b128 v[136:139], v245 offset:34816
	v_mfma_f32_16x16x32_bf16 v[108:111], v[222:225], v[172:175], v[108:111]
	ds_read_b128 v[140:143], v246 offset:34816
	v_mfma_f32_16x16x32_bf16 v[112:115], v[214:217], v[180:183], v[112:115]
	ds_read_b128 v[144:147], v245 offset:36864
	v_mfma_f32_16x16x32_bf16 v[116:119], v[222:225], v[180:183], v[116:119]
	ds_read_b128 v[148:151], v246 offset:36864
	v_mfma_f32_16x16x32_bf16 v[120:123], v[214:217], v[190:193], v[120:123]
	ds_read_b128 v[152:155], v245 offset:38912
	v_mfma_f32_16x16x32_bf16 v[124:127], v[222:225], v[190:193], v[124:127]
	ds_read_b128 v[156:159], v246 offset:38912
	v_mfma_f32_16x16x32_bf16 v[64:67], v[194:197], v[160:163], v[64:67]
	ds_read_b128 v[210:213], v247 offset:49152
	v_mfma_f32_16x16x32_bf16 v[68:71], v[202:205], v[160:163], v[68:71]
	ds_read_b128 v[214:217], v248 offset:49152
	v_mfma_f32_16x16x32_bf16 v[72:75], v[194:197], v[168:171], v[72:75]
	ds_read_b128 v[218:221], v247 offset:51200
	v_mfma_f32_16x16x32_bf16 v[76:79], v[202:205], v[168:171], v[76:79]
	ds_read_b128 v[222:225], v248 offset:51200
	v_mfma_f32_16x16x32_bf16 v[80:83], v[194:197], v[176:179], v[80:83]
	s_add_u32 s30, s30, s4
	s_addc_u32 s31, s31, s5
	v_mfma_f32_16x16x32_bf16 v[84:87], v[202:205], v[176:179], v[84:87]
	s_add_u32 s56, s56, s4
	s_addc_u32 s57, s57, s5
	v_mfma_f32_16x16x32_bf16 v[88:91], v[194:197], v[186:189], v[88:91]
	s_add_u32 s32, s32, s4
	s_addc_u32 s33, s33, s5
	v_mfma_f32_16x16x32_bf16 v[92:95], v[202:205], v[186:189], v[92:95]
	s_add_u32 s58, s58, s4
	s_addc_u32 s59, s59, s5
	v_mfma_f32_16x16x32_bf16 v[64:67], v[198:201], v[164:167], v[64:67]
	v_mfma_f32_16x16x32_bf16 v[68:71], v[206:209], v[164:167], v[68:71]
	v_mfma_f32_16x16x32_bf16 v[72:75], v[198:201], v[172:175], v[72:75]
	v_mfma_f32_16x16x32_bf16 v[76:79], v[206:209], v[172:175], v[76:79]
	v_mfma_f32_16x16x32_bf16 v[80:83], v[198:201], v[180:183], v[80:83]
	v_mfma_f32_16x16x32_bf16 v[84:87], v[206:209], v[180:183], v[84:87]
	v_mfma_f32_16x16x32_bf16 v[88:91], v[198:201], v[190:193], v[88:91]
	v_mfma_f32_16x16x32_bf16 v[92:95], v[206:209], v[190:193], v[92:95]
	s_waitcnt vmcnt(8)
	s_waitcnt lgkmcnt(0)
	s_barrier
; #define PG8_STAGE(bufoff, gbase, voff) do { _Pragma("unroll") for (int _i = 0; _i < 2; ++_i) \
;         __builtin_amdgcn_global_load_lds((const unsigned*)((const char*)(gbase) + (voff)[_i]), (PG8_LAS unsigned*)(lds + (bufoff) + ldsw + _i * 8192), 16, 0, 0); } while (0)
; #define PG8_LDA(dst, b, h) do { _Pragma("unroll") for (int m = 0; m < 4; ++m) _Pragma("unroll") for (int k = 0; k < 2; ++k) dst[m][k] = *(const PG8_LAS bf16x8*)(lds + PG8_SA(b, h) + aoff + m * 2048 + k * 1024); } while (0)
; template <class Epi, class Sched, bool ALIGN_EPI = false, bool SP2 = false>
; __device__ __forceinline__ void gemm_phase(PG8_LAS unsigned char* lds, const Gemm g, const Sched& S, const Epi& E) {
;     ...
;         const bool has_next = S.next(ui + 1, nxt);
;         const char* nA = has_next ? (const char*)g.A + (size_t)nxt.pm * tstep : cA; const char* nB = has_next ? (const char*)g.Bt + (size_t)nxt.pn * tstep : cB;
;         for (int t = 0; t < nt; t += 2) {
;             const bool last = (t == nt - 2);
;             const char* a1 = cA + (size_t)(t + 1) * kstep;
;             const char* a2 = last ? nA : cA + (size_t)(t + 2) * kstep; const char* b2 = last ? nB : cB + (size_t)(t + 2) * kstep;
;             const char* a3 = a2 + kstep; const char* b3 = b2 + kstep;
;             if (last && has_next) S.a_ready(nxt);
;             if constexpr (SP2) {
;             PG8_LDB(B0, 0, 0); PG8_LDB(B1, 0, 1); PG8_SCHED; PG8_LDA(At, 0, 0); PG8_STAGE(PG8_SA(1, 1), a1 + hstep, voffA);
;             PG8_WAIT_V(8); PG8_WAIT_L(0); PG8_BAR; PG8_MMA(0, 0, At, B0); PG8_MMA(0, 1, At, B1); PG8_BAR; PG8_SCHED;
;             PG8_LDA(At, 0, 1); PG8_STAGE(PG8_SB(0, 0), b2, voffB); PG8_STAGE(PG8_SB(0, 1), b2 + hstep, voffB); PG8_STAGE(PG8_SA(0, 0), a2, voffA);
;             PG8_WAIT_V(8); PG8_WAIT_L(0); PG8_BAR; PG8_MMA(1, 0, At, B0); PG8_MMA(1, 1, At, B1); PG8_BAR; PG8_SCHED;
;             PG8_LDB(B0, 1, 0); PG8_LDB(B1, 1, 1); PG8_SCHED; PG8_LDA(At, 1, 0); PG8_STAGE(PG8_SA(0, 1), a2 + hstep, voffA);
;             PG8_WAIT_V(8); PG8_WAIT_L(0); PG8_BAR; PG8_MMA(0, 0, At, B0); PG8_MMA(0, 1, At, B1); PG8_BAR; PG8_SCHED;
;             PG8_LDA(At, 1, 1); PG8_STAGE(PG8_SB(1, 0), b3, voffB); PG8_STAGE(PG8_SB(1, 1), b3 + hstep, voffB); PG8_STAGE(PG8_SA(1, 0), a3, voffA);
;             PG8_WAIT_V(8); PG8_WAIT_L(0); PG8_BAR; PG8_MMA(1, 0, At, B0); PG8_MMA(1, 1, At, B1); PG8_BAR; PG8_SCHED;
	v_mfma_f32_16x16x32_bf16 v[32:35], v[210:213], v[128:131], v[32:35]
	ds_read_b128 v[194:197], v247 offset:32768
	v_mfma_f32_16x16x32_bf16 v[36:39], v[218:221], v[128:131], v[36:39]
	ds_read_b128 v[198:201], v248 offset:32768
	v_mfma_f32_16x16x32_bf16 v[40:43], v[210:213], v[136:139], v[40:43]
	ds_read_b128 v[202:205], v247 offset:34816
	v_mfma_f32_16x16x32_bf16 v[44:47], v[218:221], v[136:139], v[44:47]
	ds_read_b128 v[206:209], v248 offset:34816
	v_mfma_f32_16x16x32_bf16 v[48:51], v[210:213], v[144:147], v[48:51]
	s_add_i32 m0, s35, 0x8000
	v_mfma_f32_16x16x32_bf16 v[52:55], v[218:221], v[144:147], v[52:55]
	global_load_lds_dwordx4 v249, s[30:31]
	v_mfma_f32_16x16x32_bf16 v[56:59], v[210:213], v[152:155], v[56:59]
	s_add_i32 m0, s35, 0xa000
	v_mfma_f32_16x16x32_bf16 v[60:63], v[218:221], v[152:155], v[60:63]
	global_load_lds_dwordx4 v250, s[30:31]
	v_mfma_f32_16x16x32_bf16 v[32:35], v[214:217], v[132:135], v[32:35]
	s_add_i32 m0, s35, 0x1c000
	v_mfma_f32_16x16x32_bf16 v[36:39], v[222:225], v[132:135], v[36:39]
	global_load_lds_dwordx4 v251, s[58:59]
	v_mfma_f32_16x16x32_bf16 v[40:43], v[214:217], v[140:143], v[40:43]
	s_add_i32 m0, s35, 0x1e000
	v_mfma_f32_16x16x32_bf16 v[44:47], v[222:225], v[140:143], v[44:47]
	global_load_lds_dwordx4 v252, s[58:59]
	v_mfma_f32_16x16x32_bf16 v[48:51], v[214:217], v[148:151], v[48:51]
	ds_read_b128 v[160:163], v245 offset:49152
	v_mfma_f32_16x16x32_bf16 v[52:55], v[222:225], v[148:151], v[52:55]
	ds_read_b128 v[164:167], v246 offset:49152
	v_mfma_f32_16x16x32_bf16 v[56:59], v[214:217], v[156:159], v[56:59]
	ds_read_b128 v[168:171], v245 offset:51200
	v_mfma_f32_16x16x32_bf16 v[60:63], v[222:225], v[156:159], v[60:63]
	ds_read_b128 v[172:175], v246 offset:51200
	s_waitcnt lgkmcnt(4)
	v_mfma_f32_16x16x32_bf16 v[0:3], v[194:197], v[128:131], v[0:3]
	ds_read_b128 v[176:179], v245 offset:53248
	v_mfma_f32_16x16x32_bf16 v[4:7], v[202:205], v[128:131], v[4:7]
	ds_read_b128 v[180:183], v246 offset:53248
	v_mfma_f32_16x16x32_bf16 v[8:11], v[194:197], v[136:139], v[8:11]
	ds_read_b128 v[186:189], v245 offset:55296
	v_mfma_f32_16x16x32_bf16 v[12:15], v[202:205], v[136:139], v[12:15]
	ds_read_b128 v[190:193], v246 offset:55296
	v_mfma_f32_16x16x32_bf16 v[16:19], v[194:197], v[144:147], v[16:19]
	v_mfma_f32_16x16x32_bf16 v[20:23], v[202:205], v[144:147], v[20:23]
	v_mfma_f32_16x16x32_bf16 v[24:27], v[194:197], v[152:155], v[24:27]
	v_mfma_f32_16x16x32_bf16 v[28:31], v[202:205], v[152:155], v[28:31]
	v_mfma_f32_16x16x32_bf16 v[0:3], v[198:201], v[132:135], v[0:3]
	v_mfma_f32_16x16x32_bf16 v[4:7], v[206:209], v[132:135], v[4:7]
	v_mfma_f32_16x16x32_bf16 v[8:11], v[198:201], v[140:143], v[8:11]
	v_mfma_f32_16x16x32_bf16 v[12:15], v[206:209], v[140:143], v[12:15]
	v_mfma_f32_16x16x32_bf16 v[16:19], v[198:201], v[148:151], v[16:19]
	v_mfma_f32_16x16x32_bf16 v[20:23], v[206:209], v[148:151], v[20:23]
	v_mfma_f32_16x16x32_bf16 v[24:27], v[198:201], v[156:159], v[24:27]
	v_mfma_f32_16x16x32_bf16 v[28:31], v[206:209], v[156:159], v[28:31]
	s_waitcnt vmcnt(8)
	s_waitcnt lgkmcnt(0)
	s_barrier
	v_mfma_f32_16x16x32_bf16 v[64:67], v[194:197], v[160:163], v[64:67]
	s_add_i32 m0, s35, 0xc000
	v_mfma_f32_16x16x32_bf16 v[68:71], v[202:205], v[160:163], v[68:71]
	global_load_lds_dwordx4 v249, s[56:57]
	v_mfma_f32_16x16x32_bf16 v[72:75], v[194:197], v[168:171], v[72:75]
	s_add_i32 m0, s35, 0xe000
	v_mfma_f32_16x16x32_bf16 v[76:79], v[202:205], v[168:171], v[76:79]
	global_load_lds_dwordx4 v250, s[56:57]
	v_mfma_f32_16x16x32_bf16 v[80:83], v[194:197], v[176:179], v[80:83]
	s_add_i32 m0, s35, 0x18000
	v_mfma_f32_16x16x32_bf16 v[84:87], v[202:205], v[176:179], v[84:87]
	global_load_lds_dwordx4 v251, s[32:33]
	v_mfma_f32_16x16x32_bf16 v[88:91], v[194:197], v[186:189], v[88:91]
	s_add_i32 m0, s35, 0x1a000
	v_mfma_f32_16x16x32_bf16 v[92:95], v[202:205], v[186:189], v[92:95]
	global_load_lds_dwordx4 v252, s[32:33]
	v_mfma_f32_16x16x32_bf16 v[64:67], v[198:201], v[164:167], v[64:67]
	ds_read_b128 v[128:131], v245 offset:0
	v_mfma_f32_16x16x32_bf16 v[68:71], v[206:209], v[164:167], v[68:71]
	ds_read_b128 v[132:135], v246 offset:0
	v_mfma_f32_16x16x32_bf16 v[72:75], v[198:201], v[172:175], v[72:75]
	ds_read_b128 v[136:139], v245 offset:2048
	v_mfma_f32_16x16x32_bf16 v[76:79], v[206:209], v[172:175], v[76:79]
	ds_read_b128 v[140:143], v246 offset:2048
	v_mfma_f32_16x16x32_bf16 v[80:83], v[198:201], v[180:183], v[80:83]
	ds_read_b128 v[144:147], v245 offset:4096
	v_mfma_f32_16x16x32_bf16 v[84:87], v[206:209], v[180:183], v[84:87]
	ds_read_b128 v[148:151], v246 offset:4096
	v_mfma_f32_16x16x32_bf16 v[88:91], v[198:201], v[190:193], v[88:91]
	ds_read_b128 v[152:155], v245 offset:6144
	v_mfma_f32_16x16x32_bf16 v[92:95], v[206:209], v[190:193], v[92:95]
	ds_read_b128 v[156:159], v246 offset:6144
	v_mfma_f32_16x16x32_bf16 v[96:99], v[210:213], v[160:163], v[96:99]
	ds_read_b128 v[194:197], v247 offset:0
	v_mfma_f32_16x16x32_bf16 v[100:103], v[218:221], v[160:163], v[100:103]
	ds_read_b128 v[198:201], v248 offset:0
	v_mfma_f32_16x16x32_bf16 v[104:107], v[210:213], v[168:171], v[104:107]
	ds_read_b128 v[202:205], v247 offset:2048
	v_mfma_f32_16x16x32_bf16 v[108:111], v[218:221], v[168:171], v[108:111]
	ds_read_b128 v[206:209], v248 offset:2048
	v_mfma_f32_16x16x32_bf16 v[112:115], v[210:213], v[176:179], v[112:115]
	s_add_u32 s30, s30, s4
	s_addc_u32 s31, s31, s5
	v_mfma_f32_16x16x32_bf16 v[116:119], v[218:221], v[176:179], v[116:119]
	s_add_u32 s56, s56, s4
	s_addc_u32 s57, s57, s5
	v_mfma_f32_16x16x32_bf16 v[120:123], v[210:213], v[186:189], v[120:123]
	s_add_u32 s32, s32, s4
	s_addc_u32 s33, s33, s5
	v_mfma_f32_16x16x32_bf16 v[124:127], v[218:221], v[186:189], v[124:127]
	s_add_u32 s58, s58, s4
	s_addc_u32 s59, s59, s5
	v_mfma_f32_16x16x32_bf16 v[96:99], v[214:217], v[164:167], v[96:99]
	v_mfma_f32_16x16x32_bf16 v[100:103], v[222:225], v[164:167], v[100:103]
	v_mfma_f32_16x16x32_bf16 v[104:107], v[214:217], v[172:175], v[104:107]
	v_mfma_f32_16x16x32_bf16 v[108:111], v[222:225], v[172:175], v[108:111]
	v_mfma_f32_16x16x32_bf16 v[112:115], v[214:217], v[180:183], v[112:115]
	v_mfma_f32_16x16x32_bf16 v[116:119], v[222:225], v[180:183], v[116:119]
	v_mfma_f32_16x16x32_bf16 v[120:123], v[214:217], v[190:193], v[120:123]
	v_mfma_f32_16x16x32_bf16 v[124:127], v[222:225], v[190:193], v[124:127]
	s_add_i32 s34, s34, -1
	s_cmp_lg_u32 s34, 1
	s_cbranch_scc1 .Lp6_nosw0
	s_add_u32 s45, s16, 1
	s_and_b32 s40, s45, 1
	s_lshl_b32 s4, s40, 8
	s_sub_u32 s4, 128, s4
	s_sub_u32 s5, 0, s40
	s_mul_i32 s8, s40, 11136
	s_add_u32 s30, s26, s8
	s_addc_u32 s31, s27, 0
	s_add_u32 s32, s28, s8
	s_addc_u32 s33, s29, 0
	s_add_u32 s56, s30, 0x160000
	s_addc_u32 s57, s31, 0
	s_add_u32 s58, s32, 0x160000
	s_addc_u32 s59, s33, 0

; #define PG8_STAGE(bufoff, gbase, voff) do { _Pragma("unroll") for (int _i = 0; _i < 2; ++_i) \
;         __builtin_amdgcn_global_load_lds((const unsigned*)((const char*)(gbase) + (voff)[_i]), (PG8_LAS unsigned*)(lds + (bufoff) + ldsw + _i * 8192), 16, 0, 0); } while (0)
; #define PG8_LDA(dst, b, h) do { _Pragma("unroll") for (int m = 0; m < 4; ++m) _Pragma("unroll") for (int k = 0; k < 2; ++k) dst[m][k] = *(const PG8_LAS bf16x8*)(lds + PG8_SA(b, h) + aoff + m * 2048 + k * 1024); } while (0)
; #define PG8_LDB(dst, b, h) do { _Pragma("unroll") for (int n = 0; n < 2; ++n) _Pragma("unroll") for (int k = 0; k < 2; ++k) dst[n][k] = *(const PG8_LAS bf16x8*)(lds + PG8_SB(b, h) + boff + n * 2048 + k * 1024); } while (0)
; template <class Epi, class Sched, bool ALIGN_EPI = false, bool SP2 = false>
; __device__ __forceinline__ void gemm_phase(PG8_LAS unsigned char* lds, const Gemm g, const Sched& S, const Epi& E) {
;     ...
;         for (int t = 0; t < nt; t += 2) {
;             const bool last = (t == nt - 2);
;             const char* a1 = cA + (size_t)(t + 1) * kstep;
;             const char* a2 = last ? nA : cA + (size_t)(t + 2) * kstep; const char* b2 = last ? nB : cB + (size_t)(t + 2) * kstep;
;             const char* a3 = a2 + kstep; const char* b3 = b2 + kstep;
;             if (last && has_next) S.a_ready(nxt);
;             if constexpr (SP2) {
;             PG8_LDB(B0, 0, 0); PG8_LDB(B1, 0, 1); PG8_SCHED; PG8_LDA(At, 0, 0); PG8_STAGE(PG8_SA(1, 1), a1 + hstep, voffA);
;             PG8_WAIT_V(8); PG8_WAIT_L(0); PG8_BAR; PG8_MMA(0, 0, At, B0); PG8_MMA(0, 1, At, B1); PG8_BAR; PG8_SCHED;
;             PG8_LDA(At, 0, 1); PG8_STAGE(PG8_SB(0, 0), b2, voffB); PG8_STAGE(PG8_SB(0, 1), b2 + hstep, voffB); PG8_STAGE(PG8_SA(0, 0), a2, voffA);
;             PG8_WAIT_V(8); PG8_WAIT_L(0); PG8_BAR; PG8_MMA(1, 0, At, B0); PG8_MMA(1, 1, At, B1); PG8_BAR; PG8_SCHED;
;             PG8_LDB(B0, 1, 0); PG8_LDB(B1, 1, 1); PG8_SCHED; PG8_LDA(At, 1, 0); PG8_STAGE(PG8_SA(0, 1), a2 + hstep, voffA);
;             PG8_WAIT_V(8); PG8_WAIT_L(0); PG8_BAR; PG8_MMA(0, 0, At, B0); PG8_MMA(0, 1, At, B1); PG8_BAR; PG8_SCHED;
;             PG8_LDA(At, 1, 1); PG8_STAGE(PG8_SB(1, 0), b3, voffB); PG8_STAGE(PG8_SB(1, 1), b3 + hstep, voffB); PG8_STAGE(PG8_SA(1, 0), a3, voffA);
;             PG8_WAIT_V(8); PG8_WAIT_L(0); PG8_BAR; PG8_MMA(1, 0, At, B0); PG8_MMA(1, 1, At, B1); PG8_BAR; PG8_SCHED;
.Lp6_kloop1:
	s_waitcnt vmcnt(8)
	s_waitcnt lgkmcnt(0)
	s_barrier
	v_mfma_f32_16x16x32_bf16 v[0:3], v[194:197], v[128:131], v[0:3]
	ds_read_b128 v[210:213], v247 offset:16384
	v_mfma_f32_16x16x32_bf16 v[4:7], v[202:205], v[128:131], v[4:7]
	ds_read_b128 v[214:217], v248 offset:16384
	v_mfma_f32_16x16x32_bf16 v[8:11], v[194:197], v[136:139], v[8:11]
	ds_read_b128 v[218:221], v247 offset:18432
	v_mfma_f32_16x16x32_bf16 v[12:15], v[202:205], v[136:139], v[12:15]
	ds_read_b128 v[222:225], v248 offset:18432
	v_mfma_f32_16x16x32_bf16 v[16:19], v[194:197], v[144:147], v[16:19]
	ds_read_b128 v[160:163], v245 offset:16384
	v_mfma_f32_16x16x32_bf16 v[20:23], v[202:205], v[144:147], v[20:23]
	ds_read_b128 v[164:167], v246 offset:16384
	v_mfma_f32_16x16x32_bf16 v[24:27], v[194:197], v[152:155], v[24:27]
	ds_read_b128 v[168:171], v245 offset:18432
	v_mfma_f32_16x16x32_bf16 v[28:31], v[202:205], v[152:155], v[28:31]
	ds_read_b128 v[172:175], v246 offset:18432
	v_mfma_f32_16x16x32_bf16 v[0:3], v[198:201], v[132:135], v[0:3]
	ds_read_b128 v[176:179], v245 offset:20480
	v_mfma_f32_16x16x32_bf16 v[4:7], v[206:209], v[132:135], v[4:7]
	ds_read_b128 v[180:183], v246 offset:20480
	v_mfma_f32_16x16x32_bf16 v[8:11], v[198:201], v[140:143], v[8:11]
	ds_read_b128 v[186:189], v245 offset:22528
	v_mfma_f32_16x16x32_bf16 v[12:15], v[206:209], v[140:143], v[12:15]
	ds_read_b128 v[190:193], v246 offset:22528
	v_mfma_f32_16x16x32_bf16 v[16:19], v[198:201], v[148:151], v[16:19]
	v_mfma_f32_16x16x32_bf16 v[20:23], v[206:209], v[148:151], v[20:23]
	v_mfma_f32_16x16x32_bf16 v[24:27], v[198:201], v[156:159], v[24:27]
	v_mfma_f32_16x16x32_bf16 v[28:31], v[206:209], v[156:159], v[28:31]
	s_waitcnt lgkmcnt(8)
	v_mfma_f32_16x16x32_bf16 v[32:35], v[210:213], v[128:131], v[32:35]
	v_mfma_f32_16x16x32_bf16 v[36:39], v[218:221], v[128:131], v[36:39]
	s_add_i32 m0, s35, 0x0
	v_mfma_f32_16x16x32_bf16 v[40:43], v[210:213], v[136:139], v[40:43]
	global_load_lds_dwordx4 v249, s[30:31]
	v_mfma_f32_16x16x32_bf16 v[44:47], v[218:221], v[136:139], v[44:47]
	v_mfma_f32_16x16x32_bf16 v[48:51], v[210:213], v[144:147], v[48:51]
	s_add_i32 m0, s35, 0x2000
	v_mfma_f32_16x16x32_bf16 v[52:55], v[218:221], v[144:147], v[52:55]
	global_load_lds_dwordx4 v250, s[30:31]
	v_mfma_f32_16x16x32_bf16 v[56:59], v[210:213], v[152:155], v[56:59]
	v_mfma_f32_16x16x32_bf16 v[60:63], v[218:221], v[152:155], v[60:63]
	s_add_i32 m0, s35, 0x10000
	v_mfma_f32_16x16x32_bf16 v[32:35], v[214:217], v[132:135], v[32:35]
	global_load_lds_dwordx4 v251, s[32:33]
	v_mfma_f32_16x16x32_bf16 v[36:39], v[222:225], v[132:135], v[36:39]
	v_mfma_f32_16x16x32_bf16 v[40:43], v[214:217], v[140:143], v[40:43]
	s_add_i32 m0, s35, 0x12000
	v_mfma_f32_16x16x32_bf16 v[44:47], v[222:225], v[140:143], v[44:47]
	global_load_lds_dwordx4 v252, s[32:33]
	v_mfma_f32_16x16x32_bf16 v[48:51], v[214:217], v[148:151], v[48:51]
	v_mfma_f32_16x16x32_bf16 v[52:55], v[222:225], v[148:151], v[52:55]
	v_mfma_f32_16x16x32_bf16 v[56:59], v[214:217], v[156:159], v[56:59]
	v_mfma_f32_16x16x32_bf16 v[60:63], v[222:225], v[156:159], v[60:63]
	s_waitcnt vmcnt(8)
	s_waitcnt lgkmcnt(0)
	s_barrier
	v_mfma_f32_16x16x32_bf16 v[96:99], v[210:213], v[160:163], v[96:99]
	ds_read_b128 v[128:131], v245 offset:32768
	v_mfma_f32_16x16x32_bf16 v[100:103], v[218:221], v[160:163], v[100:103]
	ds_read_b128 v[132:135], v246 offset:32768
	v_mfma_f32_16x16x32_bf16 v[104:107], v[210:213], v[168:171], v[104:107]
	ds_read_b128 v[136:139], v245 offset:34816
	v_mfma_f32_16x16x32_bf16 v[108:111], v[218:221], v[168:171], v[108:111]
	ds_read_b128 v[140:143], v246 offset:34816
	v_mfma_f32_16x16x32_bf16 v[112:115], v[210:213], v[176:179], v[112:115]
	ds_read_b128 v[144:147], v245 offset:36864
	v_mfma_f32_16x16x32_bf16 v[116:119], v[218:221], v[176:179], v[116:119]
	ds_read_b128 v[148:151], v246 offset:36864
	v_mfma_f32_16x16x32_bf16 v[120:123], v[210:213], v[186:189], v[120:123]
	ds_read_b128 v[152:155], v245 offset:38912
	v_mfma_f32_16x16x32_bf16 v[124:127], v[218:221], v[186:189], v[124:127]
	ds_read_b128 v[156:159], v246 offset:38912
	v_mfma_f32_16x16x32_bf16 v[96:99], v[214:217], v[164:167], v[96:99]
	v_mfma_f32_16x16x32_bf16 v[100:103], v[222:225], v[164:167], v[100:103]
	v_mfma_f32_16x16x32_bf16 v[104:107], v[214:217], v[172:175], v[104:107]
	v_mfma_f32_16x16x32_bf16 v[108:111], v[222:225], v[172:175], v[108:111]
	v_mfma_f32_16x16x32_bf16 v[112:115], v[214:217], v[180:183], v[112:115]
	v_mfma_f32_16x16x32_bf16 v[116:119], v[222:225], v[180:183], v[116:119]
	v_mfma_f32_16x16x32_bf16 v[120:123], v[214:217], v[190:193], v[120:123]
	v_mfma_f32_16x16x32_bf16 v[124:127], v[222:225], v[190:193], v[124:127]
	v_mfma_f32_16x16x32_bf16 v[64:67], v[194:197], v[160:163], v[64:67]
	ds_read_b128 v[210:213], v247 offset:49152
	v_mfma_f32_16x16x32_bf16 v[68:71], v[202:205], v[160:163], v[68:71]
	ds_read_b128 v[214:217], v248 offset:49152
	v_mfma_f32_16x16x32_bf16 v[72:75], v[194:197], v[168:171], v[72:75]
	ds_read_b128 v[218:221], v247 offset:51200
	v_mfma_f32_16x16x32_bf16 v[76:79], v[202:205], v[168:171], v[76:79]
	ds_read_b128 v[222:225], v248 offset:51200
	v_mfma_f32_16x16x32_bf16 v[80:83], v[194:197], v[176:179], v[80:83]
	s_add_i32 m0, s35, 0x4000
	v_mfma_f32_16x16x32_bf16 v[84:87], v[202:205], v[176:179], v[84:87]
	global_load_lds_dwordx4 v249, s[56:57]
	v_mfma_f32_16x16x32_bf16 v[88:91], v[194:197], v[186:189], v[88:91]
	s_add_i32 m0, s35, 0x6000
	v_mfma_f32_16x16x32_bf16 v[92:95], v[202:205], v[186:189], v[92:95]
	global_load_lds_dwordx4 v250, s[56:57]
	v_mfma_f32_16x16x32_bf16 v[64:67], v[198:201], v[164:167], v[64:67]
	s_add_i32 m0, s35, 0x14000
	v_mfma_f32_16x16x32_bf16 v[68:71], v[206:209], v[164:167], v[68:71]
	global_load_lds_dwordx4 v251, s[58:59]
	v_mfma_f32_16x16x32_bf16 v[72:75], v[198:201], v[172:175], v[72:75]
	s_add_i32 m0, s35, 0x16000
	v_mfma_f32_16x16x32_bf16 v[76:79], v[206:209], v[172:175], v[76:79]
	global_load_lds_dwordx4 v252, s[58:59]
	v_mfma_f32_16x16x32_bf16 v[80:83], v[198:201], v[180:183], v[80:83]
	s_add_u32 s30, s30, s4
	s_addc_u32 s31, s31, s5
	v_mfma_f32_16x16x32_bf16 v[84:87], v[206:209], v[180:183], v[84:87]
	s_add_u32 s56, s56, s4
	s_addc_u32 s57, s57, s5
	v_mfma_f32_16x16x32_bf16 v[88:91], v[198:201], v[190:193], v[88:91]
	s_add_u32 s32, s32, s4
	s_addc_u32 s33, s33, s5
	v_mfma_f32_16x16x32_bf16 v[92:95], v[206:209], v[190:193], v[92:95]
	s_add_u32 s58, s58, s4
	s_addc_u32 s59, s59, s5
	s_waitcnt vmcnt(8)
	s_waitcnt lgkmcnt(0)
	s_barrier
; #define PG8_STAGE(bufoff, gbase, voff) do { _Pragma("unroll") for (int _i = 0; _i < 2; ++_i) \
;         __builtin_amdgcn_global_load_lds((const unsigned*)((const char*)(gbase) + (voff)[_i]), (PG8_LAS unsigned*)(lds + (bufoff) + ldsw + _i * 8192), 16, 0, 0); } while (0)
; #define PG8_LDA(dst, b, h) do { _Pragma("unroll") for (int m = 0; m < 4; ++m) _Pragma("unroll") for (int k = 0; k < 2; ++k) dst[m][k] = *(const PG8_LAS bf16x8*)(lds + PG8_SA(b, h) + aoff + m * 2048 + k * 1024); } while (0)
; template <class Epi, class Sched, bool ALIGN_EPI = false, bool SP2 = false>
; __device__ __forceinline__ void gemm_phase(PG8_LAS unsigned char* lds, const Gemm g, const Sched& S, const Epi& E) {
;     ...
;         const bool has_next = S.next(ui + 1, nxt);
;         const char* nA = has_next ? (const char*)g.A + (size_t)nxt.pm * tstep : cA; const char* nB = has_next ? (const char*)g.Bt + (size_t)nxt.pn * tstep : cB;
;         for (int t = 0; t < nt; t += 2) {
;             const bool last = (t == nt - 2);
;             const char* a1 = cA + (size_t)(t + 1) * kstep;
;             const char* a2 = last ? nA : cA + (size_t)(t + 2) * kstep; const char* b2 = last ? nB : cB + (size_t)(t + 2) * kstep;
;             const char* a3 = a2 + kstep; const char* b3 = b2 + kstep;
;             if (last && has_next) S.a_ready(nxt);
;             if constexpr (SP2) {
;             PG8_LDB(B0, 0, 0); PG8_LDB(B1, 0, 1); PG8_SCHED; PG8_LDA(At, 0, 0); PG8_STAGE(PG8_SA(1, 1), a1 + hstep, voffA);
;             PG8_WAIT_V(8); PG8_WAIT_L(0); PG8_BAR; PG8_MMA(0, 0, At, B0); PG8_MMA(0, 1, At, B1); PG8_BAR; PG8_SCHED;
;             PG8_LDA(At, 0, 1); PG8_STAGE(PG8_SB(0, 0), b2, voffB); PG8_STAGE(PG8_SB(0, 1), b2 + hstep, voffB); PG8_STAGE(PG8_SA(0, 0), a2, voffA);
;             PG8_WAIT_V(8); PG8_WAIT_L(0); PG8_BAR; PG8_MMA(1, 0, At, B0); PG8_MMA(1, 1, At, B1); PG8_BAR; PG8_SCHED;
;             PG8_LDB(B0, 1, 0); PG8_LDB(B1, 1, 1); PG8_SCHED; PG8_LDA(At, 1, 0); PG8_STAGE(PG8_SA(0, 1), a2 + hstep, voffA);
;             PG8_WAIT_V(8); PG8_WAIT_L(0); PG8_BAR; PG8_MMA(0, 0, At, B0); PG8_MMA(0, 1, At, B1); PG8_BAR; PG8_SCHED;
;             PG8_LDA(At, 1, 1); PG8_STAGE(PG8_SB(1, 0), b3, voffB); PG8_STAGE(PG8_SB(1, 1), b3 + hstep, voffB); PG8_STAGE(PG8_SA(1, 0), a3, voffA);
;             PG8_WAIT_V(8); PG8_WAIT_L(0); PG8_BAR; PG8_MMA(1, 0, At, B0); PG8_MMA(1, 1, At, B1); PG8_BAR; PG8_SCHED;
	v_mfma_f32_16x16x32_bf16 v[32:35], v[210:213], v[128:131], v[32:35]
	ds_read_b128 v[194:197], v247 offset:32768
	v_mfma_f32_16x16x32_bf16 v[36:39], v[218:221], v[128:131], v[36:39]
	ds_read_b128 v[198:201], v248 offset:32768
	v_mfma_f32_16x16x32_bf16 v[40:43], v[210:213], v[136:139], v[40:43]
	ds_read_b128 v[202:205], v247 offset:34816
	v_mfma_f32_16x16x32_bf16 v[44:47], v[218:221], v[136:139], v[44:47]
	ds_read_b128 v[206:209], v248 offset:34816
	v_mfma_f32_16x16x32_bf16 v[48:51], v[210:213], v[144:147], v[48:51]
	ds_read_b128 v[160:163], v245 offset:49152
	v_mfma_f32_16x16x32_bf16 v[52:55], v[218:221], v[144:147], v[52:55]
	ds_read_b128 v[164:167], v246 offset:49152
	v_mfma_f32_16x16x32_bf16 v[56:59], v[210:213], v[152:155], v[56:59]
	ds_read_b128 v[168:171], v245 offset:51200
	v_mfma_f32_16x16x32_bf16 v[60:63], v[218:221], v[152:155], v[60:63]
	ds_read_b128 v[172:175], v246 offset:51200
	v_mfma_f32_16x16x32_bf16 v[32:35], v[214:217], v[132:135], v[32:35]
	ds_read_b128 v[176:179], v245 offset:53248
	v_mfma_f32_16x16x32_bf16 v[36:39], v[222:225], v[132:135], v[36:39]
	ds_read_b128 v[180:183], v246 offset:53248
	v_mfma_f32_16x16x32_bf16 v[40:43], v[214:217], v[140:143], v[40:43]
	ds_read_b128 v[186:189], v245 offset:55296
	v_mfma_f32_16x16x32_bf16 v[44:47], v[222:225], v[140:143], v[44:47]
	ds_read_b128 v[190:193], v246 offset:55296
	v_mfma_f32_16x16x32_bf16 v[48:51], v[214:217], v[148:151], v[48:51]
	v_mfma_f32_16x16x32_bf16 v[52:55], v[222:225], v[148:151], v[52:55]
	v_mfma_f32_16x16x32_bf16 v[56:59], v[214:217], v[156:159], v[56:59]
	v_mfma_f32_16x16x32_bf16 v[60:63], v[222:225], v[156:159], v[60:63]
	s_waitcnt lgkmcnt(8)
	v_mfma_f32_16x16x32_bf16 v[0:3], v[194:197], v[128:131], v[0:3]
	v_mfma_f32_16x16x32_bf16 v[4:7], v[202:205], v[128:131], v[4:7]
	s_add_i32 m0, s35, 0x8000
	v_mfma_f32_16x16x32_bf16 v[8:11], v[194:197], v[136:139], v[8:11]
	global_load_lds_dwordx4 v249, s[30:31]
	v_mfma_f32_16x16x32_bf16 v[12:15], v[202:205], v[136:139], v[12:15]
	v_mfma_f32_16x16x32_bf16 v[16:19], v[194:197], v[144:147], v[16:19]
	s_add_i32 m0, s35, 0xa000
	v_mfma_f32_16x16x32_bf16 v[20:23], v[202:205], v[144:147], v[20:23]
	global_load_lds_dwordx4 v250, s[30:31]
	v_mfma_f32_16x16x32_bf16 v[24:27], v[194:197], v[152:155], v[24:27]
	v_mfma_f32_16x16x32_bf16 v[28:31], v[202:205], v[152:155], v[28:31]
	s_add_i32 m0, s35, 0x1c000
	v_mfma_f32_16x16x32_bf16 v[0:3], v[198:201], v[132:135], v[0:3]
	global_load_lds_dwordx4 v251, s[58:59]
	v_mfma_f32_16x16x32_bf16 v[4:7], v[206:209], v[132:135], v[4:7]
	v_mfma_f32_16x16x32_bf16 v[8:11], v[198:201], v[140:143], v[8:11]
	s_add_i32 m0, s35, 0x1e000
	v_mfma_f32_16x16x32_bf16 v[12:15], v[206:209], v[140:143], v[12:15]
	global_load_lds_dwordx4 v252, s[58:59]
	v_mfma_f32_16x16x32_bf16 v[16:19], v[198:201], v[148:151], v[16:19]
	v_mfma_f32_16x16x32_bf16 v[20:23], v[206:209], v[148:151], v[20:23]
	v_mfma_f32_16x16x32_bf16 v[24:27], v[198:201], v[156:159], v[24:27]
	v_mfma_f32_16x16x32_bf16 v[28:31], v[206:209], v[156:159], v[28:31]
	s_waitcnt vmcnt(8)
	s_waitcnt lgkmcnt(0)
	s_barrier
	v_mfma_f32_16x16x32_bf16 v[64:67], v[194:197], v[160:163], v[64:67]
	ds_read_b128 v[128:131], v245 offset:0
	v_mfma_f32_16x16x32_bf16 v[68:71], v[202:205], v[160:163], v[68:71]
	ds_read_b128 v[132:135], v246 offset:0
	v_mfma_f32_16x16x32_bf16 v[72:75], v[194:197], v[168:171], v[72:75]
	ds_read_b128 v[136:139], v245 offset:2048
	v_mfma_f32_16x16x32_bf16 v[76:79], v[202:205], v[168:171], v[76:79]
	ds_read_b128 v[140:143], v246 offset:2048
	v_mfma_f32_16x16x32_bf16 v[80:83], v[194:197], v[176:179], v[80:83]
	ds_read_b128 v[144:147], v245 offset:4096
	v_mfma_f32_16x16x32_bf16 v[84:87], v[202:205], v[176:179], v[84:87]
	ds_read_b128 v[148:151], v246 offset:4096
	v_mfma_f32_16x16x32_bf16 v[88:91], v[194:197], v[186:189], v[88:91]
	ds_read_b128 v[152:155], v245 offset:6144
	v_mfma_f32_16x16x32_bf16 v[92:95], v[202:205], v[186:189], v[92:95]
	ds_read_b128 v[156:159], v246 offset:6144
	v_mfma_f32_16x16x32_bf16 v[64:67], v[198:201], v[164:167], v[64:67]
	v_mfma_f32_16x16x32_bf16 v[68:71], v[206:209], v[164:167], v[68:71]
	v_mfma_f32_16x16x32_bf16 v[72:75], v[198:201], v[172:175], v[72:75]
	v_mfma_f32_16x16x32_bf16 v[76:79], v[206:209], v[172:175], v[76:79]
	v_mfma_f32_16x16x32_bf16 v[80:83], v[198:201], v[180:183], v[80:83]
	v_mfma_f32_16x16x32_bf16 v[84:87], v[206:209], v[180:183], v[84:87]
	v_mfma_f32_16x16x32_bf16 v[88:91], v[198:201], v[190:193], v[88:91]
	v_mfma_f32_16x16x32_bf16 v[92:95], v[206:209], v[190:193], v[92:95]
	v_mfma_f32_16x16x32_bf16 v[96:99], v[210:213], v[160:163], v[96:99]
	ds_read_b128 v[194:197], v247 offset:0
	v_mfma_f32_16x16x32_bf16 v[100:103], v[218:221], v[160:163], v[100:103]
	ds_read_b128 v[198:201], v248 offset:0
	v_mfma_f32_16x16x32_bf16 v[104:107], v[210:213], v[168:171], v[104:107]
	ds_read_b128 v[202:205], v247 offset:2048
	v_mfma_f32_16x16x32_bf16 v[108:111], v[218:221], v[168:171], v[108:111]
	ds_read_b128 v[206:209], v248 offset:2048
	v_mfma_f32_16x16x32_bf16 v[112:115], v[210:213], v[176:179], v[112:115]
	s_add_i32 m0, s35, 0xc000
	v_mfma_f32_16x16x32_bf16 v[116:119], v[218:221], v[176:179], v[116:119]
	global_load_lds_dwordx4 v249, s[56:57]
	v_mfma_f32_16x16x32_bf16 v[120:123], v[210:213], v[186:189], v[120:123]
	s_add_i32 m0, s35, 0xe000
	v_mfma_f32_16x16x32_bf16 v[124:127], v[218:221], v[186:189], v[124:127]
	global_load_lds_dwordx4 v250, s[56:57]
	v_mfma_f32_16x16x32_bf16 v[96:99], v[214:217], v[164:167], v[96:99]
	s_add_i32 m0, s35, 0x18000
	v_mfma_f32_16x16x32_bf16 v[100:103], v[222:225], v[164:167], v[100:103]
	global_load_lds_dwordx4 v251, s[32:33]
	v_mfma_f32_16x16x32_bf16 v[104:107], v[214:217], v[172:175], v[104:107]
	s_add_i32 m0, s35, 0x1a000
	v_mfma_f32_16x16x32_bf16 v[108:111], v[222:225], v[172:175], v[108:111]
	global_load_lds_dwordx4 v252, s[32:33]
	v_mfma_f32_16x16x32_bf16 v[112:115], v[214:217], v[180:183], v[112:115]
	s_add_u32 s30, s30, s4
	s_addc_u32 s31, s31, s5
	v_mfma_f32_16x16x32_bf16 v[116:119], v[222:225], v[180:183], v[116:119]
	s_add_u32 s56, s56, s4
	s_addc_u32 s57, s57, s5
	v_mfma_f32_16x16x32_bf16 v[120:123], v[214:217], v[190:193], v[120:123]
	s_add_u32 s32, s32, s4
	s_addc_u32 s33, s33, s5
	v_mfma_f32_16x16x32_bf16 v[124:127], v[222:225], v[190:193], v[124:127]
	s_add_u32 s58, s58, s4
	s_addc_u32 s59, s59, s5
	s_add_i32 s34, s34, -1
	s_cmp_lg_u32 s34, 1
	s_cbranch_scc1 .Lp6_nosw1
	s_add_u32 s45, s16, 1
	s_and_b32 s40, s45, 1
	s_lshl_b32 s4, s40, 8
	s_sub_u32 s4, 128, s4
	s_sub_u32 s5, 0, s40
	s_mul_i32 s8, s40, 11136
	s_add_u32 s30, s26, s8
	s_addc_u32 s31, s27, 0
	s_add_u32 s32, s28, s8
	s_addc_u32 s33, s29, 0
	s_add_u32 s56, s30, 0x160000
	s_addc_u32 s57, s31, 0
	s_add_u32 s58, s32, 0x160000
	s_addc_u32 s59, s33, 0

;     __device__ __forceinline__ void tail(const f32x4& b0, const f32x4& b1, const f32x4& a0, const f32x4& a1, bf16_t* dst, float& s) const {
;         const f32x4 o0 = b0 + a0, o1 = b1 + a1;
;         s += ((o0[0] * o0[0] + o0[1] * o0[1]) + (o0[2] * o0[2] + o0[3] * o0[3])) + ((o1[0] * o1[0] + o1[1] * o1[1]) + (o1[2] * o1[2] + o1[3] * o1[3]));
;     __device__ __forceinline__ void operator()(const f32x4 (&acc)[2][2][4][2], const Unit& u, int wr, int wc, int fr, int fq) const {
;         const int col0 = u.pn * BM + wc * 32 + 8 * fq;
;         if constexpr (BASE_BF16) {
;             u32x4 raw[2][4][2];
; #pragma unroll
;             for (int ai = 0; ai < 2; ++ai)
; #pragma unroll
;                 for (int m = 0; m < 4; ++m) { const int row = u.pm * BM + ai * HALF + wr * 64 + m * 16 + fr; const size_t off = (size_t)row * ldc + col0;
; #pragma unroll
;                     for (int bj = 0; bj < 2; ++bj) raw[ai][m][bj] = *(const u32x4*)((const bf16_t*)base + off + bj * HALF); }
;             asm volatile("" ::: "memory");
; #pragma unroll
;             for (int ai = 0; ai < 2; ++ai)
; #pragma unroll
;                 for (int m = 0; m < 4; ++m) { const int row = u.pm * BM + ai * HALF + wr * 64 + m * 16 + fr; const size_t off = (size_t)row * ldc + col0; float s = 0.f;
; #pragma unroll
;                     for (int bj = 0; bj < 2; ++bj) { const u32x4 r = raw[ai][m][bj];
;                         const f32x4 b0 = {__uint_as_float(r.x << 16), __uint_as_float(r.x & 0xffff0000u), __uint_as_float(r.y << 16), __uint_as_float(r.y & 0xffff0000u)};
;                         const f32x4 b1 = {__uint_as_float(r.z << 16), __uint_as_float(r.z & 0xffff0000u), __uint_as_float(r.w << 16), __uint_as_float(r.w & 0xffff0000u)};
;                         tail(b0, b1, acc[ai][bj][m][0], acc[ai][bj][m][1], out + off + bj * HALF, s); }
.Lp6_kdone:
	s_waitcnt lgkmcnt(0)
	s_nop 7
	s_nop 7
	v_and_b32_e32 v254, 63, v185
	v_and_b32_e32 v255, 15, v254
	v_lshrrev_b32_e32 v234, 4, v254
	s_lshl_b32 s40, s37, 6
	v_add_u32_e32 v255, s40, v255
	v_lshlrev_b32_e32 v230, 2, v255
	v_lshlrev_b32_e32 v228, 12, v255
	v_lshlrev_b32_e32 v229, 13, v255
	s_lshl_b32 s41, s38, 6
	v_lshl_add_u32 v228, v234, 4, v228
	v_add_u32_e32 v228, s41, v228
	s_lshl_b32 s41, s38, 7
	v_lshl_add_u32 v229, v234, 5, v229
	v_add_u32_e32 v229, s41, v229
	v_mov_b32_e32 v231, 0x358637bd
	v_xor_b32_e32 v232, 16, v254
	v_lshlrev_b32_e32 v232, 2, v232
	v_xor_b32_e32 v233, 32, v254
	v_lshlrev_b32_e32 v233, 2, v233
	s_lshl_b32 s40, s17, 20
	s_lshl_b32 s41, s18, 9
	s_add_u32 s40, s40, s41
	s_add_u32 s48, s76, 0x6800000
	s_addc_u32 s49, s77, 0
	s_add_u32 s48, s48, s40
	s_addc_u32 s49, s49, 0
	s_lshl_b32 s40, s17, 10
	s_add_u32 s40, s40, 0x10000
	s_add_u32 s50, s76, s40
	s_addc_u32 s51, s77, 0
	v_readlane_b32 s52, v244, 2
	v_readlane_b32 s53, v244, 3
	s_lshl_b32 s40, s17, 21
	s_lshl_b32 s41, s18, 10
	s_add_u32 s40, s40, s41
	s_add_u32 s52, s52, s40
	s_addc_u32 s53, s53, 0
	s_lshl_b32 s40, s17, 6
	s_add_u32 s40, s40, 0x28000
	s_add_u32 s54, s76, s40
	s_addc_u32 s55, s77, 0
	v_add_u32_e32 v234, 0x0, v228
	global_load_dwordx4 v[128:131], v234, s[48:49] offset:0
	global_load_dwordx4 v[132:135], v234, s[48:49] offset:256
	v_add_u32_e32 v234, 0x10000, v228
	global_load_dwordx4 v[136:139], v234, s[48:49] offset:0
	global_load_dwordx4 v[140:143], v234, s[48:49] offset:256
	v_add_u32_e32 v234, 0x20000, v228
	global_load_dwordx4 v[144:147], v234, s[48:49] offset:0
	global_load_dwordx4 v[148:151], v234, s[48:49] offset:256
	v_add_u32_e32 v234, 0x30000, v228
	global_load_dwordx4 v[152:155], v234, s[48:49] offset:0
	global_load_dwordx4 v[156:159], v234, s[48:49] offset:256
	v_add_u32_e32 v234, 0x80000, v228
	global_load_dwordx4 v[160:163], v234, s[48:49] offset:0
	global_load_dwordx4 v[164:167], v234, s[48:49] offset:256
	v_add_u32_e32 v234, 0x90000, v228
	global_load_dwordx4 v[168:171], v234, s[48:49] offset:0
	global_load_dwordx4 v[172:175], v234, s[48:49] offset:256
	v_add_u32_e32 v234, 0xa0000, v228
	global_load_dwordx4 v[176:179], v234, s[48:49] offset:0
	global_load_dwordx4 v[180:183], v234, s[48:49] offset:256
	v_add_u32_e32 v234, 0xb0000, v228
	global_load_dwordx4 v[186:189], v234, s[48:49] offset:0
	global_load_dwordx4 v[190:193], v234, s[48:49] offset:256
	s_waitcnt vmcnt(0)
	v_lshlrev_b32_e32 v254, 16, v128
	v_and_b32_e32 v255, 0xffff0000, v128
	v_add_f32_e32 v0, v0, v254
	v_add_f32_e32 v1, v1, v255
	v_mul_f32_e32 v238, v0, v0
	v_fmac_f32_e32 v238, v1, v1
	v_lshlrev_b32_e32 v254, 16, v129
	v_and_b32_e32 v255, 0xffff0000, v129
	v_add_f32_e32 v2, v2, v254
	v_add_f32_e32 v3, v3, v255
	v_fmac_f32_e32 v238, v2, v2
	v_fmac_f32_e32 v238, v3, v3
	v_lshlrev_b32_e32 v254, 16, v130
	v_and_b32_e32 v255, 0xffff0000, v130
	v_add_f32_e32 v4, v4, v254
	v_add_f32_e32 v5, v5, v255
	v_fmac_f32_e32 v238, v4, v4
	v_fmac_f32_e32 v238, v5, v5
	v_lshlrev_b32_e32 v254, 16, v131
	v_and_b32_e32 v255, 0xffff0000, v131
	v_add_f32_e32 v6, v6, v254
	v_add_f32_e32 v7, v7, v255
	v_fmac_f32_e32 v238, v6, v6
	v_fmac_f32_e32 v238, v7, v7
	v_lshlrev_b32_e32 v254, 16, v132
	v_and_b32_e32 v255, 0xffff0000, v132
	v_add_f32_e32 v32, v32, v254
	v_add_f32_e32 v33, v33, v255
	v_fmac_f32_e32 v238, v32, v32
	v_fmac_f32_e32 v238, v33, v33
	v_lshlrev_b32_e32 v254, 16, v133
	v_and_b32_e32 v255, 0xffff0000, v133
	v_add_f32_e32 v34, v34, v254
	v_add_f32_e32 v35, v35, v255
	v_fmac_f32_e32 v238, v34, v34
	v_fmac_f32_e32 v238, v35, v35
	v_lshlrev_b32_e32 v254, 16, v134
	v_and_b32_e32 v255, 0xffff0000, v134
	v_add_f32_e32 v36, v36, v254
	v_add_f32_e32 v37, v37, v255
	v_fmac_f32_e32 v238, v36, v36
	v_fmac_f32_e32 v238, v37, v37
	v_lshlrev_b32_e32 v254, 16, v135
	v_and_b32_e32 v255, 0xffff0000, v135
	v_add_f32_e32 v38, v38, v254
	v_add_f32_e32 v39, v39, v255
	v_fmac_f32_e32 v238, v38, v38
	v_fmac_f32_e32 v238, v39, v39
	v_lshlrev_b32_e32 v254, 16, v136
	v_and_b32_e32 v255, 0xffff0000, v136
	v_add_f32_e32 v8, v8, v254
	v_add_f32_e32 v9, v9, v255
	v_mul_f32_e32 v239, v8, v8
	v_fmac_f32_e32 v239, v9, v9
	v_lshlrev_b32_e32 v254, 16, v137
	v_and_b32_e32 v255, 0xffff0000, v137
	v_add_f32_e32 v10, v10, v254
	v_add_f32_e32 v11, v11, v255
	v_fmac_f32_e32 v239, v10, v10
	v_fmac_f32_e32 v239, v11, v11
	v_lshlrev_b32_e32 v254, 16, v138
	v_and_b32_e32 v255, 0xffff0000, v138
	v_add_f32_e32 v12, v12, v254
	v_add_f32_e32 v13, v13, v255
	v_fmac_f32_e32 v239, v12, v12
	v_fmac_f32_e32 v239, v13, v13
	v_lshlrev_b32_e32 v254, 16, v139
	v_and_b32_e32 v255, 0xffff0000, v139
	v_add_f32_e32 v14, v14, v254
	v_add_f32_e32 v15, v15, v255
	v_fmac_f32_e32 v239, v14, v14
	v_fmac_f32_e32 v239, v15, v15
	v_lshlrev_b32_e32 v254, 16, v140
	v_and_b32_e32 v255, 0xffff0000, v140
	v_add_f32_e32 v40, v40, v254
	v_add_f32_e32 v41, v41, v255
	v_fmac_f32_e32 v239, v40, v40
	v_fmac_f32_e32 v239, v41, v41
	v_lshlrev_b32_e32 v254, 16, v141
	v_and_b32_e32 v255, 0xffff0000, v141
	v_add_f32_e32 v42, v42, v254
	v_add_f32_e32 v43, v43, v255
	v_fmac_f32_e32 v239, v42, v42
	v_fmac_f32_e32 v239, v43, v43
	v_lshlrev_b32_e32 v254, 16, v142
	v_and_b32_e32 v255, 0xffff0000, v142
	v_add_f32_e32 v44, v44, v254
	v_add_f32_e32 v45, v45, v255
	v_fmac_f32_e32 v239, v44, v44
	v_fmac_f32_e32 v239, v45, v45
	v_lshlrev_b32_e32 v254, 16, v143
	v_and_b32_e32 v255, 0xffff0000, v143
	v_add_f32_e32 v46, v46, v254
	v_add_f32_e32 v47, v47, v255
	v_fmac_f32_e32 v239, v46, v46
	v_fmac_f32_e32 v239, v47, v47
	v_lshlrev_b32_e32 v254, 16, v144
	v_and_b32_e32 v255, 0xffff0000, v144
	v_add_f32_e32 v16, v16, v254
	v_add_f32_e32 v17, v17, v255
	v_mul_f32_e32 v240, v16, v16
;     __device__ __forceinline__ void tail(const f32x4& b0, const f32x4& b1, const f32x4& a0, const f32x4& a1, bf16_t* dst, float& s) const {
;         const f32x4 o0 = b0 + a0, o1 = b1 + a1;
;         s += ((o0[0] * o0[0] + o0[1] * o0[1]) + (o0[2] * o0[2] + o0[3] * o0[3])) + ((o1[0] * o1[0] + o1[1] * o1[1]) + (o1[2] * o1[2] + o1[3] * o1[3]));
;     __device__ __forceinline__ void operator()(const f32x4 (&acc)[2][2][4][2], const Unit& u, int wr, int wc, int fr, int fq) const {
;     ...
;                     for (int bj = 0; bj < 2; ++bj) { const u32x4 r = raw[ai][m][bj];
;                         const f32x4 b0 = {__uint_as_float(r.x << 16), __uint_as_float(r.x & 0xffff0000u), __uint_as_float(r.y << 16), __uint_as_float(r.y & 0xffff0000u)};
;                         const f32x4 b1 = {__uint_as_float(r.z << 16), __uint_as_float(r.z & 0xffff0000u), __uint_as_float(r.w << 16), __uint_as_float(r.w & 0xffff0000u)};
;                         tail(b0, b1, acc[ai][bj][m][0], acc[ai][bj][m][1], out + off + bj * HALF, s); }
	v_fmac_f32_e32 v240, v17, v17
	v_lshlrev_b32_e32 v254, 16, v145
	v_and_b32_e32 v255, 0xffff0000, v145
	v_add_f32_e32 v18, v18, v254
	v_add_f32_e32 v19, v19, v255
	v_fmac_f32_e32 v240, v18, v18
	v_fmac_f32_e32 v240, v19, v19
	v_lshlrev_b32_e32 v254, 16, v146
	v_and_b32_e32 v255, 0xffff0000, v146
	v_add_f32_e32 v20, v20, v254
	v_add_f32_e32 v21, v21, v255
	v_fmac_f32_e32 v240, v20, v20
	v_fmac_f32_e32 v240, v21, v21
	v_lshlrev_b32_e32 v254, 16, v147
	v_and_b32_e32 v255, 0xffff0000, v147
	v_add_f32_e32 v22, v22, v254
	v_add_f32_e32 v23, v23, v255
	v_fmac_f32_e32 v240, v22, v22
	v_fmac_f32_e32 v240, v23, v23
	v_lshlrev_b32_e32 v254, 16, v148
	v_and_b32_e32 v255, 0xffff0000, v148
	v_add_f32_e32 v48, v48, v254
	v_add_f32_e32 v49, v49, v255
	v_fmac_f32_e32 v240, v48, v48
	v_fmac_f32_e32 v240, v49, v49
	v_lshlrev_b32_e32 v254, 16, v149
	v_and_b32_e32 v255, 0xffff0000, v149
	v_add_f32_e32 v50, v50, v254
	v_add_f32_e32 v51, v51, v255
	v_fmac_f32_e32 v240, v50, v50
	v_fmac_f32_e32 v240, v51, v51
	v_lshlrev_b32_e32 v254, 16, v150
	v_and_b32_e32 v255, 0xffff0000, v150
	v_add_f32_e32 v52, v52, v254
	v_add_f32_e32 v53, v53, v255
	v_fmac_f32_e32 v240, v52, v52
	v_fmac_f32_e32 v240, v53, v53
	v_lshlrev_b32_e32 v254, 16, v151
	v_and_b32_e32 v255, 0xffff0000, v151
	v_add_f32_e32 v54, v54, v254
	v_add_f32_e32 v55, v55, v255
	v_fmac_f32_e32 v240, v54, v54
	v_fmac_f32_e32 v240, v55, v55
	v_lshlrev_b32_e32 v254, 16, v152
	v_and_b32_e32 v255, 0xffff0000, v152
	v_add_f32_e32 v24, v24, v254
	v_add_f32_e32 v25, v25, v255
	v_mul_f32_e32 v241, v24, v24
	v_fmac_f32_e32 v241, v25, v25
	v_lshlrev_b32_e32 v254, 16, v153
	v_and_b32_e32 v255, 0xffff0000, v153
	v_add_f32_e32 v26, v26, v254
	v_add_f32_e32 v27, v27, v255
	v_fmac_f32_e32 v241, v26, v26
	v_fmac_f32_e32 v241, v27, v27
	v_lshlrev_b32_e32 v254, 16, v154
	v_and_b32_e32 v255, 0xffff0000, v154
	v_add_f32_e32 v28, v28, v254
	v_add_f32_e32 v29, v29, v255
	v_fmac_f32_e32 v241, v28, v28
	v_fmac_f32_e32 v241, v29, v29
	v_lshlrev_b32_e32 v254, 16, v155
	v_and_b32_e32 v255, 0xffff0000, v155
	v_add_f32_e32 v30, v30, v254
	v_add_f32_e32 v31, v31, v255
	v_fmac_f32_e32 v241, v30, v30
	v_fmac_f32_e32 v241, v31, v31
	v_lshlrev_b32_e32 v254, 16, v156
	v_and_b32_e32 v255, 0xffff0000, v156
	v_add_f32_e32 v56, v56, v254
	v_add_f32_e32 v57, v57, v255
	v_fmac_f32_e32 v241, v56, v56
	v_fmac_f32_e32 v241, v57, v57
	v_lshlrev_b32_e32 v254, 16, v157
	v_and_b32_e32 v255, 0xffff0000, v157
	v_add_f32_e32 v58, v58, v254
	v_add_f32_e32 v59, v59, v255
	v_fmac_f32_e32 v241, v58, v58
	v_fmac_f32_e32 v241, v59, v59
	v_lshlrev_b32_e32 v254, 16, v158
	v_and_b32_e32 v255, 0xffff0000, v158
	v_add_f32_e32 v60, v60, v254
	v_add_f32_e32 v61, v61, v255
	v_fmac_f32_e32 v241, v60, v60
	v_fmac_f32_e32 v241, v61, v61
	v_lshlrev_b32_e32 v254, 16, v159
	v_and_b32_e32 v255, 0xffff0000, v159
	v_add_f32_e32 v62, v62, v254
	v_add_f32_e32 v63, v63, v255
	v_fmac_f32_e32 v241, v62, v62
	v_fmac_f32_e32 v241, v63, v63
	v_lshlrev_b32_e32 v254, 16, v160
	v_and_b32_e32 v255, 0xffff0000, v160
	v_add_f32_e32 v64, v64, v254
	v_add_f32_e32 v65, v65, v255
	v_mul_f32_e32 v242, v64, v64
	v_fmac_f32_e32 v242, v65, v65
	v_lshlrev_b32_e32 v254, 16, v161
	v_and_b32_e32 v255, 0xffff0000, v161
	v_add_f32_e32 v66, v66, v254
	v_add_f32_e32 v67, v67, v255
	v_fmac_f32_e32 v242, v66, v66
	v_fmac_f32_e32 v242, v67, v67
	v_lshlrev_b32_e32 v254, 16, v162
	v_and_b32_e32 v255, 0xffff0000, v162
	v_add_f32_e32 v68, v68, v254
	v_add_f32_e32 v69, v69, v255
	v_fmac_f32_e32 v242, v68, v68
	v_fmac_f32_e32 v242, v69, v69
	v_lshlrev_b32_e32 v254, 16, v163
	v_and_b32_e32 v255, 0xffff0000, v163
	v_add_f32_e32 v70, v70, v254
	v_add_f32_e32 v71, v71, v255
	v_fmac_f32_e32 v242, v70, v70
	v_fmac_f32_e32 v242, v71, v71
	v_lshlrev_b32_e32 v254, 16, v164
	v_and_b32_e32 v255, 0xffff0000, v164
	v_add_f32_e32 v96, v96, v254
	v_add_f32_e32 v97, v97, v255
	v_fmac_f32_e32 v242, v96, v96
	v_fmac_f32_e32 v242, v97, v97
	v_lshlrev_b32_e32 v254, 16, v165
	v_and_b32_e32 v255, 0xffff0000, v165
	v_add_f32_e32 v98, v98, v254
	v_add_f32_e32 v99, v99, v255
	v_fmac_f32_e32 v242, v98, v98
	v_fmac_f32_e32 v242, v99, v99
	v_lshlrev_b32_e32 v254, 16, v166
	v_and_b32_e32 v255, 0xffff0000, v166
	v_add_f32_e32 v100, v100, v254
	v_add_f32_e32 v101, v101, v255
	v_fmac_f32_e32 v242, v100, v100
	v_fmac_f32_e32 v242, v101, v101
	v_lshlrev_b32_e32 v254, 16, v167
	v_and_b32_e32 v255, 0xffff0000, v167
	v_add_f32_e32 v102, v102, v254
	v_add_f32_e32 v103, v103, v255
	v_fmac_f32_e32 v242, v102, v102
	v_fmac_f32_e32 v242, v103, v103
	v_lshlrev_b32_e32 v254, 16, v168
	v_and_b32_e32 v255, 0xffff0000, v168
	v_add_f32_e32 v72, v72, v254
	v_add_f32_e32 v73, v73, v255
	v_mul_f32_e32 v243, v72, v72
	v_fmac_f32_e32 v243, v73, v73
	v_lshlrev_b32_e32 v254, 16, v169
	v_and_b32_e32 v255, 0xffff0000, v169
	v_add_f32_e32 v74, v74, v254
	v_add_f32_e32 v75, v75, v255
	v_fmac_f32_e32 v243, v74, v74
	v_fmac_f32_e32 v243, v75, v75
	v_lshlrev_b32_e32 v254, 16, v170
	v_and_b32_e32 v255, 0xffff0000, v170
	v_add_f32_e32 v76, v76, v254
	v_add_f32_e32 v77, v77, v255
	v_fmac_f32_e32 v243, v76, v76
	v_fmac_f32_e32 v243, v77, v77
	v_lshlrev_b32_e32 v254, 16, v171
	v_and_b32_e32 v255, 0xffff0000, v171
	v_add_f32_e32 v78, v78, v254
	v_add_f32_e32 v79, v79, v255
	v_fmac_f32_e32 v243, v78, v78
	v_fmac_f32_e32 v243, v79, v79
	v_lshlrev_b32_e32 v254, 16, v172
	v_and_b32_e32 v255, 0xffff0000, v172
	v_add_f32_e32 v104, v104, v254
	v_add_f32_e32 v105, v105, v255
	v_fmac_f32_e32 v243, v104, v104
	v_fmac_f32_e32 v243, v105, v105
	v_lshlrev_b32_e32 v254, 16, v173
	v_and_b32_e32 v255, 0xffff0000, v173
	v_add_f32_e32 v106, v106, v254
	v_add_f32_e32 v107, v107, v255
	v_fmac_f32_e32 v243, v106, v106
;     __device__ __forceinline__ void operator()(const f32x4 (&acc)[2][2][4][2], const Unit& u, int wr, int wc, int fr, int fq) const {
;     ...
;                     s += __shfl_xor(s, 16); s += __shfl_xor(s, 32);
;                     if (fq == 0) atomicAdd(ss + row, s); }
; __global__ void __launch_bounds__(NWAVES * 64, 2) hybrid_fwd(Args args) {
;     ...
;         f32x4 wfin[8];
; #pragma unroll
;         for (int j = 0; j < 8; ++j) wfin[j] = ((const f32x4*)norm_final_w + lane)[64 * j];
	v_fmac_f32_e32 v243, v107, v107
	v_lshlrev_b32_e32 v254, 16, v174
	v_and_b32_e32 v255, 0xffff0000, v174
	v_add_f32_e32 v108, v108, v254
	v_add_f32_e32 v109, v109, v255
	v_fmac_f32_e32 v243, v108, v108
	v_fmac_f32_e32 v243, v109, v109
	v_lshlrev_b32_e32 v254, 16, v175
	v_and_b32_e32 v255, 0xffff0000, v175
	v_add_f32_e32 v110, v110, v254
	v_add_f32_e32 v111, v111, v255
	v_fmac_f32_e32 v243, v110, v110
	v_fmac_f32_e32 v243, v111, v111
	v_lshlrev_b32_e32 v254, 16, v176
	v_and_b32_e32 v255, 0xffff0000, v176
	v_add_f32_e32 v80, v80, v254
	v_add_f32_e32 v81, v81, v255
	v_mul_f32_e32 v226, v80, v80
	v_fmac_f32_e32 v226, v81, v81
	v_lshlrev_b32_e32 v254, 16, v177
	v_and_b32_e32 v255, 0xffff0000, v177
	v_add_f32_e32 v82, v82, v254
	v_add_f32_e32 v83, v83, v255
	v_fmac_f32_e32 v226, v82, v82
	v_fmac_f32_e32 v226, v83, v83
	v_lshlrev_b32_e32 v254, 16, v178
	v_and_b32_e32 v255, 0xffff0000, v178
	v_add_f32_e32 v84, v84, v254
	v_add_f32_e32 v85, v85, v255
	v_fmac_f32_e32 v226, v84, v84
	v_fmac_f32_e32 v226, v85, v85
	v_lshlrev_b32_e32 v254, 16, v179
	v_and_b32_e32 v255, 0xffff0000, v179
	v_add_f32_e32 v86, v86, v254
	v_add_f32_e32 v87, v87, v255
	v_fmac_f32_e32 v226, v86, v86
	v_fmac_f32_e32 v226, v87, v87
	v_lshlrev_b32_e32 v254, 16, v180
	v_and_b32_e32 v255, 0xffff0000, v180
	v_add_f32_e32 v112, v112, v254
	v_add_f32_e32 v113, v113, v255
	v_fmac_f32_e32 v226, v112, v112
	v_fmac_f32_e32 v226, v113, v113
	v_lshlrev_b32_e32 v254, 16, v181
	v_and_b32_e32 v255, 0xffff0000, v181
	v_add_f32_e32 v114, v114, v254
	v_add_f32_e32 v115, v115, v255
	v_fmac_f32_e32 v226, v114, v114
	v_fmac_f32_e32 v226, v115, v115
	v_lshlrev_b32_e32 v254, 16, v182
	v_and_b32_e32 v255, 0xffff0000, v182
	v_add_f32_e32 v116, v116, v254
	v_add_f32_e32 v117, v117, v255
	v_fmac_f32_e32 v226, v116, v116
	v_fmac_f32_e32 v226, v117, v117
	v_lshlrev_b32_e32 v254, 16, v183
	v_and_b32_e32 v255, 0xffff0000, v183
	v_add_f32_e32 v118, v118, v254
	v_add_f32_e32 v119, v119, v255
	v_fmac_f32_e32 v226, v118, v118
	v_fmac_f32_e32 v226, v119, v119
	v_lshlrev_b32_e32 v254, 16, v186
	v_and_b32_e32 v255, 0xffff0000, v186
	v_add_f32_e32 v88, v88, v254
	v_add_f32_e32 v89, v89, v255
	v_mul_f32_e32 v227, v88, v88
	v_fmac_f32_e32 v227, v89, v89
	v_lshlrev_b32_e32 v254, 16, v187
	v_and_b32_e32 v255, 0xffff0000, v187
	v_add_f32_e32 v90, v90, v254
	v_add_f32_e32 v91, v91, v255
	v_fmac_f32_e32 v227, v90, v90
	v_fmac_f32_e32 v227, v91, v91
	v_lshlrev_b32_e32 v254, 16, v188
	v_and_b32_e32 v255, 0xffff0000, v188
	v_add_f32_e32 v92, v92, v254
	v_add_f32_e32 v93, v93, v255
	v_fmac_f32_e32 v227, v92, v92
	v_fmac_f32_e32 v227, v93, v93
	v_lshlrev_b32_e32 v254, 16, v189
	v_and_b32_e32 v255, 0xffff0000, v189
	v_add_f32_e32 v94, v94, v254
	v_add_f32_e32 v95, v95, v255
	v_fmac_f32_e32 v227, v94, v94
	v_fmac_f32_e32 v227, v95, v95
	v_lshlrev_b32_e32 v254, 16, v190
	v_and_b32_e32 v255, 0xffff0000, v190
	v_add_f32_e32 v120, v120, v254
	v_add_f32_e32 v121, v121, v255
	v_fmac_f32_e32 v227, v120, v120
	v_fmac_f32_e32 v227, v121, v121
	v_lshlrev_b32_e32 v254, 16, v191
	v_and_b32_e32 v255, 0xffff0000, v191
	v_add_f32_e32 v122, v122, v254
	v_add_f32_e32 v123, v123, v255
	v_fmac_f32_e32 v227, v122, v122
	v_fmac_f32_e32 v227, v123, v123
	v_lshlrev_b32_e32 v254, 16, v192
	v_and_b32_e32 v255, 0xffff0000, v192
	v_add_f32_e32 v124, v124, v254
	v_add_f32_e32 v125, v125, v255
	v_fmac_f32_e32 v227, v124, v124
	v_fmac_f32_e32 v227, v125, v125
	v_lshlrev_b32_e32 v254, 16, v193
	v_and_b32_e32 v255, 0xffff0000, v193
	v_add_f32_e32 v126, v126, v254
	v_add_f32_e32 v127, v127, v255
	v_fmac_f32_e32 v227, v126, v126
	v_fmac_f32_e32 v227, v127, v127
	v_readlane_b32 s44, v244, 0
	v_readlane_b32 s45, v244, 1
	v_and_b32_e32 v254, 63, v185
	v_lshrrev_b32_e32 v254, 4, v254
	v_lshlrev_b32_e32 v254, 5, v254
	s_lshl_b32 s40, s38, 7
	s_lshl_b32 s41, s18, 10
	s_add_u32 s40, s40, s41
	v_add_u32_e32 v254, s40, v254
	global_load_dwordx4 v[160:163], v254, s[44:45] offset:0
	global_load_dwordx4 v[164:167], v254, s[44:45] offset:16
	global_load_dwordx4 v[168:171], v254, s[44:45] offset:512
	global_load_dwordx4 v[172:175], v254, s[44:45] offset:528
	ds_bpermute_b32 v128, v232, v238
	ds_bpermute_b32 v132, v232, v239
	ds_bpermute_b32 v136, v232, v240
	ds_bpermute_b32 v140, v232, v241
	ds_bpermute_b32 v144, v232, v242
	ds_bpermute_b32 v148, v232, v243
	ds_bpermute_b32 v152, v232, v226
	ds_bpermute_b32 v156, v232, v227
	s_waitcnt lgkmcnt(0)
	v_add_f32_e32 v238, v238, v128
	v_add_f32_e32 v239, v239, v132
	v_add_f32_e32 v240, v240, v136
	v_add_f32_e32 v241, v241, v140
	v_add_f32_e32 v242, v242, v144
	v_add_f32_e32 v243, v243, v148
	v_add_f32_e32 v226, v226, v152
	v_add_f32_e32 v227, v227, v156
	ds_bpermute_b32 v128, v233, v238
	ds_bpermute_b32 v132, v233, v239
	ds_bpermute_b32 v136, v233, v240
	ds_bpermute_b32 v140, v233, v241
	ds_bpermute_b32 v144, v233, v242
	ds_bpermute_b32 v148, v233, v243
	ds_bpermute_b32 v152, v233, v226
	ds_bpermute_b32 v156, v233, v227
	s_waitcnt lgkmcnt(0)
	v_add_f32_e32 v238, v238, v128
	v_add_f32_e32 v239, v239, v132
	v_add_f32_e32 v240, v240, v136
	v_add_f32_e32 v241, v241, v140
	v_add_f32_e32 v242, v242, v144
	v_add_f32_e32 v243, v243, v148
	v_add_f32_e32 v226, v226, v152
	v_add_f32_e32 v227, v227, v156
	s_mov_b64 exec, 0xffff
	global_atomic_add_f32 v230, v238, s[50:51] offset:0
	global_atomic_add_f32 v230, v239, s[50:51] offset:64
	global_atomic_add_f32 v230, v240, s[50:51] offset:128
	global_atomic_add_f32 v230, v241, s[50:51] offset:192
	global_atomic_add_f32 v230, v242, s[50:51] offset:512
	global_atomic_add_f32 v230, v243, s[50:51] offset:576
	global_atomic_add_f32 v230, v226, s[50:51] offset:640
	global_atomic_add_f32 v230, v227, s[50:51] offset:704
	s_mov_b64 exec, -1
	s_waitcnt vmcnt(0)
	s_barrier
	s_cmp_lg_u32 s36, 0
	s_cbranch_scc1 .Lp6_fin_wait
	s_mov_b64 exec, 1
	v_mov_b32_e32 v237, 0
	v_mov_b32_e32 v236, 1
	global_atomic_add v237, v236, s[54:55]
	s_mov_b32 s42, 0

; __global__ void __launch_bounds__(NWAVES * 64, 2) hybrid_fwd(Args args) {
;     ...
;             for (int q = 0; q < 4; ++q) { const v2u* xr = (const v2u*)(MIXED + (size_t)(m0 + q) * DM) + lane; rs[q] = __builtin_amdgcn_rsqf(SS2[m0 + q] * (1.f / DM) + NORM_EPS);
; #pragma unroll
;                 for (int j = 0; j < 8; ++j) r[q][j] = xr[64 * j]; }
; #pragma unroll
;             for (int q = 0; q < 4; ++q) { f32x4* orow = (f32x4*)(out + (size_t)(m0 + q) * DM) + lane;
; #pragma unroll
;                 for (int j = 0; j < 8; ++j) { const f32x4 w = wfin[j]; const float s = rs[q];
;                     orow[64 * j] = (f32x4){__uint_as_float(r[q][j].x << 16) * s * w.x, __uint_as_float(r[q][j].x & 0xffff0000u) * s * w.y, __uint_as_float(r[q][j].y << 16) * s * w.z, __uint_as_float(r[q][j].y & 0xffff0000u) * s * w.w}; } }
.Lp6_fin_wait:
	s_barrier
	global_load_dword v238, v230, s[50:51] offset:0 sc0 sc1
	global_load_dword v239, v230, s[50:51] offset:64 sc0 sc1
	global_load_dword v240, v230, s[50:51] offset:128 sc0 sc1
	global_load_dword v241, v230, s[50:51] offset:192 sc0 sc1
	global_load_dword v242, v230, s[50:51] offset:512 sc0 sc1
	global_load_dword v243, v230, s[50:51] offset:576 sc0 sc1
	global_load_dword v226, v230, s[50:51] offset:640 sc0 sc1
	global_load_dword v227, v230, s[50:51] offset:704 sc0 sc1
	s_waitcnt vmcnt(0)
	v_fmamk_f32 v235, v238, 0x3a000000, v231
	v_add_u32_e32 v234, 0x0, v229
	v_rsq_f32_e32 v235, v235
	s_nop 0
	v_mul_f32_e32 v0, v0, v235
	v_mul_f32_e32 v1, v1, v235
	v_mul_f32_e32 v2, v2, v235
	v_mul_f32_e32 v3, v3, v235
	v_mul_f32_e32 v4, v4, v235
	v_mul_f32_e32 v5, v5, v235
	v_mul_f32_e32 v6, v6, v235
	v_mul_f32_e32 v7, v7, v235
	v_mul_f32_e32 v32, v32, v235
	v_mul_f32_e32 v33, v33, v235
	v_mul_f32_e32 v34, v34, v235
	v_mul_f32_e32 v35, v35, v235
	v_mul_f32_e32 v36, v36, v235
	v_mul_f32_e32 v37, v37, v235
	v_mul_f32_e32 v38, v38, v235
	v_mul_f32_e32 v39, v39, v235
	v_mul_f32_e32 v0, v0, v160
	v_mul_f32_e32 v1, v1, v161
	v_mul_f32_e32 v2, v2, v162
	v_mul_f32_e32 v3, v3, v163
	v_mul_f32_e32 v4, v4, v164
	v_mul_f32_e32 v5, v5, v165
	v_mul_f32_e32 v6, v6, v166
	v_mul_f32_e32 v7, v7, v167
	v_mul_f32_e32 v32, v32, v168
	v_mul_f32_e32 v33, v33, v169
	v_mul_f32_e32 v34, v34, v170
	v_mul_f32_e32 v35, v35, v171
	v_mul_f32_e32 v36, v36, v172
	v_mul_f32_e32 v37, v37, v173
	v_mul_f32_e32 v38, v38, v174
	v_mul_f32_e32 v39, v39, v175
	global_store_dwordx4 v234, v[0:3], s[52:53] offset:0
	global_store_dwordx4 v234, v[4:7], s[52:53] offset:16
	global_store_dwordx4 v234, v[32:35], s[52:53] offset:512
	global_store_dwordx4 v234, v[36:39], s[52:53] offset:528
	s_nop 1
	v_fmamk_f32 v235, v239, 0x3a000000, v231
	v_add_u32_e32 v234, 0x20000, v229
	v_rsq_f32_e32 v235, v235
	s_nop 0
	v_mul_f32_e32 v8, v8, v235
	v_mul_f32_e32 v9, v9, v235
	v_mul_f32_e32 v10, v10, v235
	v_mul_f32_e32 v11, v11, v235
	v_mul_f32_e32 v12, v12, v235
	v_mul_f32_e32 v13, v13, v235
	v_mul_f32_e32 v14, v14, v235
	v_mul_f32_e32 v15, v15, v235
	v_mul_f32_e32 v40, v40, v235
	v_mul_f32_e32 v41, v41, v235
	v_mul_f32_e32 v42, v42, v235
	v_mul_f32_e32 v43, v43, v235
	v_mul_f32_e32 v44, v44, v235
	v_mul_f32_e32 v45, v45, v235
	v_mul_f32_e32 v46, v46, v235
	v_mul_f32_e32 v47, v47, v235
	v_mul_f32_e32 v8, v8, v160
	v_mul_f32_e32 v9, v9, v161
	v_mul_f32_e32 v10, v10, v162
	v_mul_f32_e32 v11, v11, v163
	v_mul_f32_e32 v12, v12, v164
	v_mul_f32_e32 v13, v13, v165
	v_mul_f32_e32 v14, v14, v166
	v_mul_f32_e32 v15, v15, v167
	v_mul_f32_e32 v40, v40, v168
	v_mul_f32_e32 v41, v41, v169
	v_mul_f32_e32 v42, v42, v170
	v_mul_f32_e32 v43, v43, v171
	v_mul_f32_e32 v44, v44, v172
	v_mul_f32_e32 v45, v45, v173
	v_mul_f32_e32 v46, v46, v174
	v_mul_f32_e32 v47, v47, v175
	global_store_dwordx4 v234, v[8:11], s[52:53] offset:0
	global_store_dwordx4 v234, v[12:15], s[52:53] offset:16
	global_store_dwordx4 v234, v[40:43], s[52:53] offset:512
	global_store_dwordx4 v234, v[44:47], s[52:53] offset:528
	s_nop 1
	v_fmamk_f32 v235, v240, 0x3a000000, v231
	v_add_u32_e32 v234, 0x40000, v229
	v_rsq_f32_e32 v235, v235
	s_nop 0
	v_mul_f32_e32 v16, v16, v235
	v_mul_f32_e32 v17, v17, v235
	v_mul_f32_e32 v18, v18, v235
	v_mul_f32_e32 v19, v19, v235
	v_mul_f32_e32 v20, v20, v235
	v_mul_f32_e32 v21, v21, v235
	v_mul_f32_e32 v22, v22, v235
	v_mul_f32_e32 v23, v23, v235
	v_mul_f32_e32 v48, v48, v235
	v_mul_f32_e32 v49, v49, v235
	v_mul_f32_e32 v50, v50, v235
	v_mul_f32_e32 v51, v51, v235
	v_mul_f32_e32 v52, v52, v235
	v_mul_f32_e32 v53, v53, v235
	v_mul_f32_e32 v54, v54, v235
	v_mul_f32_e32 v55, v55, v235
	v_mul_f32_e32 v16, v16, v160
	v_mul_f32_e32 v17, v17, v161
	v_mul_f32_e32 v18, v18, v162
	v_mul_f32_e32 v19, v19, v163
	v_mul_f32_e32 v20, v20, v164
	v_mul_f32_e32 v21, v21, v165
	v_mul_f32_e32 v22, v22, v166
	v_mul_f32_e32 v23, v23, v167
	v_mul_f32_e32 v48, v48, v168
	v_mul_f32_e32 v49, v49, v169
	v_mul_f32_e32 v50, v50, v170
	v_mul_f32_e32 v51, v51, v171
	v_mul_f32_e32 v52, v52, v172
	v_mul_f32_e32 v53, v53, v173
	v_mul_f32_e32 v54, v54, v174
	v_mul_f32_e32 v55, v55, v175
	global_store_dwordx4 v234, v[16:19], s[52:53] offset:0
	global_store_dwordx4 v234, v[20:23], s[52:53] offset:16
	global_store_dwordx4 v234, v[48:51], s[52:53] offset:512
	global_store_dwordx4 v234, v[52:55], s[52:53] offset:528
	s_nop 1
	v_fmamk_f32 v235, v241, 0x3a000000, v231
	v_add_u32_e32 v234, 0x60000, v229
	v_rsq_f32_e32 v235, v235
	s_nop 0
	v_mul_f32_e32 v24, v24, v235
	v_mul_f32_e32 v25, v25, v235
	v_mul_f32_e32 v26, v26, v235
	v_mul_f32_e32 v27, v27, v235
	v_mul_f32_e32 v28, v28, v235
	v_mul_f32_e32 v29, v29, v235
	v_mul_f32_e32 v30, v30, v235
	v_mul_f32_e32 v31, v31, v235
	v_mul_f32_e32 v56, v56, v235
	v_mul_f32_e32 v57, v57, v235
	v_mul_f32_e32 v58, v58, v235
	v_mul_f32_e32 v59, v59, v235
	v_mul_f32_e32 v60, v60, v235
	v_mul_f32_e32 v61, v61, v235
	v_mul_f32_e32 v62, v62, v235
	v_mul_f32_e32 v63, v63, v235
	v_mul_f32_e32 v24, v24, v160
	v_mul_f32_e32 v25, v25, v161
	v_mul_f32_e32 v26, v26, v162
	v_mul_f32_e32 v27, v27, v163
	v_mul_f32_e32 v28, v28, v164
	v_mul_f32_e32 v29, v29, v165
	v_mul_f32_e32 v30, v30, v166
	v_mul_f32_e32 v31, v31, v167
	v_mul_f32_e32 v56, v56, v168
	v_mul_f32_e32 v57, v57, v169
	v_mul_f32_e32 v58, v58, v170
	v_mul_f32_e32 v59, v59, v171
	v_mul_f32_e32 v60, v60, v172
	v_mul_f32_e32 v61, v61, v173
	v_mul_f32_e32 v62, v62, v174
	v_mul_f32_e32 v63, v63, v175
	global_store_dwordx4 v234, v[24:27], s[52:53] offset:0
	global_store_dwordx4 v234, v[28:31], s[52:53] offset:16
	global_store_dwordx4 v234, v[56:59], s[52:53] offset:512
; template <class Epi, class Sched, bool ALIGN_EPI = false, bool SP2 = false>
; __device__ __forceinline__ void gemm_phase(PG8_LAS unsigned char* lds, const Gemm g, const Sched& S, const Epi& E) {
;     ...
;         if (!has_next) break;
; #pragma unroll
;         for (int a = 0; a < 2; ++a)
; #pragma unroll
;             for (int b = 0; b < 2; ++b)
; #pragma unroll
;                 for (int m = 0; m < 4; ++m)
; #pragma unroll
;                     for (int n = 0; n < 2; ++n) acc[a][b][m][n] = (f32x4){0.f, 0.f, 0.f, 0.f};
;         cur = nxt; cA = nA; cB = nB; ++ui;
; __global__ void __launch_bounds__(NWAVES * 64, 2) hybrid_fwd(Args args) {
;     ...
;             for (int q = 0; q < 4; ++q) { const v2u* xr = (const v2u*)(MIXED + (size_t)(m0 + q) * DM) + lane; rs[q] = __builtin_amdgcn_rsqf(SS2[m0 + q] * (1.f / DM) + NORM_EPS);
; #pragma unroll
;                 for (int j = 0; j < 8; ++j) r[q][j] = xr[64 * j]; }
; #pragma unroll
;             for (int q = 0; q < 4; ++q) { f32x4* orow = (f32x4*)(out + (size_t)(m0 + q) * DM) + lane;
; #pragma unroll
;                 for (int j = 0; j < 8; ++j) { const f32x4 w = wfin[j]; const float s = rs[q];
;                     orow[64 * j] = (f32x4){__uint_as_float(r[q][j].x << 16) * s * w.x, __uint_as_float(r[q][j].x & 0xffff0000u) * s * w.y, __uint_as_float(r[q][j].y << 16) * s * w.z, __uint_as_float(r[q][j].y & 0xffff0000u) * s * w.w}; } }
	global_store_dwordx4 v234, v[60:63], s[52:53] offset:528
	s_nop 1
	v_fmamk_f32 v235, v242, 0x3a000000, v231
	v_add_u32_e32 v234, 0x100000, v229
	v_rsq_f32_e32 v235, v235
	s_nop 0
	v_mul_f32_e32 v64, v64, v235
	v_mul_f32_e32 v65, v65, v235
	v_mul_f32_e32 v66, v66, v235
	v_mul_f32_e32 v67, v67, v235
	v_mul_f32_e32 v68, v68, v235
	v_mul_f32_e32 v69, v69, v235
	v_mul_f32_e32 v70, v70, v235
	v_mul_f32_e32 v71, v71, v235
	v_mul_f32_e32 v96, v96, v235
	v_mul_f32_e32 v97, v97, v235
	v_mul_f32_e32 v98, v98, v235
	v_mul_f32_e32 v99, v99, v235
	v_mul_f32_e32 v100, v100, v235
	v_mul_f32_e32 v101, v101, v235
	v_mul_f32_e32 v102, v102, v235
	v_mul_f32_e32 v103, v103, v235
	v_mul_f32_e32 v64, v64, v160
	v_mul_f32_e32 v65, v65, v161
	v_mul_f32_e32 v66, v66, v162
	v_mul_f32_e32 v67, v67, v163
	v_mul_f32_e32 v68, v68, v164
	v_mul_f32_e32 v69, v69, v165
	v_mul_f32_e32 v70, v70, v166
	v_mul_f32_e32 v71, v71, v167
	v_mul_f32_e32 v96, v96, v168
	v_mul_f32_e32 v97, v97, v169
	v_mul_f32_e32 v98, v98, v170
	v_mul_f32_e32 v99, v99, v171
	v_mul_f32_e32 v100, v100, v172
	v_mul_f32_e32 v101, v101, v173
	v_mul_f32_e32 v102, v102, v174
	v_mul_f32_e32 v103, v103, v175
	global_store_dwordx4 v234, v[64:67], s[52:53] offset:0
	global_store_dwordx4 v234, v[68:71], s[52:53] offset:16
	global_store_dwordx4 v234, v[96:99], s[52:53] offset:512
	global_store_dwordx4 v234, v[100:103], s[52:53] offset:528
	s_nop 1
	v_fmamk_f32 v235, v243, 0x3a000000, v231
	v_add_u32_e32 v234, 0x120000, v229
	v_rsq_f32_e32 v235, v235
	s_nop 0
	v_mul_f32_e32 v72, v72, v235
	v_mul_f32_e32 v73, v73, v235
	v_mul_f32_e32 v74, v74, v235
	v_mul_f32_e32 v75, v75, v235
	v_mul_f32_e32 v76, v76, v235
	v_mul_f32_e32 v77, v77, v235
	v_mul_f32_e32 v78, v78, v235
	v_mul_f32_e32 v79, v79, v235
	v_mul_f32_e32 v104, v104, v235
	v_mul_f32_e32 v105, v105, v235
	v_mul_f32_e32 v106, v106, v235
	v_mul_f32_e32 v107, v107, v235
	v_mul_f32_e32 v108, v108, v235
	v_mul_f32_e32 v109, v109, v235
	v_mul_f32_e32 v110, v110, v235
	v_mul_f32_e32 v111, v111, v235
	v_mul_f32_e32 v72, v72, v160
	v_mul_f32_e32 v73, v73, v161
	v_mul_f32_e32 v74, v74, v162
	v_mul_f32_e32 v75, v75, v163
	v_mul_f32_e32 v76, v76, v164
	v_mul_f32_e32 v77, v77, v165
	v_mul_f32_e32 v78, v78, v166
	v_mul_f32_e32 v79, v79, v167
	v_mul_f32_e32 v104, v104, v168
	v_mul_f32_e32 v105, v105, v169
	v_mul_f32_e32 v106, v106, v170
	v_mul_f32_e32 v107, v107, v171
	v_mul_f32_e32 v108, v108, v172
	v_mul_f32_e32 v109, v109, v173
	v_mul_f32_e32 v110, v110, v174
	v_mul_f32_e32 v111, v111, v175
	global_store_dwordx4 v234, v[72:75], s[52:53] offset:0
	global_store_dwordx4 v234, v[76:79], s[52:53] offset:16
	global_store_dwordx4 v234, v[104:107], s[52:53] offset:512
	global_store_dwordx4 v234, v[108:111], s[52:53] offset:528
	s_nop 1
	v_fmamk_f32 v235, v226, 0x3a000000, v231
	v_add_u32_e32 v234, 0x140000, v229
	v_rsq_f32_e32 v235, v235
	s_nop 0
	v_mul_f32_e32 v80, v80, v235
	v_mul_f32_e32 v81, v81, v235
	v_mul_f32_e32 v82, v82, v235
	v_mul_f32_e32 v83, v83, v235
	v_mul_f32_e32 v84, v84, v235
	v_mul_f32_e32 v85, v85, v235
	v_mul_f32_e32 v86, v86, v235
	v_mul_f32_e32 v87, v87, v235
	v_mul_f32_e32 v112, v112, v235
	v_mul_f32_e32 v113, v113, v235
	v_mul_f32_e32 v114, v114, v235
	v_mul_f32_e32 v115, v115, v235
	v_mul_f32_e32 v116, v116, v235
	v_mul_f32_e32 v117, v117, v235
	v_mul_f32_e32 v118, v118, v235
	v_mul_f32_e32 v119, v119, v235
	v_mul_f32_e32 v80, v80, v160
	v_mul_f32_e32 v81, v81, v161
	v_mul_f32_e32 v82, v82, v162
	v_mul_f32_e32 v83, v83, v163
	v_mul_f32_e32 v84, v84, v164
	v_mul_f32_e32 v85, v85, v165
	v_mul_f32_e32 v86, v86, v166
	v_mul_f32_e32 v87, v87, v167
	v_mul_f32_e32 v112, v112, v168
	v_mul_f32_e32 v113, v113, v169
	v_mul_f32_e32 v114, v114, v170
	v_mul_f32_e32 v115, v115, v171
	v_mul_f32_e32 v116, v116, v172
	v_mul_f32_e32 v117, v117, v173
	v_mul_f32_e32 v118, v118, v174
	v_mul_f32_e32 v119, v119, v175
	global_store_dwordx4 v234, v[80:83], s[52:53] offset:0
	global_store_dwordx4 v234, v[84:87], s[52:53] offset:16
	global_store_dwordx4 v234, v[112:115], s[52:53] offset:512
	global_store_dwordx4 v234, v[116:119], s[52:53] offset:528
	s_nop 1
	v_fmamk_f32 v235, v227, 0x3a000000, v231
	v_add_u32_e32 v234, 0x160000, v229
	v_rsq_f32_e32 v235, v235
	s_nop 0
	v_mul_f32_e32 v88, v88, v235
	v_mul_f32_e32 v89, v89, v235
	v_mul_f32_e32 v90, v90, v235
	v_mul_f32_e32 v91, v91, v235
	v_mul_f32_e32 v92, v92, v235
	v_mul_f32_e32 v93, v93, v235
	v_mul_f32_e32 v94, v94, v235
	v_mul_f32_e32 v95, v95, v235
	v_mul_f32_e32 v120, v120, v235
	v_mul_f32_e32 v121, v121, v235
	v_mul_f32_e32 v122, v122, v235
	v_mul_f32_e32 v123, v123, v235
	v_mul_f32_e32 v124, v124, v235
	v_mul_f32_e32 v125, v125, v235
	v_mul_f32_e32 v126, v126, v235
	v_mul_f32_e32 v127, v127, v235
	v_mul_f32_e32 v88, v88, v160
	v_mul_f32_e32 v89, v89, v161
	v_mul_f32_e32 v90, v90, v162
	v_mul_f32_e32 v91, v91, v163
	v_mul_f32_e32 v92, v92, v164
	v_mul_f32_e32 v93, v93, v165
	v_mul_f32_e32 v94, v94, v166
	v_mul_f32_e32 v95, v95, v167
	v_mul_f32_e32 v120, v120, v168
	v_mul_f32_e32 v121, v121, v169
	v_mul_f32_e32 v122, v122, v170
	v_mul_f32_e32 v123, v123, v171
	v_mul_f32_e32 v124, v124, v172
	v_mul_f32_e32 v125, v125, v173
	v_mul_f32_e32 v126, v126, v174
	v_mul_f32_e32 v127, v127, v175
	global_store_dwordx4 v234, v[88:91], s[52:53] offset:0
	global_store_dwordx4 v234, v[92:95], s[52:53] offset:16
	global_store_dwordx4 v234, v[120:123], s[52:53] offset:512
	global_store_dwordx4 v234, v[124:127], s[52:53] offset:528
	s_nop 1
	s_cmp_eq_u32 s19, 0
	s_cbranch_scc1 .Lp6_done
	s_mov_b32 s17, s20
	s_mov_b32 s18, s21
	s_mov_b64 s[22:23], s[26:27]
	s_mov_b64 s[24:25], s[28:29]
	s_add_u32 s16, s16, 1
	s_branch .Lp6_unit
